# on top of v9: SGU head loop no longer waits for the previous head's store acks at the loop top (full wait moved to the preheader)
# baseline (speedup 1.0000x reference)
; #define GAS __attribute__((address_space(1)))
; __device__ __forceinline__ int lane_opaque() { int l; asm volatile("v_mbcnt_lo_u32_b32 %0, -1, 0\n\tv_mbcnt_hi_u32_b32 %0, -1, %0" : "=v"(l)); return l; }
; __device__ __forceinline__ void unpack8(const v4u w, float (&f)[8]) { f[0] = bf_lo(w.x); f[1] = bf_hi(w.x); f[2] = bf_lo(w.y); f[3] = bf_hi(w.y); f[4] = bf_lo(w.z); f[5] = bf_hi(w.z); f[6] = bf_lo(w.w); f[7] = bf_hi(w.w); }
; __device__ __forceinline__ void mixer_shortconv(const Frame& F, const Args& A, int l, int chunk, const bf16* Z, bf16* MIX) {
;     const int lane = lane_opaque();
;     const int c8 = lane * 8, row0 = chunk * 128, pos0 = (chunk & 31) * 128, t0 = F.wave * 16;
;     const float* cw = A.in[8] + (size_t)l * 3 * GW;
;     float w0[8], w1[8], w2[8];
; #pragma unroll
;     for (int j = 0; j < 8; ++j) { w0[j] = cw[c8 + j]; w1[j] = cw[GW + c8 + j]; w2[j] = cw[2 * GW + c8 + j]; }
;     float xm2[8], xm1[8];
; #pragma unroll
;     for (int j = 0; j < 8; ++j) { xm2[j] = 0.f; xm1[j] = 0.f; }
; #pragma unroll
;     for (int dt = -2; dt < 16; ++dt) {
;         const int t = t0 + dt; const bool valid = (pos0 + t) >= 0;
;         const bf16* zr = Z + (size_t)(row0 + (valid ? t : 0)) * ZC;
;         float xv[8], x[8];
;         unpack8(*(const GAS v4u*)(zr + 1024 + c8), xv);
.LBB0_302:
	s_lshl_b32 s4, s26, 5
	s_and_b32 s4, s4, 0xe0
	s_bfe_u32 s5, s26, 0x50003
	s_or_b32 s36, s4, s5
	v_readlane_b32 s4, v253, 24
	s_and_b32 s21, s26, 0xff
	v_readlane_b32 s5, v253, 25
	s_and_b64 s[4:5], s[4:5], exec
	s_cselect_b32 s5, s36, s21
	s_lshl_b32 s21, s5, 7
	s_and_b32 s4, s21, 0xf80
	v_mbcnt_lo_u32_b32 v1, -1, 0
	v_mbcnt_hi_u32_b32 v1, -1, v1
	v_lshlrev_b32_e32 v2, 4, v1
	v_lshlrev_b32_e32 v3, 5, v1
	v_and_b32_e32 v4, 15, v1
	v_lshrrev_b32_e32 v5, 4, v1
	v_readlane_b32 s42, v253, 44
	v_readlane_b32 s43, v253, 45
	v_or_b32_e32 v10, 0, v5
	v_xor_b32_e32 v10, v4, v10
	v_lshlrev_b32_e32 v10, 4, v10
	v_lshl_add_u32 v6, v5, 8, v10
	v_or_b32_e32 v10, 4, v5
	v_xor_b32_e32 v10, v4, v10
	v_lshlrev_b32_e32 v10, 4, v10
	v_lshl_add_u32 v7, v5, 8, v10
	v_or_b32_e32 v10, 8, v5
	v_xor_b32_e32 v10, v4, v10
	v_lshlrev_b32_e32 v10, 4, v10
	v_lshl_add_u32 v8, v5, 8, v10
	v_or_b32_e32 v10, 12, v5
	v_xor_b32_e32 v10, v4, v10
	v_lshlrev_b32_e32 v10, 4, v10
	v_lshl_add_u32 v9, v5, 8, v10
	s_lshl_b32 s36, s56, 10
	s_add_u32 s38, s54, s36
	s_addc_u32 s39, s55, 0
	s_add_i32 m0, s36, 0
	s_nop 0
	global_load_lds_dwordx4 v6, s[38:39]
	s_add_i32 m0, s36, 1024
	s_add_u32 s48, s38, 1024
	s_addc_u32 s49, s39, 0
	global_load_lds_dwordx4 v7, s[48:49]
	s_add_i32 m0, s36, 2048
	s_add_u32 s48, s38, 2048
	s_addc_u32 s49, s39, 0
	global_load_lds_dwordx4 v8, s[48:49]
	s_add_i32 m0, s36, 3072
	s_add_u32 s48, s38, 3072
	s_addc_u32 s49, s39, 0
	global_load_lds_dwordx4 v9, s[48:49]
	s_add_i32 m0, s36, 4096
	s_add_u32 s48, s38, 4096
	s_addc_u32 s49, s39, 0
	global_load_lds_dwordx4 v6, s[48:49]
	s_add_i32 m0, s36, 5120
	s_add_u32 s48, s38, 5120
	s_addc_u32 s49, s39, 0
	global_load_lds_dwordx4 v7, s[48:49]
	s_add_i32 m0, s36, 6144
	s_add_u32 s48, s38, 6144
	s_addc_u32 s49, s39, 0
	global_load_lds_dwordx4 v8, s[48:49]
	s_add_i32 m0, s36, 7168
	s_add_u32 s48, s38, 7168
	s_addc_u32 s49, s39, 0
	global_load_lds_dwordx4 v9, s[48:49]
	s_add_i32 m0, s36, 8192
	s_add_u32 s48, s38, 8192
	s_addc_u32 s49, s39, 0
	global_load_lds_dwordx4 v6, s[48:49]
	s_add_i32 m0, s36, 9216
	s_add_u32 s48, s38, 9216
	s_addc_u32 s49, s39, 0
	global_load_lds_dwordx4 v7, s[48:49]
	s_add_i32 m0, s36, 10240
	s_add_u32 s48, s38, 10240
	s_addc_u32 s49, s39, 0
	global_load_lds_dwordx4 v8, s[48:49]
	s_add_i32 m0, s36, 11264
	s_add_u32 s48, s38, 11264
	s_addc_u32 s49, s39, 0
	global_load_lds_dwordx4 v9, s[48:49]
	s_add_i32 m0, s36, 12288
	s_add_u32 s48, s38, 12288
	s_addc_u32 s49, s39, 0
	global_load_lds_dwordx4 v6, s[48:49]
	s_add_i32 m0, s36, 13312
	s_add_u32 s48, s38, 13312
	s_addc_u32 s49, s39, 0
	global_load_lds_dwordx4 v7, s[48:49]
	s_add_i32 m0, s36, 14336
	s_add_u32 s48, s38, 14336
	s_addc_u32 s49, s39, 0
	global_load_lds_dwordx4 v8, s[48:49]
	s_add_i32 m0, s36, 15360
	s_add_u32 s48, s38, 15360
	s_addc_u32 s49, s39, 0
	global_load_lds_dwordx4 v9, s[48:49]
	s_add_i32 s36, s21, s56
	s_lshl_b32 s84, s36, 12
	s_mov_b32 s85, 0
	s_add_u32 s46, s2, s84
	s_addc_u32 s47, s3, 0
	s_add_i32 s37, s4, s56
	s_cmp_lg_u32 s37, 0
	s_cselect_b64 s[40:41], -1, 0
	s_mul_i32 s37, s36, s33
	s_add_u32 s38, s82, s37
	s_addc_u32 s39, s83, 0
	global_load_dwordx4 v[100:103], v3, s[42:43]
	global_load_dwordx4 v[104:107], v3, s[42:43] offset:16
	global_load_dwordx4 v[108:111], v3, s[42:43] offset:2048
	global_load_dwordx4 v[112:115], v3, s[42:43] offset:2064
	s_add_u32 s48, s42, 0x1000
	s_addc_u32 s49, s43, 0
	global_load_dwordx4 v[116:119], v3, s[48:49]
	global_load_dwordx4 v[120:123], v3, s[48:49] offset:16
	s_sub_u32 s48, s38, 0x3000
	s_subb_u32 s49, s39, 0
	s_and_b64 vcc, s[40:41], exec
	s_cselect_b32 s48, s48, s38
	s_cselect_b32 s49, s49, s39
	global_load_dwordx4 v[12:15], v2, s[48:49] offset:2048
	s_sub_u32 s48, s38, 0x1800
	s_subb_u32 s49, s39, 0
	s_and_b64 vcc, s[40:41], exec
	s_cselect_b32 s48, s48, s38
	s_cselect_b32 s49, s49, s39
	global_load_dwordx4 v[16:19], v2, s[48:49] offset:2048
	s_mov_b64 s[48:49], s[38:39]
	global_load_dwordx4 v[20:23], v2, s[48:49] offset:2048
	global_load_dwordx4 v[52:55], v2, s[48:49] offset:3072
	s_add_u32 s48, s48, 0x1800
	s_addc_u32 s49, s49, 0
	global_load_dwordx4 v[24:27], v2, s[48:49] offset:2048
	global_load_dwordx4 v[56:59], v2, s[48:49] offset:3072
	s_add_u32 s48, s48, 0x1800
	s_addc_u32 s49, s49, 0
	global_load_dwordx4 v[28:31], v2, s[48:49] offset:2048
	global_load_dwordx4 v[60:63], v2, s[48:49] offset:3072
	s_add_u32 s48, s48, 0x1800
	s_addc_u32 s49, s49, 0
	global_load_dwordx4 v[32:35], v2, s[48:49] offset:2048
	global_load_dwordx4 v[64:67], v2, s[48:49] offset:3072
	s_add_u32 s48, s48, 0x1800
	s_addc_u32 s49, s49, 0
	global_load_dwordx4 v[36:39], v2, s[48:49] offset:2048
	global_load_dwordx4 v[68:71], v2, s[48:49] offset:3072
	s_add_u32 s48, s48, 0x1800
	s_addc_u32 s49, s49, 0
	global_load_dwordx4 v[40:43], v2, s[48:49] offset:2048
	global_load_dwordx4 v[72:75], v2, s[48:49] offset:3072
	s_add_u32 s48, s48, 0x1800
	s_addc_u32 s49, s49, 0
	global_load_dwordx4 v[44:47], v2, s[48:49] offset:2048
	global_load_dwordx4 v[76:79], v2, s[48:49] offset:3072
	s_add_u32 s48, s48, 0x1800
	s_addc_u32 s49, s49, 0
	global_load_dwordx4 v[48:51], v2, s[48:49] offset:2048
	global_load_dwordx4 v[80:83], v2, s[48:49] offset:3072
	s_add_u32 s48, s48, 0x1800
	s_addc_u32 s49, s49, 0
	s_waitcnt vmcnt(0)
; #define GAS __attribute__((address_space(1)))
; __device__ __forceinline__ void unpack8(const v4u w, float (&f)[8]) { f[0] = bf_lo(w.x); f[1] = bf_hi(w.x); f[2] = bf_lo(w.y); f[3] = bf_hi(w.y); f[4] = bf_lo(w.z); f[5] = bf_hi(w.z); f[6] = bf_lo(w.w); f[7] = bf_hi(w.w); }
; __device__ __forceinline__ v4u pack8(const float (&f)[8]) { v4u w; w.x = cvt_pk_bf16(f[0], f[1]); w.y = cvt_pk_bf16(f[2], f[3]); w.z = cvt_pk_bf16(f[4], f[5]); w.w = cvt_pk_bf16(f[6], f[7]); return w; }
; __device__ __forceinline__ void mixer_shortconv(const Frame& F, const Args& A, int l, int chunk, const bf16* Z, bf16* MIX) {
;     ...
;     for (int dt = -2; dt < 16; ++dt) {
;         const int t = t0 + dt; const bool valid = (pos0 + t) >= 0;
;         const bf16* zr = Z + (size_t)(row0 + (valid ? t : 0)) * ZC;
;         float xv[8], x[8];
;         unpack8(*(const GAS v4u*)(zr + 1024 + c8), xv);
; #pragma unroll
;         for (int j = 0; j < 8; ++j) x[j] = valid ? xv[j] : 0.f;
;         if (dt >= 0) { float bg[8], o[8]; unpack8(*(const GAS v4u*)(zr + 1536 + c8), bg);
; #pragma unroll
;             for (int j = 0; j < 8; ++j) o[j] = bg[j] * (w0[j] * xm2[j] + w1[j] * xm1[j] + w2[j] * x[j]);
;             *(GAS v4u*)(MIX + (size_t)(row0 + t) * D + 512 + c8) = pack8(o); }
; #pragma unroll
;         for (int j = 0; j < 8; ++j) { xm2[j] = xm1[j]; xm1[j] = x[j]; }
	v_lshlrev_b32_e32 v84, 16, v12
	v_and_b32_e32 v85, 0xffff0000, v12
	v_lshlrev_b32_e32 v86, 16, v13
	v_and_b32_e32 v87, 0xffff0000, v13
	v_lshlrev_b32_e32 v88, 16, v14
	v_and_b32_e32 v89, 0xffff0000, v14
	v_lshlrev_b32_e32 v90, 16, v15
	v_and_b32_e32 v91, 0xffff0000, v15
	v_cndmask_b32_e64 v84, 0, v84, s[40:41]
	v_cndmask_b32_e64 v85, 0, v85, s[40:41]
	v_cndmask_b32_e64 v86, 0, v86, s[40:41]
	v_cndmask_b32_e64 v87, 0, v87, s[40:41]
	v_cndmask_b32_e64 v88, 0, v88, s[40:41]
	v_cndmask_b32_e64 v89, 0, v89, s[40:41]
	v_cndmask_b32_e64 v90, 0, v90, s[40:41]
	v_cndmask_b32_e64 v91, 0, v91, s[40:41]
	v_lshlrev_b32_e32 v92, 16, v16
	v_and_b32_e32 v93, 0xffff0000, v16
	v_lshlrev_b32_e32 v94, 16, v17
	v_and_b32_e32 v95, 0xffff0000, v17
	v_lshlrev_b32_e32 v96, 16, v18
	v_and_b32_e32 v97, 0xffff0000, v18
	v_lshlrev_b32_e32 v98, 16, v19
	v_and_b32_e32 v99, 0xffff0000, v19
	v_cndmask_b32_e64 v92, 0, v92, s[40:41]
	v_cndmask_b32_e64 v93, 0, v93, s[40:41]
	v_cndmask_b32_e64 v94, 0, v94, s[40:41]
	v_cndmask_b32_e64 v95, 0, v95, s[40:41]
	v_cndmask_b32_e64 v96, 0, v96, s[40:41]
	v_cndmask_b32_e64 v97, 0, v97, s[40:41]
	v_cndmask_b32_e64 v98, 0, v98, s[40:41]
	v_cndmask_b32_e64 v99, 0, v99, s[40:41]
	v_lshlrev_b32_e32 v124, 16, v20
	v_and_b32_e32 v125, 0xffff0000, v20
	v_lshlrev_b32_e32 v126, 16, v21
	v_and_b32_e32 v127, 0xffff0000, v21
	v_lshlrev_b32_e32 v128, 16, v22
	v_and_b32_e32 v129, 0xffff0000, v22
	v_lshlrev_b32_e32 v130, 16, v23
	v_and_b32_e32 v131, 0xffff0000, v23
	v_lshlrev_b32_e32 v132, 16, v52
	v_and_b32_e32 v133, 0xffff0000, v52
	v_lshlrev_b32_e32 v134, 16, v53
	v_and_b32_e32 v135, 0xffff0000, v53
	v_lshlrev_b32_e32 v136, 16, v54
	v_and_b32_e32 v137, 0xffff0000, v54
	v_lshlrev_b32_e32 v138, 16, v55
	v_and_b32_e32 v139, 0xffff0000, v55
	v_mul_f32_e32 v140, v100, v84
	v_fmac_f32_e32 v140, v108, v92
	v_fmac_f32_e32 v140, v116, v124
	v_mul_f32_e32 v140, v132, v140
	v_mul_f32_e32 v141, v101, v85
	v_fmac_f32_e32 v141, v109, v93
	v_fmac_f32_e32 v141, v117, v125
	v_mul_f32_e32 v141, v133, v141
	v_mul_f32_e32 v142, v102, v86
	v_fmac_f32_e32 v142, v110, v94
	v_fmac_f32_e32 v142, v118, v126
	v_mul_f32_e32 v142, v134, v142
	v_mul_f32_e32 v143, v103, v87
	v_fmac_f32_e32 v143, v111, v95
	v_fmac_f32_e32 v143, v119, v127
	v_mul_f32_e32 v143, v135, v143
	v_mul_f32_e32 v144, v104, v88
	v_fmac_f32_e32 v144, v112, v96
	v_fmac_f32_e32 v144, v120, v128
	v_mul_f32_e32 v144, v136, v144
	v_mul_f32_e32 v145, v105, v89
	v_fmac_f32_e32 v145, v113, v97
	v_fmac_f32_e32 v145, v121, v129
	v_mul_f32_e32 v145, v137, v145
	v_mul_f32_e32 v146, v106, v90
	v_fmac_f32_e32 v146, v114, v98
	v_fmac_f32_e32 v146, v122, v130
	v_mul_f32_e32 v146, v138, v146
	v_mul_f32_e32 v147, v107, v91
	v_fmac_f32_e32 v147, v115, v99
	v_fmac_f32_e32 v147, v123, v131
	v_mul_f32_e32 v147, v139, v147
	v_cvt_pk_bf16_f32 v140, v140, v141
	v_cvt_pk_bf16_f32 v141, v142, v143
	v_cvt_pk_bf16_f32 v142, v144, v145
	v_cvt_pk_bf16_f32 v143, v146, v147
	global_store_dwordx4 v2, v[140:143], s[46:47] offset:1024
	s_add_u32 s46, s46, 0x1000
	s_addc_u32 s47, s47, 0
	global_load_dwordx4 v[20:23], v2, s[48:49] offset:2048
	global_load_dwordx4 v[52:55], v2, s[48:49] offset:3072
	s_add_u32 s48, s48, 0x1800
	s_addc_u32 s49, s49, 0
	v_lshlrev_b32_e32 v84, 16, v24
	v_and_b32_e32 v85, 0xffff0000, v24
	v_lshlrev_b32_e32 v86, 16, v25
	v_and_b32_e32 v87, 0xffff0000, v25
	v_lshlrev_b32_e32 v88, 16, v26
	v_and_b32_e32 v89, 0xffff0000, v26
	v_lshlrev_b32_e32 v90, 16, v27
	v_and_b32_e32 v91, 0xffff0000, v27
	v_lshlrev_b32_e32 v132, 16, v56
	v_and_b32_e32 v133, 0xffff0000, v56
	v_lshlrev_b32_e32 v134, 16, v57
	v_and_b32_e32 v135, 0xffff0000, v57
	v_lshlrev_b32_e32 v136, 16, v58
	v_and_b32_e32 v137, 0xffff0000, v58
	v_lshlrev_b32_e32 v138, 16, v59
	v_and_b32_e32 v139, 0xffff0000, v59
	v_mul_f32_e32 v140, v100, v92
	v_fmac_f32_e32 v140, v108, v124
	v_fmac_f32_e32 v140, v116, v84
	v_mul_f32_e32 v140, v132, v140
	v_mul_f32_e32 v141, v101, v93
	v_fmac_f32_e32 v141, v109, v125
	v_fmac_f32_e32 v141, v117, v85
	v_mul_f32_e32 v141, v133, v141
	v_mul_f32_e32 v142, v102, v94
	v_fmac_f32_e32 v142, v110, v126
	v_fmac_f32_e32 v142, v118, v86
	v_mul_f32_e32 v142, v134, v142
	v_mul_f32_e32 v143, v103, v95
	v_fmac_f32_e32 v143, v111, v127
	v_fmac_f32_e32 v143, v119, v87
	v_mul_f32_e32 v143, v135, v143
	v_mul_f32_e32 v144, v104, v96
	v_fmac_f32_e32 v144, v112, v128
	v_fmac_f32_e32 v144, v120, v88
	v_mul_f32_e32 v144, v136, v144
	v_mul_f32_e32 v145, v105, v97
	v_fmac_f32_e32 v145, v113, v129
	v_fmac_f32_e32 v145, v121, v89
	v_mul_f32_e32 v145, v137, v145
	v_mul_f32_e32 v146, v106, v98
	v_fmac_f32_e32 v146, v114, v130
	v_fmac_f32_e32 v146, v122, v90
	v_mul_f32_e32 v146, v138, v146
	v_mul_f32_e32 v147, v107, v99
	v_fmac_f32_e32 v147, v115, v131
	v_fmac_f32_e32 v147, v123, v91
	v_mul_f32_e32 v147, v139, v147
	v_cvt_pk_bf16_f32 v140, v140, v141
	v_cvt_pk_bf16_f32 v141, v142, v143
	v_cvt_pk_bf16_f32 v142, v144, v145
	v_cvt_pk_bf16_f32 v143, v146, v147
	global_store_dwordx4 v2, v[140:143], s[46:47] offset:1024
	s_add_u32 s46, s46, 0x1000
	s_addc_u32 s47, s47, 0
	global_load_dwordx4 v[24:27], v2, s[48:49] offset:2048
	global_load_dwordx4 v[56:59], v2, s[48:49] offset:3072
	s_add_u32 s48, s48, 0x1800
	s_addc_u32 s49, s49, 0
	v_lshlrev_b32_e32 v92, 16, v28
	v_and_b32_e32 v93, 0xffff0000, v28
	v_lshlrev_b32_e32 v94, 16, v29
	v_and_b32_e32 v95, 0xffff0000, v29
	v_lshlrev_b32_e32 v96, 16, v30
	v_and_b32_e32 v97, 0xffff0000, v30
	v_lshlrev_b32_e32 v98, 16, v31
	v_and_b32_e32 v99, 0xffff0000, v31
	v_lshlrev_b32_e32 v132, 16, v60
	v_and_b32_e32 v133, 0xffff0000, v60
	v_lshlrev_b32_e32 v134, 16, v61
	v_and_b32_e32 v135, 0xffff0000, v61
	v_lshlrev_b32_e32 v136, 16, v62
; #define GAS __attribute__((address_space(1)))
; __device__ __forceinline__ void unpack8(const v4u w, float (&f)[8]) { f[0] = bf_lo(w.x); f[1] = bf_hi(w.x); f[2] = bf_lo(w.y); f[3] = bf_hi(w.y); f[4] = bf_lo(w.z); f[5] = bf_hi(w.z); f[6] = bf_lo(w.w); f[7] = bf_hi(w.w); }
; __device__ __forceinline__ v4u pack8(const float (&f)[8]) { v4u w; w.x = cvt_pk_bf16(f[0], f[1]); w.y = cvt_pk_bf16(f[2], f[3]); w.z = cvt_pk_bf16(f[4], f[5]); w.w = cvt_pk_bf16(f[6], f[7]); return w; }
; __device__ __forceinline__ void mixer_shortconv(const Frame& F, const Args& A, int l, int chunk, const bf16* Z, bf16* MIX) {
;     ...
;     for (int dt = -2; dt < 16; ++dt) {
;         const int t = t0 + dt; const bool valid = (pos0 + t) >= 0;
;         const bf16* zr = Z + (size_t)(row0 + (valid ? t : 0)) * ZC;
;         float xv[8], x[8];
;         unpack8(*(const GAS v4u*)(zr + 1024 + c8), xv);
; #pragma unroll
;         for (int j = 0; j < 8; ++j) x[j] = valid ? xv[j] : 0.f;
;         if (dt >= 0) { float bg[8], o[8]; unpack8(*(const GAS v4u*)(zr + 1536 + c8), bg);
; #pragma unroll
;             for (int j = 0; j < 8; ++j) o[j] = bg[j] * (w0[j] * xm2[j] + w1[j] * xm1[j] + w2[j] * x[j]);
;             *(GAS v4u*)(MIX + (size_t)(row0 + t) * D + 512 + c8) = pack8(o); }
; #pragma unroll
;         for (int j = 0; j < 8; ++j) { xm2[j] = xm1[j]; xm1[j] = x[j]; }
	v_and_b32_e32 v137, 0xffff0000, v62
	v_lshlrev_b32_e32 v138, 16, v63
	v_and_b32_e32 v139, 0xffff0000, v63
	v_mul_f32_e32 v140, v100, v124
	v_fmac_f32_e32 v140, v108, v84
	v_fmac_f32_e32 v140, v116, v92
	v_mul_f32_e32 v140, v132, v140
	v_mul_f32_e32 v141, v101, v125
	v_fmac_f32_e32 v141, v109, v85
	v_fmac_f32_e32 v141, v117, v93
	v_mul_f32_e32 v141, v133, v141
	v_mul_f32_e32 v142, v102, v126
	v_fmac_f32_e32 v142, v110, v86
	v_fmac_f32_e32 v142, v118, v94
	v_mul_f32_e32 v142, v134, v142
	v_mul_f32_e32 v143, v103, v127
	v_fmac_f32_e32 v143, v111, v87
	v_fmac_f32_e32 v143, v119, v95
	v_mul_f32_e32 v143, v135, v143
	v_mul_f32_e32 v144, v104, v128
	v_fmac_f32_e32 v144, v112, v88
	v_fmac_f32_e32 v144, v120, v96
	v_mul_f32_e32 v144, v136, v144
	v_mul_f32_e32 v145, v105, v129
	v_fmac_f32_e32 v145, v113, v89
	v_fmac_f32_e32 v145, v121, v97
	v_mul_f32_e32 v145, v137, v145
	v_mul_f32_e32 v146, v106, v130
	v_fmac_f32_e32 v146, v114, v90
	v_fmac_f32_e32 v146, v122, v98
	v_mul_f32_e32 v146, v138, v146
	v_mul_f32_e32 v147, v107, v131
	v_fmac_f32_e32 v147, v115, v91
	v_fmac_f32_e32 v147, v123, v99
	v_mul_f32_e32 v147, v139, v147
	v_cvt_pk_bf16_f32 v140, v140, v141
	v_cvt_pk_bf16_f32 v141, v142, v143
	v_cvt_pk_bf16_f32 v142, v144, v145
	v_cvt_pk_bf16_f32 v143, v146, v147
	global_store_dwordx4 v2, v[140:143], s[46:47] offset:1024
	s_add_u32 s46, s46, 0x1000
	s_addc_u32 s47, s47, 0
	global_load_dwordx4 v[28:31], v2, s[48:49] offset:2048
	global_load_dwordx4 v[60:63], v2, s[48:49] offset:3072
	s_add_u32 s48, s48, 0x1800
	s_addc_u32 s49, s49, 0
	v_lshlrev_b32_e32 v124, 16, v32
	v_and_b32_e32 v125, 0xffff0000, v32
	v_lshlrev_b32_e32 v126, 16, v33
	v_and_b32_e32 v127, 0xffff0000, v33
	v_lshlrev_b32_e32 v128, 16, v34
	v_and_b32_e32 v129, 0xffff0000, v34
	v_lshlrev_b32_e32 v130, 16, v35
	v_and_b32_e32 v131, 0xffff0000, v35
	v_lshlrev_b32_e32 v132, 16, v64
	v_and_b32_e32 v133, 0xffff0000, v64
	v_lshlrev_b32_e32 v134, 16, v65
	v_and_b32_e32 v135, 0xffff0000, v65
	v_lshlrev_b32_e32 v136, 16, v66
	v_and_b32_e32 v137, 0xffff0000, v66
	v_lshlrev_b32_e32 v138, 16, v67
	v_and_b32_e32 v139, 0xffff0000, v67
	v_mul_f32_e32 v140, v100, v84
	v_fmac_f32_e32 v140, v108, v92
	v_fmac_f32_e32 v140, v116, v124
	v_mul_f32_e32 v140, v132, v140
	v_mul_f32_e32 v141, v101, v85
	v_fmac_f32_e32 v141, v109, v93
	v_fmac_f32_e32 v141, v117, v125
	v_mul_f32_e32 v141, v133, v141
	v_mul_f32_e32 v142, v102, v86
	v_fmac_f32_e32 v142, v110, v94
	v_fmac_f32_e32 v142, v118, v126
	v_mul_f32_e32 v142, v134, v142
	v_mul_f32_e32 v143, v103, v87
	v_fmac_f32_e32 v143, v111, v95
	v_fmac_f32_e32 v143, v119, v127
	v_mul_f32_e32 v143, v135, v143
	v_mul_f32_e32 v144, v104, v88
	v_fmac_f32_e32 v144, v112, v96
	v_fmac_f32_e32 v144, v120, v128
	v_mul_f32_e32 v144, v136, v144
	v_mul_f32_e32 v145, v105, v89
	v_fmac_f32_e32 v145, v113, v97
	v_fmac_f32_e32 v145, v121, v129
	v_mul_f32_e32 v145, v137, v145
	v_mul_f32_e32 v146, v106, v90
	v_fmac_f32_e32 v146, v114, v98
	v_fmac_f32_e32 v146, v122, v130
	v_mul_f32_e32 v146, v138, v146
	v_mul_f32_e32 v147, v107, v91
	v_fmac_f32_e32 v147, v115, v99
	v_fmac_f32_e32 v147, v123, v131
	v_mul_f32_e32 v147, v139, v147
	v_cvt_pk_bf16_f32 v140, v140, v141
	v_cvt_pk_bf16_f32 v141, v142, v143
	v_cvt_pk_bf16_f32 v142, v144, v145
	v_cvt_pk_bf16_f32 v143, v146, v147
	global_store_dwordx4 v2, v[140:143], s[46:47] offset:1024
	s_add_u32 s46, s46, 0x1000
	s_addc_u32 s47, s47, 0
	global_load_dwordx4 v[32:35], v2, s[48:49] offset:2048
	global_load_dwordx4 v[64:67], v2, s[48:49] offset:3072
	s_add_u32 s48, s48, 0x1800
	s_addc_u32 s49, s49, 0
	v_lshlrev_b32_e32 v84, 16, v36
	v_and_b32_e32 v85, 0xffff0000, v36
	v_lshlrev_b32_e32 v86, 16, v37
	v_and_b32_e32 v87, 0xffff0000, v37
	v_lshlrev_b32_e32 v88, 16, v38
	v_and_b32_e32 v89, 0xffff0000, v38
	v_lshlrev_b32_e32 v90, 16, v39
	v_and_b32_e32 v91, 0xffff0000, v39
	v_lshlrev_b32_e32 v132, 16, v68
	v_and_b32_e32 v133, 0xffff0000, v68
	v_lshlrev_b32_e32 v134, 16, v69
	v_and_b32_e32 v135, 0xffff0000, v69
	v_lshlrev_b32_e32 v136, 16, v70
	v_and_b32_e32 v137, 0xffff0000, v70
	v_lshlrev_b32_e32 v138, 16, v71
	v_and_b32_e32 v139, 0xffff0000, v71
	v_mul_f32_e32 v140, v100, v92
	v_fmac_f32_e32 v140, v108, v124
	v_fmac_f32_e32 v140, v116, v84
	v_mul_f32_e32 v140, v132, v140
	v_mul_f32_e32 v141, v101, v93
	v_fmac_f32_e32 v141, v109, v125
	v_fmac_f32_e32 v141, v117, v85
	v_mul_f32_e32 v141, v133, v141
	v_mul_f32_e32 v142, v102, v94
	v_fmac_f32_e32 v142, v110, v126
	v_fmac_f32_e32 v142, v118, v86
	v_mul_f32_e32 v142, v134, v142
	v_mul_f32_e32 v143, v103, v95
	v_fmac_f32_e32 v143, v111, v127
	v_fmac_f32_e32 v143, v119, v87
	v_mul_f32_e32 v143, v135, v143
	v_mul_f32_e32 v144, v104, v96
	v_fmac_f32_e32 v144, v112, v128
	v_fmac_f32_e32 v144, v120, v88
	v_mul_f32_e32 v144, v136, v144
	v_mul_f32_e32 v145, v105, v97
	v_fmac_f32_e32 v145, v113, v129
	v_fmac_f32_e32 v145, v121, v89
	v_mul_f32_e32 v145, v137, v145
	v_mul_f32_e32 v146, v106, v98
	v_fmac_f32_e32 v146, v114, v130
	v_fmac_f32_e32 v146, v122, v90
	v_mul_f32_e32 v146, v138, v146
	v_mul_f32_e32 v147, v107, v99
	v_fmac_f32_e32 v147, v115, v131
	v_fmac_f32_e32 v147, v123, v91
	v_mul_f32_e32 v147, v139, v147
	v_cvt_pk_bf16_f32 v140, v140, v141
	v_cvt_pk_bf16_f32 v141, v142, v143
	v_cvt_pk_bf16_f32 v142, v144, v145
	v_cvt_pk_bf16_f32 v143, v146, v147
	global_store_dwordx4 v2, v[140:143], s[46:47] offset:1024
	s_add_u32 s46, s46, 0x1000
	s_addc_u32 s47, s47, 0
	global_load_dwordx4 v[36:39], v2, s[48:49] offset:2048
	global_load_dwordx4 v[68:71], v2, s[48:49] offset:3072
	s_add_u32 s48, s48, 0x1800
	s_addc_u32 s49, s49, 0
	v_lshlrev_b32_e32 v92, 16, v40
	v_and_b32_e32 v93, 0xffff0000, v40
	v_lshlrev_b32_e32 v94, 16, v41
; #define GAS __attribute__((address_space(1)))
; __device__ __forceinline__ void unpack8(const v4u w, float (&f)[8]) { f[0] = bf_lo(w.x); f[1] = bf_hi(w.x); f[2] = bf_lo(w.y); f[3] = bf_hi(w.y); f[4] = bf_lo(w.z); f[5] = bf_hi(w.z); f[6] = bf_lo(w.w); f[7] = bf_hi(w.w); }
; __device__ __forceinline__ v4u pack8(const float (&f)[8]) { v4u w; w.x = cvt_pk_bf16(f[0], f[1]); w.y = cvt_pk_bf16(f[2], f[3]); w.z = cvt_pk_bf16(f[4], f[5]); w.w = cvt_pk_bf16(f[6], f[7]); return w; }
; __device__ __forceinline__ void mixer_shortconv(const Frame& F, const Args& A, int l, int chunk, const bf16* Z, bf16* MIX) {
;     ...
;     for (int dt = -2; dt < 16; ++dt) {
;         const int t = t0 + dt; const bool valid = (pos0 + t) >= 0;
;         const bf16* zr = Z + (size_t)(row0 + (valid ? t : 0)) * ZC;
;         float xv[8], x[8];
;         unpack8(*(const GAS v4u*)(zr + 1024 + c8), xv);
; #pragma unroll
;         for (int j = 0; j < 8; ++j) x[j] = valid ? xv[j] : 0.f;
;         if (dt >= 0) { float bg[8], o[8]; unpack8(*(const GAS v4u*)(zr + 1536 + c8), bg);
; #pragma unroll
;             for (int j = 0; j < 8; ++j) o[j] = bg[j] * (w0[j] * xm2[j] + w1[j] * xm1[j] + w2[j] * x[j]);
;             *(GAS v4u*)(MIX + (size_t)(row0 + t) * D + 512 + c8) = pack8(o); }
; #pragma unroll
;         for (int j = 0; j < 8; ++j) { xm2[j] = xm1[j]; xm1[j] = x[j]; }
;     }
; __device__ __forceinline__ void mixer_pool(const Frame& F, int l, int chunk, const bf16* Z, bf16* MIX) {
;     ...
;     const int i = lane & 15, g4 = lane >> 4, t = F.wave * 16 + i, row = chunk * 128 + t, pos = (chunk & 31) * 128 + t;
;     const bool prev_ok = ((chunk & 31) * 128 + F.wave * 16) > 0;
;     const bf16* pwt = (const bf16*)(F.ws + WS_PWT) + (size_t)l * 4 * 128 * 128 + (size_t)i * 128 + 8 * g4;
;     const bf16* zrow = Z + (size_t)row * ZC + 2560 + 8 * g4; bf16* orow = MIX + (size_t)row * D + 1536 + 4 * g4;
	v_and_b32_e32 v95, 0xffff0000, v41
	v_lshlrev_b32_e32 v96, 16, v42
	v_and_b32_e32 v97, 0xffff0000, v42
	v_lshlrev_b32_e32 v98, 16, v43
	v_and_b32_e32 v99, 0xffff0000, v43
	v_lshlrev_b32_e32 v132, 16, v72
	v_and_b32_e32 v133, 0xffff0000, v72
	v_lshlrev_b32_e32 v134, 16, v73
	v_and_b32_e32 v135, 0xffff0000, v73
	v_lshlrev_b32_e32 v136, 16, v74
	v_and_b32_e32 v137, 0xffff0000, v74
	v_lshlrev_b32_e32 v138, 16, v75
	v_and_b32_e32 v139, 0xffff0000, v75
	v_mul_f32_e32 v140, v100, v124
	v_fmac_f32_e32 v140, v108, v84
	v_fmac_f32_e32 v140, v116, v92
	v_mul_f32_e32 v140, v132, v140
	v_mul_f32_e32 v141, v101, v125
	v_fmac_f32_e32 v141, v109, v85
	v_fmac_f32_e32 v141, v117, v93
	v_mul_f32_e32 v141, v133, v141
	v_mul_f32_e32 v142, v102, v126
	v_fmac_f32_e32 v142, v110, v86
	v_fmac_f32_e32 v142, v118, v94
	v_mul_f32_e32 v142, v134, v142
	v_mul_f32_e32 v143, v103, v127
	v_fmac_f32_e32 v143, v111, v87
	v_fmac_f32_e32 v143, v119, v95
	v_mul_f32_e32 v143, v135, v143
	v_mul_f32_e32 v144, v104, v128
	v_fmac_f32_e32 v144, v112, v88
	v_fmac_f32_e32 v144, v120, v96
	v_mul_f32_e32 v144, v136, v144
	v_mul_f32_e32 v145, v105, v129
	v_fmac_f32_e32 v145, v113, v89
	v_fmac_f32_e32 v145, v121, v97
	v_mul_f32_e32 v145, v137, v145
	v_mul_f32_e32 v146, v106, v130
	v_fmac_f32_e32 v146, v114, v90
	v_fmac_f32_e32 v146, v122, v98
	v_mul_f32_e32 v146, v138, v146
	v_mul_f32_e32 v147, v107, v131
	v_fmac_f32_e32 v147, v115, v91
	v_fmac_f32_e32 v147, v123, v99
	v_mul_f32_e32 v147, v139, v147
	v_cvt_pk_bf16_f32 v140, v140, v141
	v_cvt_pk_bf16_f32 v141, v142, v143
	v_cvt_pk_bf16_f32 v142, v144, v145
	v_cvt_pk_bf16_f32 v143, v146, v147
	global_store_dwordx4 v2, v[140:143], s[46:47] offset:1024
	s_add_u32 s46, s46, 0x1000
	s_addc_u32 s47, s47, 0
	global_load_dwordx4 v[40:43], v2, s[48:49] offset:2048
	global_load_dwordx4 v[72:75], v2, s[48:49] offset:3072
	s_add_u32 s48, s48, 0x1800
	s_addc_u32 s49, s49, 0
	v_lshlrev_b32_e32 v124, 16, v44
	v_and_b32_e32 v125, 0xffff0000, v44
	v_lshlrev_b32_e32 v126, 16, v45
	v_and_b32_e32 v127, 0xffff0000, v45
	v_lshlrev_b32_e32 v128, 16, v46
	v_and_b32_e32 v129, 0xffff0000, v46
	v_lshlrev_b32_e32 v130, 16, v47
	v_and_b32_e32 v131, 0xffff0000, v47
	v_lshlrev_b32_e32 v132, 16, v76
	v_and_b32_e32 v133, 0xffff0000, v76
	v_lshlrev_b32_e32 v134, 16, v77
	v_and_b32_e32 v135, 0xffff0000, v77
	v_lshlrev_b32_e32 v136, 16, v78
	v_and_b32_e32 v137, 0xffff0000, v78
	v_lshlrev_b32_e32 v138, 16, v79
	v_and_b32_e32 v139, 0xffff0000, v79
	v_mul_f32_e32 v140, v100, v84
	v_fmac_f32_e32 v140, v108, v92
	v_fmac_f32_e32 v140, v116, v124
	v_mul_f32_e32 v140, v132, v140
	v_mul_f32_e32 v141, v101, v85
	v_fmac_f32_e32 v141, v109, v93
	v_fmac_f32_e32 v141, v117, v125
	v_mul_f32_e32 v141, v133, v141
	v_mul_f32_e32 v142, v102, v86
	v_fmac_f32_e32 v142, v110, v94
	v_fmac_f32_e32 v142, v118, v126
	v_mul_f32_e32 v142, v134, v142
	v_mul_f32_e32 v143, v103, v87
	v_fmac_f32_e32 v143, v111, v95
	v_fmac_f32_e32 v143, v119, v127
	v_mul_f32_e32 v143, v135, v143
	v_mul_f32_e32 v144, v104, v88
	v_fmac_f32_e32 v144, v112, v96
	v_fmac_f32_e32 v144, v120, v128
	v_mul_f32_e32 v144, v136, v144
	v_mul_f32_e32 v145, v105, v89
	v_fmac_f32_e32 v145, v113, v97
	v_fmac_f32_e32 v145, v121, v129
	v_mul_f32_e32 v145, v137, v145
	v_mul_f32_e32 v146, v106, v90
	v_fmac_f32_e32 v146, v114, v98
	v_fmac_f32_e32 v146, v122, v130
	v_mul_f32_e32 v146, v138, v146
	v_mul_f32_e32 v147, v107, v91
	v_fmac_f32_e32 v147, v115, v99
	v_fmac_f32_e32 v147, v123, v131
	v_mul_f32_e32 v147, v139, v147
	v_cvt_pk_bf16_f32 v140, v140, v141
	v_cvt_pk_bf16_f32 v141, v142, v143
	v_cvt_pk_bf16_f32 v142, v144, v145
	v_cvt_pk_bf16_f32 v143, v146, v147
	global_store_dwordx4 v2, v[140:143], s[46:47] offset:1024
	s_add_u32 s46, s46, 0x1000
	s_addc_u32 s47, s47, 0
	global_load_dwordx4 v[44:47], v2, s[48:49] offset:2048
	global_load_dwordx4 v[76:79], v2, s[48:49] offset:3072
	s_add_u32 s48, s48, 0x1800
	s_addc_u32 s49, s49, 0
	v_lshlrev_b32_e32 v84, 16, v48
	v_and_b32_e32 v85, 0xffff0000, v48
	v_lshlrev_b32_e32 v86, 16, v49
	v_and_b32_e32 v87, 0xffff0000, v49
	v_lshlrev_b32_e32 v88, 16, v50
	v_and_b32_e32 v89, 0xffff0000, v50
	v_lshlrev_b32_e32 v90, 16, v51
	v_and_b32_e32 v91, 0xffff0000, v51
	v_lshlrev_b32_e32 v132, 16, v80
	v_and_b32_e32 v133, 0xffff0000, v80
	v_lshlrev_b32_e32 v134, 16, v81
	v_and_b32_e32 v135, 0xffff0000, v81
	v_lshlrev_b32_e32 v136, 16, v82
	v_and_b32_e32 v137, 0xffff0000, v82
	v_lshlrev_b32_e32 v138, 16, v83
	v_and_b32_e32 v139, 0xffff0000, v83
	v_mul_f32_e32 v140, v100, v92
	v_fmac_f32_e32 v140, v108, v124
	v_fmac_f32_e32 v140, v116, v84
	v_mul_f32_e32 v140, v132, v140
	v_mul_f32_e32 v141, v101, v93
	v_fmac_f32_e32 v141, v109, v125
	v_fmac_f32_e32 v141, v117, v85
	v_mul_f32_e32 v141, v133, v141
	v_mul_f32_e32 v142, v102, v94
	v_fmac_f32_e32 v142, v110, v126
	v_fmac_f32_e32 v142, v118, v86
	v_mul_f32_e32 v142, v134, v142
	v_mul_f32_e32 v143, v103, v95
	v_fmac_f32_e32 v143, v111, v127
	v_fmac_f32_e32 v143, v119, v87
	v_mul_f32_e32 v143, v135, v143
	v_mul_f32_e32 v144, v104, v96
	v_fmac_f32_e32 v144, v112, v128
	v_fmac_f32_e32 v144, v120, v88
	v_mul_f32_e32 v144, v136, v144
	v_mul_f32_e32 v145, v105, v97
	v_fmac_f32_e32 v145, v113, v129
	v_fmac_f32_e32 v145, v121, v89
	v_mul_f32_e32 v145, v137, v145
	v_mul_f32_e32 v146, v106, v98
	v_fmac_f32_e32 v146, v114, v130
	v_fmac_f32_e32 v146, v122, v90
	v_mul_f32_e32 v146, v138, v146
	v_mul_f32_e32 v147, v107, v99
	v_fmac_f32_e32 v147, v115, v131
	v_fmac_f32_e32 v147, v123, v91
	v_mul_f32_e32 v147, v139, v147
	v_cvt_pk_bf16_f32 v140, v140, v141
	v_cvt_pk_bf16_f32 v141, v142, v143
	v_cvt_pk_bf16_f32 v142, v144, v145
	v_cvt_pk_bf16_f32 v143, v146, v147
	global_store_dwordx4 v2, v[140:143], s[46:47] offset:1024
	s_add_u32 s46, s46, 0x1000
	s_addc_u32 s47, s47, 0
	global_load_dwordx4 v[48:51], v2, s[48:49] offset:2048
	global_load_dwordx4 v[80:83], v2, s[48:49] offset:3072
	s_add_u32 s48, s48, 0x1800
	s_addc_u32 s49, s49, 0
	v_mul_u32_u24_e32 v11, 0x1800, v4
	v_lshl_add_u32 v11, v5, 4, v11
	s_add_u32 s38, s38, 0x1400
	s_addc_u32 s39, s39, 0
	s_sub_u32 s48, s38, 0x18000
	s_subb_u32 s49, s39, 0
	s_and_b64 vcc, s[40:41], exec
	s_cselect_b32 s48, s48, s38
	s_cselect_b32 s49, s49, s39
	s_waitcnt vmcnt(21)
; #define GAS __attribute__((address_space(1)))
; __device__ __forceinline__ void unpack8(const v4u w, float (&f)[8]) { f[0] = bf_lo(w.x); f[1] = bf_hi(w.x); f[2] = bf_lo(w.y); f[3] = bf_hi(w.y); f[4] = bf_lo(w.z); f[5] = bf_hi(w.z); f[6] = bf_lo(w.w); f[7] = bf_hi(w.w); }
; __device__ __forceinline__ v4u pack8(const float (&f)[8]) { v4u w; w.x = cvt_pk_bf16(f[0], f[1]); w.y = cvt_pk_bf16(f[2], f[3]); w.z = cvt_pk_bf16(f[4], f[5]); w.w = cvt_pk_bf16(f[6], f[7]); return w; }
; __device__ __forceinline__ void mixer_shortconv(const Frame& F, const Args& A, int l, int chunk, const bf16* Z, bf16* MIX) {
;     ...
;     for (int dt = -2; dt < 16; ++dt) {
;         const int t = t0 + dt; const bool valid = (pos0 + t) >= 0;
;         const bf16* zr = Z + (size_t)(row0 + (valid ? t : 0)) * ZC;
;         float xv[8], x[8];
;         unpack8(*(const GAS v4u*)(zr + 1024 + c8), xv);
; #pragma unroll
;         for (int j = 0; j < 8; ++j) x[j] = valid ? xv[j] : 0.f;
;         if (dt >= 0) { float bg[8], o[8]; unpack8(*(const GAS v4u*)(zr + 1536 + c8), bg);
; #pragma unroll
;             for (int j = 0; j < 8; ++j) o[j] = bg[j] * (w0[j] * xm2[j] + w1[j] * xm1[j] + w2[j] * x[j]);
;             *(GAS v4u*)(MIX + (size_t)(row0 + t) * D + 512 + c8) = pack8(o); }
; #pragma unroll
;         for (int j = 0; j < 8; ++j) { xm2[j] = xm1[j]; xm1[j] = x[j]; }
;     }
; template <int W> __device__ __forceinline__ void pool_group(const bf16* zrow  , const bf16* pw  , bf16* orow  , int pos, bool prev_ok) {
;     ...
;     for (int kk = 0; kk < 4; ++kk) { cw[kk] = *(const GAS v4u*)(zrow + 32 * kk); pv[kk] = prev_ok ? *(const GAS v4u*)(zrow + 32 * kk - (ptrdiff_t)16 * ZC) : (v4u){0u, 0u, 0u, 0u}; }
	v_lshlrev_b32_e32 v92, 16, v20
	v_and_b32_e32 v93, 0xffff0000, v20
	v_lshlrev_b32_e32 v94, 16, v21
	v_and_b32_e32 v95, 0xffff0000, v21
	v_lshlrev_b32_e32 v96, 16, v22
	v_and_b32_e32 v97, 0xffff0000, v22
	v_lshlrev_b32_e32 v98, 16, v23
	v_and_b32_e32 v99, 0xffff0000, v23
	v_lshlrev_b32_e32 v132, 16, v52
	v_and_b32_e32 v133, 0xffff0000, v52
	v_lshlrev_b32_e32 v134, 16, v53
	v_and_b32_e32 v135, 0xffff0000, v53
	v_lshlrev_b32_e32 v136, 16, v54
	v_and_b32_e32 v137, 0xffff0000, v54
	v_lshlrev_b32_e32 v138, 16, v55
	v_and_b32_e32 v139, 0xffff0000, v55
	v_mul_f32_e32 v140, v100, v124
	v_fmac_f32_e32 v140, v108, v84
	v_fmac_f32_e32 v140, v116, v92
	v_mul_f32_e32 v140, v132, v140
	v_mul_f32_e32 v141, v101, v125
	v_fmac_f32_e32 v141, v109, v85
	v_fmac_f32_e32 v141, v117, v93
	v_mul_f32_e32 v141, v133, v141
	v_mul_f32_e32 v142, v102, v126
	v_fmac_f32_e32 v142, v110, v86
	v_fmac_f32_e32 v142, v118, v94
	v_mul_f32_e32 v142, v134, v142
	v_mul_f32_e32 v143, v103, v127
	v_fmac_f32_e32 v143, v111, v87
	v_fmac_f32_e32 v143, v119, v95
	v_mul_f32_e32 v143, v135, v143
	v_mul_f32_e32 v144, v104, v128
	v_fmac_f32_e32 v144, v112, v88
	v_fmac_f32_e32 v144, v120, v96
	v_mul_f32_e32 v144, v136, v144
	v_mul_f32_e32 v145, v105, v129
	v_fmac_f32_e32 v145, v113, v89
	v_fmac_f32_e32 v145, v121, v97
	v_mul_f32_e32 v145, v137, v145
	v_mul_f32_e32 v146, v106, v130
	v_fmac_f32_e32 v146, v114, v90
	v_fmac_f32_e32 v146, v122, v98
	v_mul_f32_e32 v146, v138, v146
	v_mul_f32_e32 v147, v107, v131
	v_fmac_f32_e32 v147, v115, v91
	v_fmac_f32_e32 v147, v123, v99
	v_mul_f32_e32 v147, v139, v147
	v_cvt_pk_bf16_f32 v140, v140, v141
	v_cvt_pk_bf16_f32 v141, v142, v143
	v_cvt_pk_bf16_f32 v142, v144, v145
	v_cvt_pk_bf16_f32 v143, v146, v147
	global_store_dwordx4 v2, v[140:143], s[46:47] offset:1024
	s_add_u32 s46, s46, 0x1000
	s_addc_u32 s47, s47, 0
	global_load_dwordx4 v[12:15], v11, s[38:39]
	global_load_dwordx4 v[16:19], v11, s[48:49]
	s_waitcnt vmcnt(21)
	v_lshlrev_b32_e32 v124, 16, v24
	v_and_b32_e32 v125, 0xffff0000, v24
	v_lshlrev_b32_e32 v126, 16, v25
	v_and_b32_e32 v127, 0xffff0000, v25
	v_lshlrev_b32_e32 v128, 16, v26
	v_and_b32_e32 v129, 0xffff0000, v26
	v_lshlrev_b32_e32 v130, 16, v27
	v_and_b32_e32 v131, 0xffff0000, v27
	v_lshlrev_b32_e32 v132, 16, v56
	v_and_b32_e32 v133, 0xffff0000, v56
	v_lshlrev_b32_e32 v134, 16, v57
	v_and_b32_e32 v135, 0xffff0000, v57
	v_lshlrev_b32_e32 v136, 16, v58
	v_and_b32_e32 v137, 0xffff0000, v58
	v_lshlrev_b32_e32 v138, 16, v59
	v_and_b32_e32 v139, 0xffff0000, v59
	v_mul_f32_e32 v140, v100, v84
	v_fmac_f32_e32 v140, v108, v92
	v_fmac_f32_e32 v140, v116, v124
	v_mul_f32_e32 v140, v132, v140
	v_mul_f32_e32 v141, v101, v85
	v_fmac_f32_e32 v141, v109, v93
	v_fmac_f32_e32 v141, v117, v125
	v_mul_f32_e32 v141, v133, v141
	v_mul_f32_e32 v142, v102, v86
	v_fmac_f32_e32 v142, v110, v94
	v_fmac_f32_e32 v142, v118, v126
	v_mul_f32_e32 v142, v134, v142
	v_mul_f32_e32 v143, v103, v87
	v_fmac_f32_e32 v143, v111, v95
	v_fmac_f32_e32 v143, v119, v127
	v_mul_f32_e32 v143, v135, v143
	v_mul_f32_e32 v144, v104, v88
	v_fmac_f32_e32 v144, v112, v96
	v_fmac_f32_e32 v144, v120, v128
	v_mul_f32_e32 v144, v136, v144
	v_mul_f32_e32 v145, v105, v89
	v_fmac_f32_e32 v145, v113, v97
	v_fmac_f32_e32 v145, v121, v129
	v_mul_f32_e32 v145, v137, v145
	v_mul_f32_e32 v146, v106, v90
	v_fmac_f32_e32 v146, v114, v98
	v_fmac_f32_e32 v146, v122, v130
	v_mul_f32_e32 v146, v138, v146
	v_mul_f32_e32 v147, v107, v91
	v_fmac_f32_e32 v147, v115, v99
	v_fmac_f32_e32 v147, v123, v131
	v_mul_f32_e32 v147, v139, v147
	v_cvt_pk_bf16_f32 v140, v140, v141
	v_cvt_pk_bf16_f32 v141, v142, v143
	v_cvt_pk_bf16_f32 v142, v144, v145
	v_cvt_pk_bf16_f32 v143, v146, v147
	global_store_dwordx4 v2, v[140:143], s[46:47] offset:1024
	s_add_u32 s46, s46, 0x1000
	s_addc_u32 s47, s47, 0
	global_load_dwordx4 v[20:23], v11, s[38:39] offset:64
	global_load_dwordx4 v[24:27], v11, s[48:49] offset:64
	s_waitcnt vmcnt(21)
	v_lshlrev_b32_e32 v84, 16, v28
	v_and_b32_e32 v85, 0xffff0000, v28
	v_lshlrev_b32_e32 v86, 16, v29
	v_and_b32_e32 v87, 0xffff0000, v29
	v_lshlrev_b32_e32 v88, 16, v30
	v_and_b32_e32 v89, 0xffff0000, v30
	v_lshlrev_b32_e32 v90, 16, v31
	v_and_b32_e32 v91, 0xffff0000, v31
	v_lshlrev_b32_e32 v132, 16, v60
	v_and_b32_e32 v133, 0xffff0000, v60
	v_lshlrev_b32_e32 v134, 16, v61
	v_and_b32_e32 v135, 0xffff0000, v61
	v_lshlrev_b32_e32 v136, 16, v62
	v_and_b32_e32 v137, 0xffff0000, v62
	v_lshlrev_b32_e32 v138, 16, v63
	v_and_b32_e32 v139, 0xffff0000, v63
	v_mul_f32_e32 v140, v100, v92
	v_fmac_f32_e32 v140, v108, v124
	v_fmac_f32_e32 v140, v116, v84
	v_mul_f32_e32 v140, v132, v140
	v_mul_f32_e32 v141, v101, v93
	v_fmac_f32_e32 v141, v109, v125
	v_fmac_f32_e32 v141, v117, v85
	v_mul_f32_e32 v141, v133, v141
	v_mul_f32_e32 v142, v102, v94
	v_fmac_f32_e32 v142, v110, v126
	v_fmac_f32_e32 v142, v118, v86
	v_mul_f32_e32 v142, v134, v142
	v_mul_f32_e32 v143, v103, v95
	v_fmac_f32_e32 v143, v111, v127
	v_fmac_f32_e32 v143, v119, v87
	v_mul_f32_e32 v143, v135, v143
	v_mul_f32_e32 v144, v104, v96
	v_fmac_f32_e32 v144, v112, v128
	v_fmac_f32_e32 v144, v120, v88
	v_mul_f32_e32 v144, v136, v144
	v_mul_f32_e32 v145, v105, v97
	v_fmac_f32_e32 v145, v113, v129
	v_fmac_f32_e32 v145, v121, v89
	v_mul_f32_e32 v145, v137, v145
	v_mul_f32_e32 v146, v106, v98
	v_fmac_f32_e32 v146, v114, v130
	v_fmac_f32_e32 v146, v122, v90
	v_mul_f32_e32 v146, v138, v146
	v_mul_f32_e32 v147, v107, v99
	v_fmac_f32_e32 v147, v115, v131
	v_fmac_f32_e32 v147, v123, v91
	v_mul_f32_e32 v147, v139, v147
	v_cvt_pk_bf16_f32 v140, v140, v141
	v_cvt_pk_bf16_f32 v141, v142, v143
	v_cvt_pk_bf16_f32 v142, v144, v145
	v_cvt_pk_bf16_f32 v143, v146, v147
	global_store_dwordx4 v2, v[140:143], s[46:47] offset:1024
	s_add_u32 s46, s46, 0x1000
	s_addc_u32 s47, s47, 0
	s_waitcnt vmcnt(19)
; #define GAS __attribute__((address_space(1)))
; __device__ __forceinline__ void unpack8(const v4u w, float (&f)[8]) { f[0] = bf_lo(w.x); f[1] = bf_hi(w.x); f[2] = bf_lo(w.y); f[3] = bf_hi(w.y); f[4] = bf_lo(w.z); f[5] = bf_hi(w.z); f[6] = bf_lo(w.w); f[7] = bf_hi(w.w); }
; __device__ __forceinline__ v4u pack8(const float (&f)[8]) { v4u w; w.x = cvt_pk_bf16(f[0], f[1]); w.y = cvt_pk_bf16(f[2], f[3]); w.z = cvt_pk_bf16(f[4], f[5]); w.w = cvt_pk_bf16(f[6], f[7]); return w; }
; __device__ __forceinline__ void mixer_shortconv(const Frame& F, const Args& A, int l, int chunk, const bf16* Z, bf16* MIX) {
;     ...
;     for (int dt = -2; dt < 16; ++dt) {
;         const int t = t0 + dt; const bool valid = (pos0 + t) >= 0;
;         const bf16* zr = Z + (size_t)(row0 + (valid ? t : 0)) * ZC;
;         float xv[8], x[8];
;         unpack8(*(const GAS v4u*)(zr + 1024 + c8), xv);
; #pragma unroll
;         for (int j = 0; j < 8; ++j) x[j] = valid ? xv[j] : 0.f;
;         if (dt >= 0) { float bg[8], o[8]; unpack8(*(const GAS v4u*)(zr + 1536 + c8), bg);
; #pragma unroll
;             for (int j = 0; j < 8; ++j) o[j] = bg[j] * (w0[j] * xm2[j] + w1[j] * xm1[j] + w2[j] * x[j]);
;             *(GAS v4u*)(MIX + (size_t)(row0 + t) * D + 512 + c8) = pack8(o); }
; #pragma unroll
;         for (int j = 0; j < 8; ++j) { xm2[j] = xm1[j]; xm1[j] = x[j]; }
;     }
; template <int W> __device__ __forceinline__ void pool_group(const bf16* zrow  , const bf16* pw  , bf16* orow  , int pos, bool prev_ok) {
;     ...
;     for (int kk = 0; kk < 4; ++kk) { cw[kk] = *(const GAS v4u*)(zrow + 32 * kk); pv[kk] = prev_ok ? *(const GAS v4u*)(zrow + 32 * kk - (ptrdiff_t)16 * ZC) : (v4u){0u, 0u, 0u, 0u}; }
	v_lshlrev_b32_e32 v92, 16, v32
	v_and_b32_e32 v93, 0xffff0000, v32
	v_lshlrev_b32_e32 v94, 16, v33
	v_and_b32_e32 v95, 0xffff0000, v33
	v_lshlrev_b32_e32 v96, 16, v34
	v_and_b32_e32 v97, 0xffff0000, v34
	v_lshlrev_b32_e32 v98, 16, v35
	v_and_b32_e32 v99, 0xffff0000, v35
	v_lshlrev_b32_e32 v132, 16, v64
	v_and_b32_e32 v133, 0xffff0000, v64
	v_lshlrev_b32_e32 v134, 16, v65
	v_and_b32_e32 v135, 0xffff0000, v65
	v_lshlrev_b32_e32 v136, 16, v66
	v_and_b32_e32 v137, 0xffff0000, v66
	v_lshlrev_b32_e32 v138, 16, v67
	v_and_b32_e32 v139, 0xffff0000, v67
	v_mul_f32_e32 v140, v100, v124
	v_fmac_f32_e32 v140, v108, v84
	v_fmac_f32_e32 v140, v116, v92
	v_mul_f32_e32 v140, v132, v140
	v_mul_f32_e32 v141, v101, v125
	v_fmac_f32_e32 v141, v109, v85
	v_fmac_f32_e32 v141, v117, v93
	v_mul_f32_e32 v141, v133, v141
	v_mul_f32_e32 v142, v102, v126
	v_fmac_f32_e32 v142, v110, v86
	v_fmac_f32_e32 v142, v118, v94
	v_mul_f32_e32 v142, v134, v142
	v_mul_f32_e32 v143, v103, v127
	v_fmac_f32_e32 v143, v111, v87
	v_fmac_f32_e32 v143, v119, v95
	v_mul_f32_e32 v143, v135, v143
	v_mul_f32_e32 v144, v104, v128
	v_fmac_f32_e32 v144, v112, v88
	v_fmac_f32_e32 v144, v120, v96
	v_mul_f32_e32 v144, v136, v144
	v_mul_f32_e32 v145, v105, v129
	v_fmac_f32_e32 v145, v113, v89
	v_fmac_f32_e32 v145, v121, v97
	v_mul_f32_e32 v145, v137, v145
	v_mul_f32_e32 v146, v106, v130
	v_fmac_f32_e32 v146, v114, v90
	v_fmac_f32_e32 v146, v122, v98
	v_mul_f32_e32 v146, v138, v146
	v_mul_f32_e32 v147, v107, v131
	v_fmac_f32_e32 v147, v115, v91
	v_fmac_f32_e32 v147, v123, v99
	v_mul_f32_e32 v147, v139, v147
	v_cvt_pk_bf16_f32 v140, v140, v141
	v_cvt_pk_bf16_f32 v141, v142, v143
	v_cvt_pk_bf16_f32 v142, v144, v145
	v_cvt_pk_bf16_f32 v143, v146, v147
	global_store_dwordx4 v2, v[140:143], s[46:47] offset:1024
	s_add_u32 s46, s46, 0x1000
	s_addc_u32 s47, s47, 0
	global_load_dwordx4 v[28:31], v11, s[38:39] offset:128
	global_load_dwordx4 v[32:35], v11, s[48:49] offset:128
	s_waitcnt vmcnt(19)
	v_lshlrev_b32_e32 v124, 16, v36
	v_and_b32_e32 v125, 0xffff0000, v36
	v_lshlrev_b32_e32 v126, 16, v37
	v_and_b32_e32 v127, 0xffff0000, v37
	v_lshlrev_b32_e32 v128, 16, v38
	v_and_b32_e32 v129, 0xffff0000, v38
	v_lshlrev_b32_e32 v130, 16, v39
	v_and_b32_e32 v131, 0xffff0000, v39
	v_lshlrev_b32_e32 v132, 16, v68
	v_and_b32_e32 v133, 0xffff0000, v68
	v_lshlrev_b32_e32 v134, 16, v69
	v_and_b32_e32 v135, 0xffff0000, v69
	v_lshlrev_b32_e32 v136, 16, v70
	v_and_b32_e32 v137, 0xffff0000, v70
	v_lshlrev_b32_e32 v138, 16, v71
	v_and_b32_e32 v139, 0xffff0000, v71
	v_mul_f32_e32 v140, v100, v84
	v_fmac_f32_e32 v140, v108, v92
	v_fmac_f32_e32 v140, v116, v124
	v_mul_f32_e32 v140, v132, v140
	v_mul_f32_e32 v141, v101, v85
	v_fmac_f32_e32 v141, v109, v93
	v_fmac_f32_e32 v141, v117, v125
	v_mul_f32_e32 v141, v133, v141
	v_mul_f32_e32 v142, v102, v86
	v_fmac_f32_e32 v142, v110, v94
	v_fmac_f32_e32 v142, v118, v126
	v_mul_f32_e32 v142, v134, v142
	v_mul_f32_e32 v143, v103, v87
	v_fmac_f32_e32 v143, v111, v95
	v_fmac_f32_e32 v143, v119, v127
	v_mul_f32_e32 v143, v135, v143
	v_mul_f32_e32 v144, v104, v88
	v_fmac_f32_e32 v144, v112, v96
	v_fmac_f32_e32 v144, v120, v128
	v_mul_f32_e32 v144, v136, v144
	v_mul_f32_e32 v145, v105, v89
	v_fmac_f32_e32 v145, v113, v97
	v_fmac_f32_e32 v145, v121, v129
	v_mul_f32_e32 v145, v137, v145
	v_mul_f32_e32 v146, v106, v90
	v_fmac_f32_e32 v146, v114, v98
	v_fmac_f32_e32 v146, v122, v130
	v_mul_f32_e32 v146, v138, v146
	v_mul_f32_e32 v147, v107, v91
	v_fmac_f32_e32 v147, v115, v99
	v_fmac_f32_e32 v147, v123, v131
	v_mul_f32_e32 v147, v139, v147
	v_cvt_pk_bf16_f32 v140, v140, v141
	v_cvt_pk_bf16_f32 v141, v142, v143
	v_cvt_pk_bf16_f32 v142, v144, v145
	v_cvt_pk_bf16_f32 v143, v146, v147
	global_store_dwordx4 v2, v[140:143], s[46:47] offset:1024
	s_add_u32 s46, s46, 0x1000
	s_addc_u32 s47, s47, 0
	s_waitcnt vmcnt(17)
	v_lshlrev_b32_e32 v84, 16, v40
	v_and_b32_e32 v85, 0xffff0000, v40
	v_lshlrev_b32_e32 v86, 16, v41
	v_and_b32_e32 v87, 0xffff0000, v41
	v_lshlrev_b32_e32 v88, 16, v42
	v_and_b32_e32 v89, 0xffff0000, v42
	v_lshlrev_b32_e32 v90, 16, v43
	v_and_b32_e32 v91, 0xffff0000, v43
	v_lshlrev_b32_e32 v132, 16, v72
	v_and_b32_e32 v133, 0xffff0000, v72
	v_lshlrev_b32_e32 v134, 16, v73
	v_and_b32_e32 v135, 0xffff0000, v73
	v_lshlrev_b32_e32 v136, 16, v74
	v_and_b32_e32 v137, 0xffff0000, v74
	v_lshlrev_b32_e32 v138, 16, v75
	v_and_b32_e32 v139, 0xffff0000, v75
	v_mul_f32_e32 v140, v100, v92
	v_fmac_f32_e32 v140, v108, v124
	v_fmac_f32_e32 v140, v116, v84
	v_mul_f32_e32 v140, v132, v140
	v_mul_f32_e32 v141, v101, v93
	v_fmac_f32_e32 v141, v109, v125
	v_fmac_f32_e32 v141, v117, v85
	v_mul_f32_e32 v141, v133, v141
	v_mul_f32_e32 v142, v102, v94
	v_fmac_f32_e32 v142, v110, v126
	v_fmac_f32_e32 v142, v118, v86
	v_mul_f32_e32 v142, v134, v142
	v_mul_f32_e32 v143, v103, v95
	v_fmac_f32_e32 v143, v111, v127
	v_fmac_f32_e32 v143, v119, v87
	v_mul_f32_e32 v143, v135, v143
	v_mul_f32_e32 v144, v104, v96
	v_fmac_f32_e32 v144, v112, v128
	v_fmac_f32_e32 v144, v120, v88
	v_mul_f32_e32 v144, v136, v144
	v_mul_f32_e32 v145, v105, v97
	v_fmac_f32_e32 v145, v113, v129
	v_fmac_f32_e32 v145, v121, v89
	v_mul_f32_e32 v145, v137, v145
	v_mul_f32_e32 v146, v106, v98
	v_fmac_f32_e32 v146, v114, v130
	v_fmac_f32_e32 v146, v122, v90
	v_mul_f32_e32 v146, v138, v146
	v_mul_f32_e32 v147, v107, v99
	v_fmac_f32_e32 v147, v115, v131
	v_fmac_f32_e32 v147, v123, v91
	v_mul_f32_e32 v147, v139, v147
	v_cvt_pk_bf16_f32 v140, v140, v141
	v_cvt_pk_bf16_f32 v141, v142, v143
	v_cvt_pk_bf16_f32 v142, v144, v145
	v_cvt_pk_bf16_f32 v143, v146, v147
	global_store_dwordx4 v2, v[140:143], s[46:47] offset:1024
	s_add_u32 s46, s46, 0x1000
	s_addc_u32 s47, s47, 0
	global_load_dwordx4 v[36:39], v11, s[38:39] offset:192
	global_load_dwordx4 v[40:43], v11, s[48:49] offset:192
	s_waitcnt vmcnt(17)
; #define GAS __attribute__((address_space(1)))
; __device__ __forceinline__ void unpack8(const v4u w, float (&f)[8]) { f[0] = bf_lo(w.x); f[1] = bf_hi(w.x); f[2] = bf_lo(w.y); f[3] = bf_hi(w.y); f[4] = bf_lo(w.z); f[5] = bf_hi(w.z); f[6] = bf_lo(w.w); f[7] = bf_hi(w.w); }
; __device__ __forceinline__ v4u pack8(const float (&f)[8]) { v4u w; w.x = cvt_pk_bf16(f[0], f[1]); w.y = cvt_pk_bf16(f[2], f[3]); w.z = cvt_pk_bf16(f[4], f[5]); w.w = cvt_pk_bf16(f[6], f[7]); return w; }
; __device__ __forceinline__ void mixer_shortconv(const Frame& F, const Args& A, int l, int chunk, const bf16* Z, bf16* MIX) {
;     ...
;     for (int dt = -2; dt < 16; ++dt) {
;         const int t = t0 + dt; const bool valid = (pos0 + t) >= 0;
;         const bf16* zr = Z + (size_t)(row0 + (valid ? t : 0)) * ZC;
;         float xv[8], x[8];
;         unpack8(*(const GAS v4u*)(zr + 1024 + c8), xv);
; #pragma unroll
;         for (int j = 0; j < 8; ++j) x[j] = valid ? xv[j] : 0.f;
;         if (dt >= 0) { float bg[8], o[8]; unpack8(*(const GAS v4u*)(zr + 1536 + c8), bg);
; #pragma unroll
;             for (int j = 0; j < 8; ++j) o[j] = bg[j] * (w0[j] * xm2[j] + w1[j] * xm1[j] + w2[j] * x[j]);
;             *(GAS v4u*)(MIX + (size_t)(row0 + t) * D + 512 + c8) = pack8(o); }
; #pragma unroll
;         for (int j = 0; j < 8; ++j) { xm2[j] = xm1[j]; xm1[j] = x[j]; }
;     }
; template <int W> __device__ __forceinline__ void pool_group(const bf16* zrow  , const bf16* pw  , bf16* orow  , int pos, bool prev_ok) {
;     const float inv = 1.0f / (float)((pos + 1) < W ? (pos + 1) : W);
;     f32x4 acc[8];
; #pragma unroll
;     for (int dt = 0; dt < 8; ++dt) acc[dt] = (f32x4){0.f, 0.f, 0.f, 0.f};
;     v4u cw[4], pv[4], aw[2][8];
; #pragma unroll
;     for (int kk = 0; kk < 4; ++kk) { cw[kk] = *(const GAS v4u*)(zrow + 32 * kk); pv[kk] = prev_ok ? *(const GAS v4u*)(zrow + 32 * kk - (ptrdiff_t)16 * ZC) : (v4u){0u, 0u, 0u, 0u}; }
; #pragma unroll
;     for (int dt = 0; dt < 8; ++dt) aw[0][dt] = *(const GAS v4u*)(pw + (size_t)16 * dt * 128);
	v_lshlrev_b32_e32 v92, 16, v44
	v_and_b32_e32 v93, 0xffff0000, v44
	v_lshlrev_b32_e32 v94, 16, v45
	v_and_b32_e32 v95, 0xffff0000, v45
	v_lshlrev_b32_e32 v96, 16, v46
	v_and_b32_e32 v97, 0xffff0000, v46
	v_lshlrev_b32_e32 v98, 16, v47
	v_and_b32_e32 v99, 0xffff0000, v47
	v_lshlrev_b32_e32 v132, 16, v76
	v_and_b32_e32 v133, 0xffff0000, v76
	v_lshlrev_b32_e32 v134, 16, v77
	v_and_b32_e32 v135, 0xffff0000, v77
	v_lshlrev_b32_e32 v136, 16, v78
	v_and_b32_e32 v137, 0xffff0000, v78
	v_lshlrev_b32_e32 v138, 16, v79
	v_and_b32_e32 v139, 0xffff0000, v79
	v_mul_f32_e32 v140, v100, v124
	v_fmac_f32_e32 v140, v108, v84
	v_fmac_f32_e32 v140, v116, v92
	v_mul_f32_e32 v140, v132, v140
	v_mul_f32_e32 v141, v101, v125
	v_fmac_f32_e32 v141, v109, v85
	v_fmac_f32_e32 v141, v117, v93
	v_mul_f32_e32 v141, v133, v141
	v_mul_f32_e32 v142, v102, v126
	v_fmac_f32_e32 v142, v110, v86
	v_fmac_f32_e32 v142, v118, v94
	v_mul_f32_e32 v142, v134, v142
	v_mul_f32_e32 v143, v103, v127
	v_fmac_f32_e32 v143, v111, v87
	v_fmac_f32_e32 v143, v119, v95
	v_mul_f32_e32 v143, v135, v143
	v_mul_f32_e32 v144, v104, v128
	v_fmac_f32_e32 v144, v112, v88
	v_fmac_f32_e32 v144, v120, v96
	v_mul_f32_e32 v144, v136, v144
	v_mul_f32_e32 v145, v105, v129
	v_fmac_f32_e32 v145, v113, v89
	v_fmac_f32_e32 v145, v121, v97
	v_mul_f32_e32 v145, v137, v145
	v_mul_f32_e32 v146, v106, v130
	v_fmac_f32_e32 v146, v114, v90
	v_fmac_f32_e32 v146, v122, v98
	v_mul_f32_e32 v146, v138, v146
	v_mul_f32_e32 v147, v107, v131
	v_fmac_f32_e32 v147, v115, v91
	v_fmac_f32_e32 v147, v123, v99
	v_mul_f32_e32 v147, v139, v147
	v_cvt_pk_bf16_f32 v140, v140, v141
	v_cvt_pk_bf16_f32 v141, v142, v143
	v_cvt_pk_bf16_f32 v142, v144, v145
	v_cvt_pk_bf16_f32 v143, v146, v147
	global_store_dwordx4 v2, v[140:143], s[46:47] offset:1024
	s_add_u32 s46, s46, 0x1000
	s_addc_u32 s47, s47, 0
	s_waitcnt vmcnt(15)
	v_lshlrev_b32_e32 v124, 16, v48
	v_and_b32_e32 v125, 0xffff0000, v48
	v_lshlrev_b32_e32 v126, 16, v49
	v_and_b32_e32 v127, 0xffff0000, v49
	v_lshlrev_b32_e32 v128, 16, v50
	v_and_b32_e32 v129, 0xffff0000, v50
	v_lshlrev_b32_e32 v130, 16, v51
	v_and_b32_e32 v131, 0xffff0000, v51
	v_lshlrev_b32_e32 v132, 16, v80
	v_and_b32_e32 v133, 0xffff0000, v80
	v_lshlrev_b32_e32 v134, 16, v81
	v_and_b32_e32 v135, 0xffff0000, v81
	v_lshlrev_b32_e32 v136, 16, v82
	v_and_b32_e32 v137, 0xffff0000, v82
	v_lshlrev_b32_e32 v138, 16, v83
	v_and_b32_e32 v139, 0xffff0000, v83
	v_mul_f32_e32 v140, v100, v84
	v_fmac_f32_e32 v140, v108, v92
	v_fmac_f32_e32 v140, v116, v124
	v_mul_f32_e32 v140, v132, v140
	v_mul_f32_e32 v141, v101, v85
	v_fmac_f32_e32 v141, v109, v93
	v_fmac_f32_e32 v141, v117, v125
	v_mul_f32_e32 v141, v133, v141
	v_mul_f32_e32 v142, v102, v86
	v_fmac_f32_e32 v142, v110, v94
	v_fmac_f32_e32 v142, v118, v126
	v_mul_f32_e32 v142, v134, v142
	v_mul_f32_e32 v143, v103, v87
	v_fmac_f32_e32 v143, v111, v95
	v_fmac_f32_e32 v143, v119, v127
	v_mul_f32_e32 v143, v135, v143
	v_mul_f32_e32 v144, v104, v88
	v_fmac_f32_e32 v144, v112, v96
	v_fmac_f32_e32 v144, v120, v128
	v_mul_f32_e32 v144, v136, v144
	v_mul_f32_e32 v145, v105, v89
	v_fmac_f32_e32 v145, v113, v97
	v_fmac_f32_e32 v145, v121, v129
	v_mul_f32_e32 v145, v137, v145
	v_mul_f32_e32 v146, v106, v90
	v_fmac_f32_e32 v146, v114, v98
	v_fmac_f32_e32 v146, v122, v130
	v_mul_f32_e32 v146, v138, v146
	v_mul_f32_e32 v147, v107, v91
	v_fmac_f32_e32 v147, v115, v99
	v_fmac_f32_e32 v147, v123, v131
	v_mul_f32_e32 v147, v139, v147
	v_cvt_pk_bf16_f32 v140, v140, v141
	v_cvt_pk_bf16_f32 v141, v142, v143
	v_cvt_pk_bf16_f32 v142, v144, v145
	v_cvt_pk_bf16_f32 v143, v146, v147
	global_store_dwordx4 v2, v[140:143], s[46:47] offset:1024
	s_add_u32 s46, s46, 0x1000
	s_addc_u32 s47, s47, 0
	s_barrier
	v_lshlrev_b32_e32 v142, 12, v4
	v_lshl_add_u32 v142, v5, 3, v142
	v_or_b32_e32 v10, 0, v5
	v_xor_b32_e32 v10, v4, v10
	v_lshlrev_b32_e32 v10, 4, v10
	v_lshl_add_u32 v143, v4, 8, v10
	v_or_b32_e32 v10, 4, v5
	v_xor_b32_e32 v10, v4, v10
	v_lshlrev_b32_e32 v10, 4, v10
	v_lshl_add_u32 v144, v4, 8, v10
	v_or_b32_e32 v10, 8, v5
	v_xor_b32_e32 v10, v4, v10
	v_lshlrev_b32_e32 v10, 4, v10
	v_lshl_add_u32 v145, v4, 8, v10
	v_or_b32_e32 v10, 12, v5
	v_xor_b32_e32 v10, v4, v10
	v_lshlrev_b32_e32 v10, 4, v10
	v_lshl_add_u32 v146, v4, 8, v10
	s_add_i32 s37, s4, s56
	v_add_u32_e32 v140, s37, v4
	v_add_u32_e32 v140, 1, v140
	s_add_u32 s46, s2, s84
	s_addc_u32 s47, s3, 0
	s_add_u32 s46, s46, 0xc00
	s_addc_u32 s47, s47, 0
	v_min_i32_e32 v139, 2, v140
	v_cvt_f32_i32_e32 v139, v139
	v_div_scale_f32 v1, s[42:43], v139, v139, 1.0
	v_rcp_f32_e32 v2, v1
	s_nop 0
	v_fma_f32 v7, -v1, v2, 1.0
	v_fmac_f32_e32 v2, v7, v2
	v_div_scale_f32 v3, vcc, 1.0, v139, 1.0
	v_mul_f32_e32 v6, v3, v2
	v_fma_f32 v7, -v1, v6, v3
	v_fmac_f32_e32 v6, v7, v2
	v_fma_f32 v1, -v1, v6, v3
	s_nop 1
	v_div_fmas_f32 v1, v1, v2, v6
	v_div_fixup_f32 v138, v1, v139, 1.0
	v_add_u32_e32 v147, 0, v143
	ds_read_b128 v[44:47], v147
	ds_read_b128 v[48:51], v147 offset:4096
	ds_read_b128 v[52:55], v147 offset:8192
	ds_read_b128 v[56:59], v147 offset:12288
	ds_read_b128 v[60:63], v147 offset:16384
	ds_read_b128 v[64:67], v147 offset:20480
	ds_read_b128 v[68:71], v147 offset:24576
	ds_read_b128 v[72:75], v147 offset:28672
	s_waitcnt vmcnt(13)
; #define GAS __attribute__((address_space(1)))
; __device__ __forceinline__ void unpack8(const v4u w, float (&f)[8]) { f[0] = bf_lo(w.x); f[1] = bf_hi(w.x); f[2] = bf_lo(w.y); f[3] = bf_hi(w.y); f[4] = bf_lo(w.z); f[5] = bf_hi(w.z); f[6] = bf_lo(w.w); f[7] = bf_hi(w.w); }
; __device__ __forceinline__ v4u pack8(const float (&f)[8]) { v4u w; w.x = cvt_pk_bf16(f[0], f[1]); w.y = cvt_pk_bf16(f[2], f[3]); w.z = cvt_pk_bf16(f[4], f[5]); w.w = cvt_pk_bf16(f[6], f[7]); return w; }
; template <int SH> __device__ __forceinline__ float row_shr(float v) { return __int_as_float(__builtin_amdgcn_update_dpp(0, __float_as_int(v), 0x110 + SH, 0xf, 0xf, true)); }
; template <int SH> __device__ __forceinline__ float row_shl(float v) { return __int_as_float(__builtin_amdgcn_update_dpp(0, __float_as_int(v), 0x100 + SH, 0xf, 0xf, true)); }
; template <int S> __device__ __forceinline__ void win_step(float (&c)[8], float (&p)[8]) {
; #pragma unroll
;     for (int j = 0; j < 8; ++j) { const float cn = c[j] + row_shr<S>(c[j]) + row_shl<16 - S>(p[j]); p[j] += row_shr<S>(p[j]); c[j] = cn; }
; }
; template <int W> __device__ __forceinline__ void pool_group(const bf16* zrow  , const bf16* pw  , bf16* orow  , int pos, bool prev_ok) {
;     ...
;     for (int kk = 0; kk < 4; ++kk) {
;         if (kk < 3) {
; #pragma unroll
;             for (int dt = 0; dt < 8; ++dt) aw[(kk + 1) & 1][dt] = *(const GAS v4u*)(pw + (size_t)16 * dt * 128 + 32 * (kk + 1)); }
;         float own[8], c[8], p[8];
;         unpack8(cw[kk], own); unpack8(pv[kk], p);
; #pragma unroll
;         for (int j = 0; j < 8; ++j) c[j] = own[j];
;         win_step<1>(c, p);
;         if (W >= 4) win_step<2>(c, p);
;         if (W >= 8) win_step<4>(c, p);
;         if (W >= 16) win_step<8>(c, p);
;         float pl[8];
; #pragma unroll
;         for (int j = 0; j < 8; ++j) pl[j] = c[j] * inv - own[j];
;         const v4u pwk = pack8(pl); const bf16x8 pf = __builtin_bit_cast(bf16x8, pwk);
; #pragma unroll
;         for (int dt = 0; dt < 8; ++dt) acc[dt] = __builtin_amdgcn_mfma_f32_16x16x32_bf16(__builtin_bit_cast(bf16x8, aw[kk & 1][dt]), pf, acc[dt], 0, 0, 0);
	v_lshlrev_b32_e32 v108, 16, v12
	v_and_b32_e32 v109, 0xffff0000, v12
	v_lshlrev_b32_e32 v110, 16, v13
	v_and_b32_e32 v111, 0xffff0000, v13
	v_lshlrev_b32_e32 v112, 16, v14
	v_and_b32_e32 v113, 0xffff0000, v14
	v_lshlrev_b32_e32 v114, 16, v15
	v_and_b32_e32 v115, 0xffff0000, v15
	v_lshlrev_b32_e32 v124, 16, v16
	v_and_b32_e32 v125, 0xffff0000, v16
	v_lshlrev_b32_e32 v126, 16, v17
	v_and_b32_e32 v127, 0xffff0000, v17
	v_lshlrev_b32_e32 v128, 16, v18
	v_and_b32_e32 v129, 0xffff0000, v18
	v_lshlrev_b32_e32 v130, 16, v19
	v_and_b32_e32 v131, 0xffff0000, v19
	v_cndmask_b32_e64 v124, 0, v124, s[40:41]
	v_cndmask_b32_e64 v125, 0, v125, s[40:41]
	v_cndmask_b32_e64 v126, 0, v126, s[40:41]
	v_cndmask_b32_e64 v127, 0, v127, s[40:41]
	v_cndmask_b32_e64 v128, 0, v128, s[40:41]
	v_cndmask_b32_e64 v129, 0, v129, s[40:41]
	v_cndmask_b32_e64 v130, 0, v130, s[40:41]
	v_cndmask_b32_e64 v131, 0, v131, s[40:41]
	global_load_dwordx4 v[12:15], v11, s[38:39] offset:256
	global_load_dwordx4 v[16:19], v11, s[48:49] offset:256
	v_mov_b32_e32 v116, v108
	v_mov_b32_e32 v117, v109
	v_mov_b32_e32 v118, v110
	v_mov_b32_e32 v119, v111
	v_mov_b32_e32 v120, v112
	v_mov_b32_e32 v121, v113
	v_mov_b32_e32 v122, v114
	v_mov_b32_e32 v123, v115
	v_add_f32_dpp v132, v116, v116 row_shr:1 row_mask:0xf bank_mask:0xf bound_ctrl:1
	v_add_f32_dpp v116, v124, v132 row_shl:15 row_mask:0xf bank_mask:0xf bound_ctrl:1
	v_add_f32_dpp v124, v124, v124 row_shr:1 row_mask:0xf bank_mask:0xf bound_ctrl:1
	v_add_f32_dpp v132, v117, v117 row_shr:1 row_mask:0xf bank_mask:0xf bound_ctrl:1
	v_add_f32_dpp v117, v125, v132 row_shl:15 row_mask:0xf bank_mask:0xf bound_ctrl:1
	v_add_f32_dpp v125, v125, v125 row_shr:1 row_mask:0xf bank_mask:0xf bound_ctrl:1
	v_add_f32_dpp v132, v118, v118 row_shr:1 row_mask:0xf bank_mask:0xf bound_ctrl:1
	v_add_f32_dpp v118, v126, v132 row_shl:15 row_mask:0xf bank_mask:0xf bound_ctrl:1
	v_add_f32_dpp v126, v126, v126 row_shr:1 row_mask:0xf bank_mask:0xf bound_ctrl:1
	v_add_f32_dpp v132, v119, v119 row_shr:1 row_mask:0xf bank_mask:0xf bound_ctrl:1
	v_add_f32_dpp v119, v127, v132 row_shl:15 row_mask:0xf bank_mask:0xf bound_ctrl:1
	v_add_f32_dpp v127, v127, v127 row_shr:1 row_mask:0xf bank_mask:0xf bound_ctrl:1
	v_add_f32_dpp v132, v120, v120 row_shr:1 row_mask:0xf bank_mask:0xf bound_ctrl:1
	v_add_f32_dpp v120, v128, v132 row_shl:15 row_mask:0xf bank_mask:0xf bound_ctrl:1
	v_add_f32_dpp v128, v128, v128 row_shr:1 row_mask:0xf bank_mask:0xf bound_ctrl:1
	v_add_f32_dpp v132, v121, v121 row_shr:1 row_mask:0xf bank_mask:0xf bound_ctrl:1
	v_add_f32_dpp v121, v129, v132 row_shl:15 row_mask:0xf bank_mask:0xf bound_ctrl:1
	v_add_f32_dpp v129, v129, v129 row_shr:1 row_mask:0xf bank_mask:0xf bound_ctrl:1
	v_add_f32_dpp v132, v122, v122 row_shr:1 row_mask:0xf bank_mask:0xf bound_ctrl:1
	v_add_f32_dpp v122, v130, v132 row_shl:15 row_mask:0xf bank_mask:0xf bound_ctrl:1
	v_add_f32_dpp v130, v130, v130 row_shr:1 row_mask:0xf bank_mask:0xf bound_ctrl:1
	v_add_f32_dpp v132, v123, v123 row_shr:1 row_mask:0xf bank_mask:0xf bound_ctrl:1
	v_add_f32_dpp v123, v131, v132 row_shl:15 row_mask:0xf bank_mask:0xf bound_ctrl:1
	v_add_f32_dpp v131, v131, v131 row_shr:1 row_mask:0xf bank_mask:0xf bound_ctrl:1
	v_fma_f32 v116, v116, v138, -v108
	v_fma_f32 v117, v117, v138, -v109
	v_fma_f32 v118, v118, v138, -v110
	v_fma_f32 v119, v119, v138, -v111
	v_fma_f32 v120, v120, v138, -v112
	v_fma_f32 v121, v121, v138, -v113
	v_fma_f32 v122, v122, v138, -v114
	v_fma_f32 v123, v123, v138, -v115
	v_cvt_pk_bf16_f32 v134, v116, v117
	v_cvt_pk_bf16_f32 v135, v118, v119
	v_cvt_pk_bf16_f32 v136, v120, v121
	v_cvt_pk_bf16_f32 v137, v122, v123
	s_waitcnt lgkmcnt(0)
	s_nop 0
	v_mfma_f32_16x16x32_bf16 v[76:79], v[44:47], v[134:137], 0
	v_mfma_f32_16x16x32_bf16 v[80:83], v[48:51], v[134:137], 0
	v_mfma_f32_16x16x32_bf16 v[84:87], v[52:55], v[134:137], 0
	v_mfma_f32_16x16x32_bf16 v[88:91], v[56:59], v[134:137], 0
	v_mfma_f32_16x16x32_bf16 v[92:95], v[60:63], v[134:137], 0
	v_mfma_f32_16x16x32_bf16 v[96:99], v[64:67], v[134:137], 0
	v_mfma_f32_16x16x32_bf16 v[100:103], v[68:71], v[134:137], 0
	v_mfma_f32_16x16x32_bf16 v[104:107], v[72:75], v[134:137], 0
	v_add_u32_e32 v147, 0, v144
	ds_read_b128 v[44:47], v147
	ds_read_b128 v[48:51], v147 offset:4096
	ds_read_b128 v[52:55], v147 offset:8192
	ds_read_b128 v[56:59], v147 offset:12288
	ds_read_b128 v[60:63], v147 offset:16384
	ds_read_b128 v[64:67], v147 offset:20480
	ds_read_b128 v[68:71], v147 offset:24576
	ds_read_b128 v[72:75], v147 offset:28672
	s_waitcnt vmcnt(12)
; #define GAS __attribute__((address_space(1)))
; __device__ __forceinline__ void unpack8(const v4u w, float (&f)[8]) { f[0] = bf_lo(w.x); f[1] = bf_hi(w.x); f[2] = bf_lo(w.y); f[3] = bf_hi(w.y); f[4] = bf_lo(w.z); f[5] = bf_hi(w.z); f[6] = bf_lo(w.w); f[7] = bf_hi(w.w); }
; __device__ __forceinline__ v4u pack8(const float (&f)[8]) { v4u w; w.x = cvt_pk_bf16(f[0], f[1]); w.y = cvt_pk_bf16(f[2], f[3]); w.z = cvt_pk_bf16(f[4], f[5]); w.w = cvt_pk_bf16(f[6], f[7]); return w; }
; template <int SH> __device__ __forceinline__ float row_shr(float v) { return __int_as_float(__builtin_amdgcn_update_dpp(0, __float_as_int(v), 0x110 + SH, 0xf, 0xf, true)); }
; template <int SH> __device__ __forceinline__ float row_shl(float v) { return __int_as_float(__builtin_amdgcn_update_dpp(0, __float_as_int(v), 0x100 + SH, 0xf, 0xf, true)); }
; template <int S> __device__ __forceinline__ void win_step(float (&c)[8], float (&p)[8]) {
; #pragma unroll
;     for (int j = 0; j < 8; ++j) { const float cn = c[j] + row_shr<S>(c[j]) + row_shl<16 - S>(p[j]); p[j] += row_shr<S>(p[j]); c[j] = cn; }
; }
; template <int W> __device__ __forceinline__ void pool_group(const bf16* zrow  , const bf16* pw  , bf16* orow  , int pos, bool prev_ok) {
;     ...
;     for (int kk = 0; kk < 4; ++kk) {
;         if (kk < 3) {
; #pragma unroll
;             for (int dt = 0; dt < 8; ++dt) aw[(kk + 1) & 1][dt] = *(const GAS v4u*)(pw + (size_t)16 * dt * 128 + 32 * (kk + 1)); }
;         float own[8], c[8], p[8];
;         unpack8(cw[kk], own); unpack8(pv[kk], p);
; #pragma unroll
;         for (int j = 0; j < 8; ++j) c[j] = own[j];
;         win_step<1>(c, p);
;         if (W >= 4) win_step<2>(c, p);
;         if (W >= 8) win_step<4>(c, p);
;         if (W >= 16) win_step<8>(c, p);
;         float pl[8];
; #pragma unroll
;         for (int j = 0; j < 8; ++j) pl[j] = c[j] * inv - own[j];
;         const v4u pwk = pack8(pl); const bf16x8 pf = __builtin_bit_cast(bf16x8, pwk);
; #pragma unroll
;         for (int dt = 0; dt < 8; ++dt) acc[dt] = __builtin_amdgcn_mfma_f32_16x16x32_bf16(__builtin_bit_cast(bf16x8, aw[kk & 1][dt]), pf, acc[dt], 0, 0, 0);
	v_lshlrev_b32_e32 v108, 16, v20
	v_and_b32_e32 v109, 0xffff0000, v20
	v_lshlrev_b32_e32 v110, 16, v21
	v_and_b32_e32 v111, 0xffff0000, v21
	v_lshlrev_b32_e32 v112, 16, v22
	v_and_b32_e32 v113, 0xffff0000, v22
	v_lshlrev_b32_e32 v114, 16, v23
	v_and_b32_e32 v115, 0xffff0000, v23
	v_lshlrev_b32_e32 v124, 16, v24
	v_and_b32_e32 v125, 0xffff0000, v24
	v_lshlrev_b32_e32 v126, 16, v25
	v_and_b32_e32 v127, 0xffff0000, v25
	v_lshlrev_b32_e32 v128, 16, v26
	v_and_b32_e32 v129, 0xffff0000, v26
	v_lshlrev_b32_e32 v130, 16, v27
	v_and_b32_e32 v131, 0xffff0000, v27
	v_cndmask_b32_e64 v124, 0, v124, s[40:41]
	v_cndmask_b32_e64 v125, 0, v125, s[40:41]
	v_cndmask_b32_e64 v126, 0, v126, s[40:41]
	v_cndmask_b32_e64 v127, 0, v127, s[40:41]
	v_cndmask_b32_e64 v128, 0, v128, s[40:41]
	v_cndmask_b32_e64 v129, 0, v129, s[40:41]
	v_cndmask_b32_e64 v130, 0, v130, s[40:41]
	v_cndmask_b32_e64 v131, 0, v131, s[40:41]
	global_load_dwordx4 v[20:23], v11, s[38:39] offset:320
	global_load_dwordx4 v[24:27], v11, s[48:49] offset:320
	v_mov_b32_e32 v116, v108
	v_mov_b32_e32 v117, v109
	v_mov_b32_e32 v118, v110
	v_mov_b32_e32 v119, v111
	v_mov_b32_e32 v120, v112
	v_mov_b32_e32 v121, v113
	v_mov_b32_e32 v122, v114
	v_mov_b32_e32 v123, v115
	v_add_f32_dpp v132, v116, v116 row_shr:1 row_mask:0xf bank_mask:0xf bound_ctrl:1
	v_add_f32_dpp v116, v124, v132 row_shl:15 row_mask:0xf bank_mask:0xf bound_ctrl:1
	v_add_f32_dpp v124, v124, v124 row_shr:1 row_mask:0xf bank_mask:0xf bound_ctrl:1
	v_add_f32_dpp v132, v117, v117 row_shr:1 row_mask:0xf bank_mask:0xf bound_ctrl:1
	v_add_f32_dpp v117, v125, v132 row_shl:15 row_mask:0xf bank_mask:0xf bound_ctrl:1
	v_add_f32_dpp v125, v125, v125 row_shr:1 row_mask:0xf bank_mask:0xf bound_ctrl:1
	v_add_f32_dpp v132, v118, v118 row_shr:1 row_mask:0xf bank_mask:0xf bound_ctrl:1
	v_add_f32_dpp v118, v126, v132 row_shl:15 row_mask:0xf bank_mask:0xf bound_ctrl:1
	v_add_f32_dpp v126, v126, v126 row_shr:1 row_mask:0xf bank_mask:0xf bound_ctrl:1
	v_add_f32_dpp v132, v119, v119 row_shr:1 row_mask:0xf bank_mask:0xf bound_ctrl:1
	v_add_f32_dpp v119, v127, v132 row_shl:15 row_mask:0xf bank_mask:0xf bound_ctrl:1
	v_add_f32_dpp v127, v127, v127 row_shr:1 row_mask:0xf bank_mask:0xf bound_ctrl:1
	v_add_f32_dpp v132, v120, v120 row_shr:1 row_mask:0xf bank_mask:0xf bound_ctrl:1
	v_add_f32_dpp v120, v128, v132 row_shl:15 row_mask:0xf bank_mask:0xf bound_ctrl:1
	v_add_f32_dpp v128, v128, v128 row_shr:1 row_mask:0xf bank_mask:0xf bound_ctrl:1
	v_add_f32_dpp v132, v121, v121 row_shr:1 row_mask:0xf bank_mask:0xf bound_ctrl:1
	v_add_f32_dpp v121, v129, v132 row_shl:15 row_mask:0xf bank_mask:0xf bound_ctrl:1
	v_add_f32_dpp v129, v129, v129 row_shr:1 row_mask:0xf bank_mask:0xf bound_ctrl:1
	v_add_f32_dpp v132, v122, v122 row_shr:1 row_mask:0xf bank_mask:0xf bound_ctrl:1
	v_add_f32_dpp v122, v130, v132 row_shl:15 row_mask:0xf bank_mask:0xf bound_ctrl:1
	v_add_f32_dpp v130, v130, v130 row_shr:1 row_mask:0xf bank_mask:0xf bound_ctrl:1
	v_add_f32_dpp v132, v123, v123 row_shr:1 row_mask:0xf bank_mask:0xf bound_ctrl:1
	v_add_f32_dpp v123, v131, v132 row_shl:15 row_mask:0xf bank_mask:0xf bound_ctrl:1
	v_add_f32_dpp v131, v131, v131 row_shr:1 row_mask:0xf bank_mask:0xf bound_ctrl:1
	v_fma_f32 v116, v116, v138, -v108
	v_fma_f32 v117, v117, v138, -v109
	v_fma_f32 v118, v118, v138, -v110
	v_fma_f32 v119, v119, v138, -v111
	v_fma_f32 v120, v120, v138, -v112
	v_fma_f32 v121, v121, v138, -v113
	v_fma_f32 v122, v122, v138, -v114
	v_fma_f32 v123, v123, v138, -v115
	v_cvt_pk_bf16_f32 v134, v116, v117
	v_cvt_pk_bf16_f32 v135, v118, v119
	v_cvt_pk_bf16_f32 v136, v120, v121
	v_cvt_pk_bf16_f32 v137, v122, v123
	s_waitcnt lgkmcnt(0)
	s_nop 0
	v_mfma_f32_16x16x32_bf16 v[76:79], v[44:47], v[134:137], v[76:79]
	v_mfma_f32_16x16x32_bf16 v[80:83], v[48:51], v[134:137], v[80:83]
	v_mfma_f32_16x16x32_bf16 v[84:87], v[52:55], v[134:137], v[84:87]
	v_mfma_f32_16x16x32_bf16 v[88:91], v[56:59], v[134:137], v[88:91]
	v_mfma_f32_16x16x32_bf16 v[92:95], v[60:63], v[134:137], v[92:95]
	v_mfma_f32_16x16x32_bf16 v[96:99], v[64:67], v[134:137], v[96:99]
	v_mfma_f32_16x16x32_bf16 v[100:103], v[68:71], v[134:137], v[100:103]
	v_mfma_f32_16x16x32_bf16 v[104:107], v[72:75], v[134:137], v[104:107]
	v_add_u32_e32 v147, 0, v145
	ds_read_b128 v[44:47], v147
	ds_read_b128 v[48:51], v147 offset:4096
	ds_read_b128 v[52:55], v147 offset:8192
	ds_read_b128 v[56:59], v147 offset:12288
	ds_read_b128 v[60:63], v147 offset:16384
	ds_read_b128 v[64:67], v147 offset:20480
	ds_read_b128 v[68:71], v147 offset:24576
	ds_read_b128 v[72:75], v147 offset:28672
	s_waitcnt vmcnt(10)
; #define GAS __attribute__((address_space(1)))
; __device__ __forceinline__ void unpack8(const v4u w, float (&f)[8]) { f[0] = bf_lo(w.x); f[1] = bf_hi(w.x); f[2] = bf_lo(w.y); f[3] = bf_hi(w.y); f[4] = bf_lo(w.z); f[5] = bf_hi(w.z); f[6] = bf_lo(w.w); f[7] = bf_hi(w.w); }
; __device__ __forceinline__ v4u pack8(const float (&f)[8]) { v4u w; w.x = cvt_pk_bf16(f[0], f[1]); w.y = cvt_pk_bf16(f[2], f[3]); w.z = cvt_pk_bf16(f[4], f[5]); w.w = cvt_pk_bf16(f[6], f[7]); return w; }
; template <int SH> __device__ __forceinline__ float row_shr(float v) { return __int_as_float(__builtin_amdgcn_update_dpp(0, __float_as_int(v), 0x110 + SH, 0xf, 0xf, true)); }
; template <int SH> __device__ __forceinline__ float row_shl(float v) { return __int_as_float(__builtin_amdgcn_update_dpp(0, __float_as_int(v), 0x100 + SH, 0xf, 0xf, true)); }
; template <int S> __device__ __forceinline__ void win_step(float (&c)[8], float (&p)[8]) {
; #pragma unroll
;     for (int j = 0; j < 8; ++j) { const float cn = c[j] + row_shr<S>(c[j]) + row_shl<16 - S>(p[j]); p[j] += row_shr<S>(p[j]); c[j] = cn; }
; }
; template <int W> __device__ __forceinline__ void pool_group(const bf16* zrow  , const bf16* pw  , bf16* orow  , int pos, bool prev_ok) {
;     ...
;     for (int kk = 0; kk < 4; ++kk) {
;         if (kk < 3) {
; #pragma unroll
;             for (int dt = 0; dt < 8; ++dt) aw[(kk + 1) & 1][dt] = *(const GAS v4u*)(pw + (size_t)16 * dt * 128 + 32 * (kk + 1)); }
;         float own[8], c[8], p[8];
;         unpack8(cw[kk], own); unpack8(pv[kk], p);
; #pragma unroll
;         for (int j = 0; j < 8; ++j) c[j] = own[j];
;         win_step<1>(c, p);
;         if (W >= 4) win_step<2>(c, p);
;         if (W >= 8) win_step<4>(c, p);
;         if (W >= 16) win_step<8>(c, p);
;         float pl[8];
; #pragma unroll
;         for (int j = 0; j < 8; ++j) pl[j] = c[j] * inv - own[j];
;         const v4u pwk = pack8(pl); const bf16x8 pf = __builtin_bit_cast(bf16x8, pwk);
; #pragma unroll
;         for (int dt = 0; dt < 8; ++dt) acc[dt] = __builtin_amdgcn_mfma_f32_16x16x32_bf16(__builtin_bit_cast(bf16x8, aw[kk & 1][dt]), pf, acc[dt], 0, 0, 0);
	v_lshlrev_b32_e32 v108, 16, v28
	v_and_b32_e32 v109, 0xffff0000, v28
	v_lshlrev_b32_e32 v110, 16, v29
	v_and_b32_e32 v111, 0xffff0000, v29
	v_lshlrev_b32_e32 v112, 16, v30
	v_and_b32_e32 v113, 0xffff0000, v30
	v_lshlrev_b32_e32 v114, 16, v31
	v_and_b32_e32 v115, 0xffff0000, v31
	v_lshlrev_b32_e32 v124, 16, v32
	v_and_b32_e32 v125, 0xffff0000, v32
	v_lshlrev_b32_e32 v126, 16, v33
	v_and_b32_e32 v127, 0xffff0000, v33
	v_lshlrev_b32_e32 v128, 16, v34
	v_and_b32_e32 v129, 0xffff0000, v34
	v_lshlrev_b32_e32 v130, 16, v35
	v_and_b32_e32 v131, 0xffff0000, v35
	v_cndmask_b32_e64 v124, 0, v124, s[40:41]
	v_cndmask_b32_e64 v125, 0, v125, s[40:41]
	v_cndmask_b32_e64 v126, 0, v126, s[40:41]
	v_cndmask_b32_e64 v127, 0, v127, s[40:41]
	v_cndmask_b32_e64 v128, 0, v128, s[40:41]
	v_cndmask_b32_e64 v129, 0, v129, s[40:41]
	v_cndmask_b32_e64 v130, 0, v130, s[40:41]
	v_cndmask_b32_e64 v131, 0, v131, s[40:41]
	global_load_dwordx4 v[28:31], v11, s[38:39] offset:384
	global_load_dwordx4 v[32:35], v11, s[48:49] offset:384
	v_mov_b32_e32 v116, v108
	v_mov_b32_e32 v117, v109
	v_mov_b32_e32 v118, v110
	v_mov_b32_e32 v119, v111
	v_mov_b32_e32 v120, v112
	v_mov_b32_e32 v121, v113
	v_mov_b32_e32 v122, v114
	v_mov_b32_e32 v123, v115
	v_add_f32_dpp v132, v116, v116 row_shr:1 row_mask:0xf bank_mask:0xf bound_ctrl:1
	v_add_f32_dpp v116, v124, v132 row_shl:15 row_mask:0xf bank_mask:0xf bound_ctrl:1
	v_add_f32_dpp v124, v124, v124 row_shr:1 row_mask:0xf bank_mask:0xf bound_ctrl:1
	v_add_f32_dpp v132, v117, v117 row_shr:1 row_mask:0xf bank_mask:0xf bound_ctrl:1
	v_add_f32_dpp v117, v125, v132 row_shl:15 row_mask:0xf bank_mask:0xf bound_ctrl:1
	v_add_f32_dpp v125, v125, v125 row_shr:1 row_mask:0xf bank_mask:0xf bound_ctrl:1
	v_add_f32_dpp v132, v118, v118 row_shr:1 row_mask:0xf bank_mask:0xf bound_ctrl:1
	v_add_f32_dpp v118, v126, v132 row_shl:15 row_mask:0xf bank_mask:0xf bound_ctrl:1
	v_add_f32_dpp v126, v126, v126 row_shr:1 row_mask:0xf bank_mask:0xf bound_ctrl:1
	v_add_f32_dpp v132, v119, v119 row_shr:1 row_mask:0xf bank_mask:0xf bound_ctrl:1
	v_add_f32_dpp v119, v127, v132 row_shl:15 row_mask:0xf bank_mask:0xf bound_ctrl:1
	v_add_f32_dpp v127, v127, v127 row_shr:1 row_mask:0xf bank_mask:0xf bound_ctrl:1
	v_add_f32_dpp v132, v120, v120 row_shr:1 row_mask:0xf bank_mask:0xf bound_ctrl:1
	v_add_f32_dpp v120, v128, v132 row_shl:15 row_mask:0xf bank_mask:0xf bound_ctrl:1
	v_add_f32_dpp v128, v128, v128 row_shr:1 row_mask:0xf bank_mask:0xf bound_ctrl:1
	v_add_f32_dpp v132, v121, v121 row_shr:1 row_mask:0xf bank_mask:0xf bound_ctrl:1
	v_add_f32_dpp v121, v129, v132 row_shl:15 row_mask:0xf bank_mask:0xf bound_ctrl:1
	v_add_f32_dpp v129, v129, v129 row_shr:1 row_mask:0xf bank_mask:0xf bound_ctrl:1
	v_add_f32_dpp v132, v122, v122 row_shr:1 row_mask:0xf bank_mask:0xf bound_ctrl:1
	v_add_f32_dpp v122, v130, v132 row_shl:15 row_mask:0xf bank_mask:0xf bound_ctrl:1
	v_add_f32_dpp v130, v130, v130 row_shr:1 row_mask:0xf bank_mask:0xf bound_ctrl:1
	v_add_f32_dpp v132, v123, v123 row_shr:1 row_mask:0xf bank_mask:0xf bound_ctrl:1
	v_add_f32_dpp v123, v131, v132 row_shl:15 row_mask:0xf bank_mask:0xf bound_ctrl:1
	v_add_f32_dpp v131, v131, v131 row_shr:1 row_mask:0xf bank_mask:0xf bound_ctrl:1
	v_fma_f32 v116, v116, v138, -v108
	v_fma_f32 v117, v117, v138, -v109
	v_fma_f32 v118, v118, v138, -v110
	v_fma_f32 v119, v119, v138, -v111
	v_fma_f32 v120, v120, v138, -v112
	v_fma_f32 v121, v121, v138, -v113
	v_fma_f32 v122, v122, v138, -v114
	v_fma_f32 v123, v123, v138, -v115
	v_cvt_pk_bf16_f32 v134, v116, v117
	v_cvt_pk_bf16_f32 v135, v118, v119
	v_cvt_pk_bf16_f32 v136, v120, v121
	v_cvt_pk_bf16_f32 v137, v122, v123
	s_waitcnt lgkmcnt(0)
	s_nop 0
	v_mfma_f32_16x16x32_bf16 v[76:79], v[44:47], v[134:137], v[76:79]
	v_mfma_f32_16x16x32_bf16 v[80:83], v[48:51], v[134:137], v[80:83]
	v_mfma_f32_16x16x32_bf16 v[84:87], v[52:55], v[134:137], v[84:87]
	v_mfma_f32_16x16x32_bf16 v[88:91], v[56:59], v[134:137], v[88:91]
	v_mfma_f32_16x16x32_bf16 v[92:95], v[60:63], v[134:137], v[92:95]
	v_mfma_f32_16x16x32_bf16 v[96:99], v[64:67], v[134:137], v[96:99]
	v_mfma_f32_16x16x32_bf16 v[100:103], v[68:71], v[134:137], v[100:103]
	v_mfma_f32_16x16x32_bf16 v[104:107], v[72:75], v[134:137], v[104:107]
	v_add_u32_e32 v147, 0, v146
	ds_read_b128 v[44:47], v147
	ds_read_b128 v[48:51], v147 offset:4096
	ds_read_b128 v[52:55], v147 offset:8192
	ds_read_b128 v[56:59], v147 offset:12288
	ds_read_b128 v[60:63], v147 offset:16384
	ds_read_b128 v[64:67], v147 offset:20480
	ds_read_b128 v[68:71], v147 offset:24576
	ds_read_b128 v[72:75], v147 offset:28672
	s_waitcnt vmcnt(8)
; __device__ __forceinline__ unsigned cvt_pk_bf16(float lo, float hi) { return __builtin_bit_cast(unsigned, __builtin_convertvector((f32x2_t){lo, hi}, bf16x2_t)); }
; #define GAS __attribute__((address_space(1)))
; __device__ __forceinline__ void unpack8(const v4u w, float (&f)[8]) { f[0] = bf_lo(w.x); f[1] = bf_hi(w.x); f[2] = bf_lo(w.y); f[3] = bf_hi(w.y); f[4] = bf_lo(w.z); f[5] = bf_hi(w.z); f[6] = bf_lo(w.w); f[7] = bf_hi(w.w); }
; __device__ __forceinline__ v4u pack8(const float (&f)[8]) { v4u w; w.x = cvt_pk_bf16(f[0], f[1]); w.y = cvt_pk_bf16(f[2], f[3]); w.z = cvt_pk_bf16(f[4], f[5]); w.w = cvt_pk_bf16(f[6], f[7]); return w; }
; template <int W> __device__ __forceinline__ void pool_group(const bf16* zrow  , const bf16* pw  , bf16* orow  , int pos, bool prev_ok) {
;     const float inv = 1.0f / (float)((pos + 1) < W ? (pos + 1) : W);
;     ...
;     for (int kk = 0; kk < 4; ++kk) {
;         if (kk < 3) {
; #pragma unroll
;             for (int dt = 0; dt < 8; ++dt) aw[(kk + 1) & 1][dt] = *(const GAS v4u*)(pw + (size_t)16 * dt * 128 + 32 * (kk + 1)); }
;         float own[8], c[8], p[8];
;         unpack8(cw[kk], own); unpack8(pv[kk], p);
; #pragma unroll
;         for (int j = 0; j < 8; ++j) c[j] = own[j];
;         win_step<1>(c, p);
;         if (W >= 4) win_step<2>(c, p);
;         if (W >= 8) win_step<4>(c, p);
;         if (W >= 16) win_step<8>(c, p);
;         float pl[8];
; #pragma unroll
;         for (int j = 0; j < 8; ++j) pl[j] = c[j] * inv - own[j];
;         const v4u pwk = pack8(pl); const bf16x8 pf = __builtin_bit_cast(bf16x8, pwk);
; #pragma unroll
;         for (int dt = 0; dt < 8; ++dt) acc[dt] = __builtin_amdgcn_mfma_f32_16x16x32_bf16(__builtin_bit_cast(bf16x8, aw[kk & 1][dt]), pf, acc[dt], 0, 0, 0);
;     }
; #pragma unroll
;     for (int dt = 0; dt < 8; ++dt) { v2u w; w.x = cvt_pk_bf16(acc[dt][0], acc[dt][1]); w.y = cvt_pk_bf16(acc[dt][2], acc[dt][3]); *(GAS v2u*)(orow + 16 * dt) = w; }
	v_lshlrev_b32_e32 v108, 16, v36
	v_and_b32_e32 v109, 0xffff0000, v36
	v_lshlrev_b32_e32 v110, 16, v37
	v_and_b32_e32 v111, 0xffff0000, v37
	v_lshlrev_b32_e32 v112, 16, v38
	v_and_b32_e32 v113, 0xffff0000, v38
	v_lshlrev_b32_e32 v114, 16, v39
	v_and_b32_e32 v115, 0xffff0000, v39
	v_lshlrev_b32_e32 v124, 16, v40
	v_and_b32_e32 v125, 0xffff0000, v40
	v_lshlrev_b32_e32 v126, 16, v41
	v_and_b32_e32 v127, 0xffff0000, v41
	v_lshlrev_b32_e32 v128, 16, v42
	v_and_b32_e32 v129, 0xffff0000, v42
	v_lshlrev_b32_e32 v130, 16, v43
	v_and_b32_e32 v131, 0xffff0000, v43
	v_cndmask_b32_e64 v124, 0, v124, s[40:41]
	v_cndmask_b32_e64 v125, 0, v125, s[40:41]
	v_cndmask_b32_e64 v126, 0, v126, s[40:41]
	v_cndmask_b32_e64 v127, 0, v127, s[40:41]
	v_cndmask_b32_e64 v128, 0, v128, s[40:41]
	v_cndmask_b32_e64 v129, 0, v129, s[40:41]
	v_cndmask_b32_e64 v130, 0, v130, s[40:41]
	v_cndmask_b32_e64 v131, 0, v131, s[40:41]
	global_load_dwordx4 v[36:39], v11, s[38:39] offset:448
	global_load_dwordx4 v[40:43], v11, s[48:49] offset:448
	v_mov_b32_e32 v116, v108
	v_mov_b32_e32 v117, v109
	v_mov_b32_e32 v118, v110
	v_mov_b32_e32 v119, v111
	v_mov_b32_e32 v120, v112
	v_mov_b32_e32 v121, v113
	v_mov_b32_e32 v122, v114
	v_mov_b32_e32 v123, v115
	v_add_f32_dpp v132, v116, v116 row_shr:1 row_mask:0xf bank_mask:0xf bound_ctrl:1
	v_add_f32_dpp v116, v124, v132 row_shl:15 row_mask:0xf bank_mask:0xf bound_ctrl:1
	v_add_f32_dpp v124, v124, v124 row_shr:1 row_mask:0xf bank_mask:0xf bound_ctrl:1
	v_add_f32_dpp v132, v117, v117 row_shr:1 row_mask:0xf bank_mask:0xf bound_ctrl:1
	v_add_f32_dpp v117, v125, v132 row_shl:15 row_mask:0xf bank_mask:0xf bound_ctrl:1
	v_add_f32_dpp v125, v125, v125 row_shr:1 row_mask:0xf bank_mask:0xf bound_ctrl:1
	v_add_f32_dpp v132, v118, v118 row_shr:1 row_mask:0xf bank_mask:0xf bound_ctrl:1
	v_add_f32_dpp v118, v126, v132 row_shl:15 row_mask:0xf bank_mask:0xf bound_ctrl:1
	v_add_f32_dpp v126, v126, v126 row_shr:1 row_mask:0xf bank_mask:0xf bound_ctrl:1
	v_add_f32_dpp v132, v119, v119 row_shr:1 row_mask:0xf bank_mask:0xf bound_ctrl:1
	v_add_f32_dpp v119, v127, v132 row_shl:15 row_mask:0xf bank_mask:0xf bound_ctrl:1
	v_add_f32_dpp v127, v127, v127 row_shr:1 row_mask:0xf bank_mask:0xf bound_ctrl:1
	v_add_f32_dpp v132, v120, v120 row_shr:1 row_mask:0xf bank_mask:0xf bound_ctrl:1
	v_add_f32_dpp v120, v128, v132 row_shl:15 row_mask:0xf bank_mask:0xf bound_ctrl:1
	v_add_f32_dpp v128, v128, v128 row_shr:1 row_mask:0xf bank_mask:0xf bound_ctrl:1
	v_add_f32_dpp v132, v121, v121 row_shr:1 row_mask:0xf bank_mask:0xf bound_ctrl:1
	v_add_f32_dpp v121, v129, v132 row_shl:15 row_mask:0xf bank_mask:0xf bound_ctrl:1
	v_add_f32_dpp v129, v129, v129 row_shr:1 row_mask:0xf bank_mask:0xf bound_ctrl:1
	v_add_f32_dpp v132, v122, v122 row_shr:1 row_mask:0xf bank_mask:0xf bound_ctrl:1
	v_add_f32_dpp v122, v130, v132 row_shl:15 row_mask:0xf bank_mask:0xf bound_ctrl:1
	v_add_f32_dpp v130, v130, v130 row_shr:1 row_mask:0xf bank_mask:0xf bound_ctrl:1
	v_add_f32_dpp v132, v123, v123 row_shr:1 row_mask:0xf bank_mask:0xf bound_ctrl:1
	v_add_f32_dpp v123, v131, v132 row_shl:15 row_mask:0xf bank_mask:0xf bound_ctrl:1
	v_add_f32_dpp v131, v131, v131 row_shr:1 row_mask:0xf bank_mask:0xf bound_ctrl:1
	v_fma_f32 v116, v116, v138, -v108
	v_fma_f32 v117, v117, v138, -v109
	v_fma_f32 v118, v118, v138, -v110
	v_fma_f32 v119, v119, v138, -v111
	v_fma_f32 v120, v120, v138, -v112
	v_fma_f32 v121, v121, v138, -v113
	v_fma_f32 v122, v122, v138, -v114
	v_fma_f32 v123, v123, v138, -v115
	v_cvt_pk_bf16_f32 v134, v116, v117
	v_cvt_pk_bf16_f32 v135, v118, v119
	v_cvt_pk_bf16_f32 v136, v120, v121
	v_cvt_pk_bf16_f32 v137, v122, v123
	s_waitcnt lgkmcnt(0)
	s_nop 0
	v_mfma_f32_16x16x32_bf16 v[76:79], v[44:47], v[134:137], v[76:79]
	v_mfma_f32_16x16x32_bf16 v[80:83], v[48:51], v[134:137], v[80:83]
	v_mfma_f32_16x16x32_bf16 v[84:87], v[52:55], v[134:137], v[84:87]
	v_mfma_f32_16x16x32_bf16 v[88:91], v[56:59], v[134:137], v[88:91]
	v_mfma_f32_16x16x32_bf16 v[92:95], v[60:63], v[134:137], v[92:95]
	v_mfma_f32_16x16x32_bf16 v[96:99], v[64:67], v[134:137], v[96:99]
	v_mfma_f32_16x16x32_bf16 v[100:103], v[68:71], v[134:137], v[100:103]
	v_mfma_f32_16x16x32_bf16 v[104:107], v[72:75], v[134:137], v[104:107]
	s_nop 7
	s_nop 1
	v_cvt_pk_bf16_f32 v132, v76, v77
	v_cvt_pk_bf16_f32 v133, v78, v79
	global_store_dwordx2 v142, v[132:133], s[46:47] offset:0
	s_nop 0
	v_cvt_pk_bf16_f32 v132, v80, v81
	v_cvt_pk_bf16_f32 v133, v82, v83
	global_store_dwordx2 v142, v[132:133], s[46:47] offset:32
	s_nop 0
	v_cvt_pk_bf16_f32 v132, v84, v85
	v_cvt_pk_bf16_f32 v133, v86, v87
	global_store_dwordx2 v142, v[132:133], s[46:47] offset:64
	s_nop 0
	v_cvt_pk_bf16_f32 v132, v88, v89
	v_cvt_pk_bf16_f32 v133, v90, v91
	global_store_dwordx2 v142, v[132:133], s[46:47] offset:96
	s_nop 0
	v_cvt_pk_bf16_f32 v132, v92, v93
	v_cvt_pk_bf16_f32 v133, v94, v95
	global_store_dwordx2 v142, v[132:133], s[46:47] offset:128
	s_nop 0
	v_cvt_pk_bf16_f32 v132, v96, v97
	v_cvt_pk_bf16_f32 v133, v98, v99
	global_store_dwordx2 v142, v[132:133], s[46:47] offset:160
	s_nop 0
	v_cvt_pk_bf16_f32 v132, v100, v101
	v_cvt_pk_bf16_f32 v133, v102, v103
	global_store_dwordx2 v142, v[132:133], s[46:47] offset:192
	s_nop 0
	v_cvt_pk_bf16_f32 v132, v104, v105
	v_cvt_pk_bf16_f32 v133, v106, v107
	global_store_dwordx2 v142, v[132:133], s[46:47] offset:224
	s_nop 0
	v_min_i32_e32 v139, 4, v140
	v_cvt_f32_i32_e32 v139, v139
	v_div_scale_f32 v1, s[42:43], v139, v139, 1.0
	v_rcp_f32_e32 v2, v1
	s_nop 0
	v_fma_f32 v7, -v1, v2, 1.0
	v_fmac_f32_e32 v2, v7, v2
	v_div_scale_f32 v3, vcc, 1.0, v139, 1.0
	v_mul_f32_e32 v6, v3, v2
	v_fma_f32 v7, -v1, v6, v3
	v_fmac_f32_e32 v6, v7, v2
	v_fma_f32 v1, -v1, v6, v3
	s_nop 1
	v_div_fmas_f32 v1, v1, v2, v6
	v_div_fixup_f32 v138, v1, v139, 1.0
	v_add_u32_e32 v147, 32768, v143
	ds_read_b128 v[44:47], v147
	ds_read_b128 v[48:51], v147 offset:4096
	ds_read_b128 v[52:55], v147 offset:8192
	ds_read_b128 v[56:59], v147 offset:12288
	ds_read_b128 v[60:63], v147 offset:16384
	ds_read_b128 v[64:67], v147 offset:20480
	ds_read_b128 v[68:71], v147 offset:24576
	ds_read_b128 v[72:75], v147 offset:28672
	s_waitcnt vmcnt(14)
; #define GAS __attribute__((address_space(1)))
; __device__ __forceinline__ void unpack8(const v4u w, float (&f)[8]) { f[0] = bf_lo(w.x); f[1] = bf_hi(w.x); f[2] = bf_lo(w.y); f[3] = bf_hi(w.y); f[4] = bf_lo(w.z); f[5] = bf_hi(w.z); f[6] = bf_lo(w.w); f[7] = bf_hi(w.w); }
; __device__ __forceinline__ v4u pack8(const float (&f)[8]) { v4u w; w.x = cvt_pk_bf16(f[0], f[1]); w.y = cvt_pk_bf16(f[2], f[3]); w.z = cvt_pk_bf16(f[4], f[5]); w.w = cvt_pk_bf16(f[6], f[7]); return w; }
; template <int SH> __device__ __forceinline__ float row_shr(float v) { return __int_as_float(__builtin_amdgcn_update_dpp(0, __float_as_int(v), 0x110 + SH, 0xf, 0xf, true)); }
; template <int SH> __device__ __forceinline__ float row_shl(float v) { return __int_as_float(__builtin_amdgcn_update_dpp(0, __float_as_int(v), 0x100 + SH, 0xf, 0xf, true)); }
; template <int S> __device__ __forceinline__ void win_step(float (&c)[8], float (&p)[8]) {
; #pragma unroll
;     for (int j = 0; j < 8; ++j) { const float cn = c[j] + row_shr<S>(c[j]) + row_shl<16 - S>(p[j]); p[j] += row_shr<S>(p[j]); c[j] = cn; }
; }
; template <int W> __device__ __forceinline__ void pool_group(const bf16* zrow  , const bf16* pw  , bf16* orow  , int pos, bool prev_ok) {
;     ...
;     for (int kk = 0; kk < 4; ++kk) {
;         if (kk < 3) {
; #pragma unroll
;             for (int dt = 0; dt < 8; ++dt) aw[(kk + 1) & 1][dt] = *(const GAS v4u*)(pw + (size_t)16 * dt * 128 + 32 * (kk + 1)); }
;         float own[8], c[8], p[8];
;         unpack8(cw[kk], own); unpack8(pv[kk], p);
; #pragma unroll
;         for (int j = 0; j < 8; ++j) c[j] = own[j];
;         win_step<1>(c, p);
;         if (W >= 4) win_step<2>(c, p);
;         if (W >= 8) win_step<4>(c, p);
;         if (W >= 16) win_step<8>(c, p);
;         float pl[8];
; #pragma unroll
;         for (int j = 0; j < 8; ++j) pl[j] = c[j] * inv - own[j];
;         const v4u pwk = pack8(pl); const bf16x8 pf = __builtin_bit_cast(bf16x8, pwk);
; #pragma unroll
;         for (int dt = 0; dt < 8; ++dt) acc[dt] = __builtin_amdgcn_mfma_f32_16x16x32_bf16(__builtin_bit_cast(bf16x8, aw[kk & 1][dt]), pf, acc[dt], 0, 0, 0);
	v_lshlrev_b32_e32 v108, 16, v12
	v_and_b32_e32 v109, 0xffff0000, v12
	v_lshlrev_b32_e32 v110, 16, v13
	v_and_b32_e32 v111, 0xffff0000, v13
	v_lshlrev_b32_e32 v112, 16, v14
	v_and_b32_e32 v113, 0xffff0000, v14
	v_lshlrev_b32_e32 v114, 16, v15
	v_and_b32_e32 v115, 0xffff0000, v15
	v_lshlrev_b32_e32 v124, 16, v16
	v_and_b32_e32 v125, 0xffff0000, v16
	v_lshlrev_b32_e32 v126, 16, v17
	v_and_b32_e32 v127, 0xffff0000, v17
	v_lshlrev_b32_e32 v128, 16, v18
	v_and_b32_e32 v129, 0xffff0000, v18
	v_lshlrev_b32_e32 v130, 16, v19
	v_and_b32_e32 v131, 0xffff0000, v19
	v_cndmask_b32_e64 v124, 0, v124, s[40:41]
	v_cndmask_b32_e64 v125, 0, v125, s[40:41]
	v_cndmask_b32_e64 v126, 0, v126, s[40:41]
	v_cndmask_b32_e64 v127, 0, v127, s[40:41]
	v_cndmask_b32_e64 v128, 0, v128, s[40:41]
	v_cndmask_b32_e64 v129, 0, v129, s[40:41]
	v_cndmask_b32_e64 v130, 0, v130, s[40:41]
	v_cndmask_b32_e64 v131, 0, v131, s[40:41]
	global_load_dwordx4 v[12:15], v11, s[38:39] offset:512
	global_load_dwordx4 v[16:19], v11, s[48:49] offset:512
	v_mov_b32_e32 v116, v108
	v_mov_b32_e32 v117, v109
	v_mov_b32_e32 v118, v110
	v_mov_b32_e32 v119, v111
	v_mov_b32_e32 v120, v112
	v_mov_b32_e32 v121, v113
	v_mov_b32_e32 v122, v114
	v_mov_b32_e32 v123, v115
	v_add_f32_dpp v132, v116, v116 row_shr:1 row_mask:0xf bank_mask:0xf bound_ctrl:1
	v_add_f32_dpp v116, v124, v132 row_shl:15 row_mask:0xf bank_mask:0xf bound_ctrl:1
	v_add_f32_dpp v124, v124, v124 row_shr:1 row_mask:0xf bank_mask:0xf bound_ctrl:1
	v_add_f32_dpp v132, v117, v117 row_shr:1 row_mask:0xf bank_mask:0xf bound_ctrl:1
	v_add_f32_dpp v117, v125, v132 row_shl:15 row_mask:0xf bank_mask:0xf bound_ctrl:1
	v_add_f32_dpp v125, v125, v125 row_shr:1 row_mask:0xf bank_mask:0xf bound_ctrl:1
	v_add_f32_dpp v132, v118, v118 row_shr:1 row_mask:0xf bank_mask:0xf bound_ctrl:1
	v_add_f32_dpp v118, v126, v132 row_shl:15 row_mask:0xf bank_mask:0xf bound_ctrl:1
	v_add_f32_dpp v126, v126, v126 row_shr:1 row_mask:0xf bank_mask:0xf bound_ctrl:1
	v_add_f32_dpp v132, v119, v119 row_shr:1 row_mask:0xf bank_mask:0xf bound_ctrl:1
	v_add_f32_dpp v119, v127, v132 row_shl:15 row_mask:0xf bank_mask:0xf bound_ctrl:1
	v_add_f32_dpp v127, v127, v127 row_shr:1 row_mask:0xf bank_mask:0xf bound_ctrl:1
	v_add_f32_dpp v132, v120, v120 row_shr:1 row_mask:0xf bank_mask:0xf bound_ctrl:1
	v_add_f32_dpp v120, v128, v132 row_shl:15 row_mask:0xf bank_mask:0xf bound_ctrl:1
	v_add_f32_dpp v128, v128, v128 row_shr:1 row_mask:0xf bank_mask:0xf bound_ctrl:1
	v_add_f32_dpp v132, v121, v121 row_shr:1 row_mask:0xf bank_mask:0xf bound_ctrl:1
	v_add_f32_dpp v121, v129, v132 row_shl:15 row_mask:0xf bank_mask:0xf bound_ctrl:1
	v_add_f32_dpp v129, v129, v129 row_shr:1 row_mask:0xf bank_mask:0xf bound_ctrl:1
	v_add_f32_dpp v132, v122, v122 row_shr:1 row_mask:0xf bank_mask:0xf bound_ctrl:1
	v_add_f32_dpp v122, v130, v132 row_shl:15 row_mask:0xf bank_mask:0xf bound_ctrl:1
	v_add_f32_dpp v130, v130, v130 row_shr:1 row_mask:0xf bank_mask:0xf bound_ctrl:1
	v_add_f32_dpp v132, v123, v123 row_shr:1 row_mask:0xf bank_mask:0xf bound_ctrl:1
	v_add_f32_dpp v123, v131, v132 row_shl:15 row_mask:0xf bank_mask:0xf bound_ctrl:1
	v_add_f32_dpp v131, v131, v131 row_shr:1 row_mask:0xf bank_mask:0xf bound_ctrl:1
	v_add_f32_dpp v132, v116, v116 row_shr:2 row_mask:0xf bank_mask:0xf bound_ctrl:1
	v_add_f32_dpp v116, v124, v132 row_shl:14 row_mask:0xf bank_mask:0xf bound_ctrl:1
	v_add_f32_dpp v124, v124, v124 row_shr:2 row_mask:0xf bank_mask:0xf bound_ctrl:1
	v_add_f32_dpp v132, v117, v117 row_shr:2 row_mask:0xf bank_mask:0xf bound_ctrl:1
	v_add_f32_dpp v117, v125, v132 row_shl:14 row_mask:0xf bank_mask:0xf bound_ctrl:1
	v_add_f32_dpp v125, v125, v125 row_shr:2 row_mask:0xf bank_mask:0xf bound_ctrl:1
	v_add_f32_dpp v132, v118, v118 row_shr:2 row_mask:0xf bank_mask:0xf bound_ctrl:1
	v_add_f32_dpp v118, v126, v132 row_shl:14 row_mask:0xf bank_mask:0xf bound_ctrl:1
	v_add_f32_dpp v126, v126, v126 row_shr:2 row_mask:0xf bank_mask:0xf bound_ctrl:1
	v_add_f32_dpp v132, v119, v119 row_shr:2 row_mask:0xf bank_mask:0xf bound_ctrl:1
	v_add_f32_dpp v119, v127, v132 row_shl:14 row_mask:0xf bank_mask:0xf bound_ctrl:1
	v_add_f32_dpp v127, v127, v127 row_shr:2 row_mask:0xf bank_mask:0xf bound_ctrl:1
	v_add_f32_dpp v132, v120, v120 row_shr:2 row_mask:0xf bank_mask:0xf bound_ctrl:1
	v_add_f32_dpp v120, v128, v132 row_shl:14 row_mask:0xf bank_mask:0xf bound_ctrl:1
	v_add_f32_dpp v128, v128, v128 row_shr:2 row_mask:0xf bank_mask:0xf bound_ctrl:1
	v_add_f32_dpp v132, v121, v121 row_shr:2 row_mask:0xf bank_mask:0xf bound_ctrl:1
	v_add_f32_dpp v121, v129, v132 row_shl:14 row_mask:0xf bank_mask:0xf bound_ctrl:1
	v_add_f32_dpp v129, v129, v129 row_shr:2 row_mask:0xf bank_mask:0xf bound_ctrl:1
	v_add_f32_dpp v132, v122, v122 row_shr:2 row_mask:0xf bank_mask:0xf bound_ctrl:1
	v_add_f32_dpp v122, v130, v132 row_shl:14 row_mask:0xf bank_mask:0xf bound_ctrl:1
	v_add_f32_dpp v130, v130, v130 row_shr:2 row_mask:0xf bank_mask:0xf bound_ctrl:1
	v_add_f32_dpp v132, v123, v123 row_shr:2 row_mask:0xf bank_mask:0xf bound_ctrl:1
	v_add_f32_dpp v123, v131, v132 row_shl:14 row_mask:0xf bank_mask:0xf bound_ctrl:1
	v_add_f32_dpp v131, v131, v131 row_shr:2 row_mask:0xf bank_mask:0xf bound_ctrl:1
	v_fma_f32 v116, v116, v138, -v108
	v_fma_f32 v117, v117, v138, -v109
	v_fma_f32 v118, v118, v138, -v110
	v_fma_f32 v119, v119, v138, -v111
	v_fma_f32 v120, v120, v138, -v112
	v_fma_f32 v121, v121, v138, -v113
	v_fma_f32 v122, v122, v138, -v114
	v_fma_f32 v123, v123, v138, -v115
	v_cvt_pk_bf16_f32 v134, v116, v117
	v_cvt_pk_bf16_f32 v135, v118, v119
	v_cvt_pk_bf16_f32 v136, v120, v121
	v_cvt_pk_bf16_f32 v137, v122, v123
	s_waitcnt lgkmcnt(0)
; #define GAS __attribute__((address_space(1)))
; __device__ __forceinline__ void unpack8(const v4u w, float (&f)[8]) { f[0] = bf_lo(w.x); f[1] = bf_hi(w.x); f[2] = bf_lo(w.y); f[3] = bf_hi(w.y); f[4] = bf_lo(w.z); f[5] = bf_hi(w.z); f[6] = bf_lo(w.w); f[7] = bf_hi(w.w); }
; __device__ __forceinline__ v4u pack8(const float (&f)[8]) { v4u w; w.x = cvt_pk_bf16(f[0], f[1]); w.y = cvt_pk_bf16(f[2], f[3]); w.z = cvt_pk_bf16(f[4], f[5]); w.w = cvt_pk_bf16(f[6], f[7]); return w; }
; template <int SH> __device__ __forceinline__ float row_shr(float v) { return __int_as_float(__builtin_amdgcn_update_dpp(0, __float_as_int(v), 0x110 + SH, 0xf, 0xf, true)); }
; template <int SH> __device__ __forceinline__ float row_shl(float v) { return __int_as_float(__builtin_amdgcn_update_dpp(0, __float_as_int(v), 0x100 + SH, 0xf, 0xf, true)); }
; template <int S> __device__ __forceinline__ void win_step(float (&c)[8], float (&p)[8]) {
; #pragma unroll
;     for (int j = 0; j < 8; ++j) { const float cn = c[j] + row_shr<S>(c[j]) + row_shl<16 - S>(p[j]); p[j] += row_shr<S>(p[j]); c[j] = cn; }
; }
; template <int W> __device__ __forceinline__ void pool_group(const bf16* zrow  , const bf16* pw  , bf16* orow  , int pos, bool prev_ok) {
;     ...
;     for (int kk = 0; kk < 4; ++kk) {
;         if (kk < 3) {
; #pragma unroll
;             for (int dt = 0; dt < 8; ++dt) aw[(kk + 1) & 1][dt] = *(const GAS v4u*)(pw + (size_t)16 * dt * 128 + 32 * (kk + 1)); }
;         float own[8], c[8], p[8];
;         unpack8(cw[kk], own); unpack8(pv[kk], p);
; #pragma unroll
;         for (int j = 0; j < 8; ++j) c[j] = own[j];
;         win_step<1>(c, p);
;         if (W >= 4) win_step<2>(c, p);
;         if (W >= 8) win_step<4>(c, p);
;         if (W >= 16) win_step<8>(c, p);
;         float pl[8];
; #pragma unroll
;         for (int j = 0; j < 8; ++j) pl[j] = c[j] * inv - own[j];
;         const v4u pwk = pack8(pl); const bf16x8 pf = __builtin_bit_cast(bf16x8, pwk);
; #pragma unroll
;         for (int dt = 0; dt < 8; ++dt) acc[dt] = __builtin_amdgcn_mfma_f32_16x16x32_bf16(__builtin_bit_cast(bf16x8, aw[kk & 1][dt]), pf, acc[dt], 0, 0, 0);
	s_nop 0
	v_mfma_f32_16x16x32_bf16 v[76:79], v[44:47], v[134:137], 0
	v_mfma_f32_16x16x32_bf16 v[80:83], v[48:51], v[134:137], 0
	v_mfma_f32_16x16x32_bf16 v[84:87], v[52:55], v[134:137], 0
	v_mfma_f32_16x16x32_bf16 v[88:91], v[56:59], v[134:137], 0
	v_mfma_f32_16x16x32_bf16 v[92:95], v[60:63], v[134:137], 0
	v_mfma_f32_16x16x32_bf16 v[96:99], v[64:67], v[134:137], 0
	v_mfma_f32_16x16x32_bf16 v[100:103], v[68:71], v[134:137], 0
	v_mfma_f32_16x16x32_bf16 v[104:107], v[72:75], v[134:137], 0
	v_add_u32_e32 v147, 32768, v144
	ds_read_b128 v[44:47], v147
	ds_read_b128 v[48:51], v147 offset:4096
	ds_read_b128 v[52:55], v147 offset:8192
	ds_read_b128 v[56:59], v147 offset:12288
	ds_read_b128 v[60:63], v147 offset:16384
	ds_read_b128 v[64:67], v147 offset:20480
	ds_read_b128 v[68:71], v147 offset:24576
	ds_read_b128 v[72:75], v147 offset:28672
	s_waitcnt vmcnt(14)
	v_lshlrev_b32_e32 v108, 16, v20
	v_and_b32_e32 v109, 0xffff0000, v20
	v_lshlrev_b32_e32 v110, 16, v21
	v_and_b32_e32 v111, 0xffff0000, v21
	v_lshlrev_b32_e32 v112, 16, v22
	v_and_b32_e32 v113, 0xffff0000, v22
	v_lshlrev_b32_e32 v114, 16, v23
	v_and_b32_e32 v115, 0xffff0000, v23
	v_lshlrev_b32_e32 v124, 16, v24
	v_and_b32_e32 v125, 0xffff0000, v24
	v_lshlrev_b32_e32 v126, 16, v25
	v_and_b32_e32 v127, 0xffff0000, v25
	v_lshlrev_b32_e32 v128, 16, v26
	v_and_b32_e32 v129, 0xffff0000, v26
	v_lshlrev_b32_e32 v130, 16, v27
	v_and_b32_e32 v131, 0xffff0000, v27
	v_cndmask_b32_e64 v124, 0, v124, s[40:41]
	v_cndmask_b32_e64 v125, 0, v125, s[40:41]
	v_cndmask_b32_e64 v126, 0, v126, s[40:41]
	v_cndmask_b32_e64 v127, 0, v127, s[40:41]
	v_cndmask_b32_e64 v128, 0, v128, s[40:41]
	v_cndmask_b32_e64 v129, 0, v129, s[40:41]
	v_cndmask_b32_e64 v130, 0, v130, s[40:41]
	v_cndmask_b32_e64 v131, 0, v131, s[40:41]
	global_load_dwordx4 v[20:23], v11, s[38:39] offset:576
	global_load_dwordx4 v[24:27], v11, s[48:49] offset:576
	v_mov_b32_e32 v116, v108
	v_mov_b32_e32 v117, v109
	v_mov_b32_e32 v118, v110
	v_mov_b32_e32 v119, v111
	v_mov_b32_e32 v120, v112
	v_mov_b32_e32 v121, v113
	v_mov_b32_e32 v122, v114
	v_mov_b32_e32 v123, v115
	v_add_f32_dpp v132, v116, v116 row_shr:1 row_mask:0xf bank_mask:0xf bound_ctrl:1
	v_add_f32_dpp v116, v124, v132 row_shl:15 row_mask:0xf bank_mask:0xf bound_ctrl:1
	v_add_f32_dpp v124, v124, v124 row_shr:1 row_mask:0xf bank_mask:0xf bound_ctrl:1
	v_add_f32_dpp v132, v117, v117 row_shr:1 row_mask:0xf bank_mask:0xf bound_ctrl:1
	v_add_f32_dpp v117, v125, v132 row_shl:15 row_mask:0xf bank_mask:0xf bound_ctrl:1
	v_add_f32_dpp v125, v125, v125 row_shr:1 row_mask:0xf bank_mask:0xf bound_ctrl:1
	v_add_f32_dpp v132, v118, v118 row_shr:1 row_mask:0xf bank_mask:0xf bound_ctrl:1
	v_add_f32_dpp v118, v126, v132 row_shl:15 row_mask:0xf bank_mask:0xf bound_ctrl:1
	v_add_f32_dpp v126, v126, v126 row_shr:1 row_mask:0xf bank_mask:0xf bound_ctrl:1
	v_add_f32_dpp v132, v119, v119 row_shr:1 row_mask:0xf bank_mask:0xf bound_ctrl:1
	v_add_f32_dpp v119, v127, v132 row_shl:15 row_mask:0xf bank_mask:0xf bound_ctrl:1
	v_add_f32_dpp v127, v127, v127 row_shr:1 row_mask:0xf bank_mask:0xf bound_ctrl:1
	v_add_f32_dpp v132, v120, v120 row_shr:1 row_mask:0xf bank_mask:0xf bound_ctrl:1
	v_add_f32_dpp v120, v128, v132 row_shl:15 row_mask:0xf bank_mask:0xf bound_ctrl:1
	v_add_f32_dpp v128, v128, v128 row_shr:1 row_mask:0xf bank_mask:0xf bound_ctrl:1
	v_add_f32_dpp v132, v121, v121 row_shr:1 row_mask:0xf bank_mask:0xf bound_ctrl:1
	v_add_f32_dpp v121, v129, v132 row_shl:15 row_mask:0xf bank_mask:0xf bound_ctrl:1
	v_add_f32_dpp v129, v129, v129 row_shr:1 row_mask:0xf bank_mask:0xf bound_ctrl:1
	v_add_f32_dpp v132, v122, v122 row_shr:1 row_mask:0xf bank_mask:0xf bound_ctrl:1
	v_add_f32_dpp v122, v130, v132 row_shl:15 row_mask:0xf bank_mask:0xf bound_ctrl:1
	v_add_f32_dpp v130, v130, v130 row_shr:1 row_mask:0xf bank_mask:0xf bound_ctrl:1
	v_add_f32_dpp v132, v123, v123 row_shr:1 row_mask:0xf bank_mask:0xf bound_ctrl:1
	v_add_f32_dpp v123, v131, v132 row_shl:15 row_mask:0xf bank_mask:0xf bound_ctrl:1
	v_add_f32_dpp v131, v131, v131 row_shr:1 row_mask:0xf bank_mask:0xf bound_ctrl:1
	v_add_f32_dpp v132, v116, v116 row_shr:2 row_mask:0xf bank_mask:0xf bound_ctrl:1
	v_add_f32_dpp v116, v124, v132 row_shl:14 row_mask:0xf bank_mask:0xf bound_ctrl:1
	v_add_f32_dpp v124, v124, v124 row_shr:2 row_mask:0xf bank_mask:0xf bound_ctrl:1
	v_add_f32_dpp v132, v117, v117 row_shr:2 row_mask:0xf bank_mask:0xf bound_ctrl:1
	v_add_f32_dpp v117, v125, v132 row_shl:14 row_mask:0xf bank_mask:0xf bound_ctrl:1
	v_add_f32_dpp v125, v125, v125 row_shr:2 row_mask:0xf bank_mask:0xf bound_ctrl:1
	v_add_f32_dpp v132, v118, v118 row_shr:2 row_mask:0xf bank_mask:0xf bound_ctrl:1
	v_add_f32_dpp v118, v126, v132 row_shl:14 row_mask:0xf bank_mask:0xf bound_ctrl:1
	v_add_f32_dpp v126, v126, v126 row_shr:2 row_mask:0xf bank_mask:0xf bound_ctrl:1
	v_add_f32_dpp v132, v119, v119 row_shr:2 row_mask:0xf bank_mask:0xf bound_ctrl:1
	v_add_f32_dpp v119, v127, v132 row_shl:14 row_mask:0xf bank_mask:0xf bound_ctrl:1
	v_add_f32_dpp v127, v127, v127 row_shr:2 row_mask:0xf bank_mask:0xf bound_ctrl:1
	v_add_f32_dpp v132, v120, v120 row_shr:2 row_mask:0xf bank_mask:0xf bound_ctrl:1
	v_add_f32_dpp v120, v128, v132 row_shl:14 row_mask:0xf bank_mask:0xf bound_ctrl:1
	v_add_f32_dpp v128, v128, v128 row_shr:2 row_mask:0xf bank_mask:0xf bound_ctrl:1
	v_add_f32_dpp v132, v121, v121 row_shr:2 row_mask:0xf bank_mask:0xf bound_ctrl:1
	v_add_f32_dpp v121, v129, v132 row_shl:14 row_mask:0xf bank_mask:0xf bound_ctrl:1
	v_add_f32_dpp v129, v129, v129 row_shr:2 row_mask:0xf bank_mask:0xf bound_ctrl:1
	v_add_f32_dpp v132, v122, v122 row_shr:2 row_mask:0xf bank_mask:0xf bound_ctrl:1
	v_add_f32_dpp v122, v130, v132 row_shl:14 row_mask:0xf bank_mask:0xf bound_ctrl:1
	v_add_f32_dpp v130, v130, v130 row_shr:2 row_mask:0xf bank_mask:0xf bound_ctrl:1
	v_add_f32_dpp v132, v123, v123 row_shr:2 row_mask:0xf bank_mask:0xf bound_ctrl:1
	v_add_f32_dpp v123, v131, v132 row_shl:14 row_mask:0xf bank_mask:0xf bound_ctrl:1
	v_add_f32_dpp v131, v131, v131 row_shr:2 row_mask:0xf bank_mask:0xf bound_ctrl:1
	v_fma_f32 v116, v116, v138, -v108
	v_fma_f32 v117, v117, v138, -v109
	v_fma_f32 v118, v118, v138, -v110
	v_fma_f32 v119, v119, v138, -v111
	v_fma_f32 v120, v120, v138, -v112
	v_fma_f32 v121, v121, v138, -v113
	v_fma_f32 v122, v122, v138, -v114
	v_fma_f32 v123, v123, v138, -v115
	v_cvt_pk_bf16_f32 v134, v116, v117
	v_cvt_pk_bf16_f32 v135, v118, v119
	v_cvt_pk_bf16_f32 v136, v120, v121
	v_cvt_pk_bf16_f32 v137, v122, v123
	s_waitcnt lgkmcnt(0)
; #define GAS __attribute__((address_space(1)))
; __device__ __forceinline__ void unpack8(const v4u w, float (&f)[8]) { f[0] = bf_lo(w.x); f[1] = bf_hi(w.x); f[2] = bf_lo(w.y); f[3] = bf_hi(w.y); f[4] = bf_lo(w.z); f[5] = bf_hi(w.z); f[6] = bf_lo(w.w); f[7] = bf_hi(w.w); }
; __device__ __forceinline__ v4u pack8(const float (&f)[8]) { v4u w; w.x = cvt_pk_bf16(f[0], f[1]); w.y = cvt_pk_bf16(f[2], f[3]); w.z = cvt_pk_bf16(f[4], f[5]); w.w = cvt_pk_bf16(f[6], f[7]); return w; }
; template <int SH> __device__ __forceinline__ float row_shr(float v) { return __int_as_float(__builtin_amdgcn_update_dpp(0, __float_as_int(v), 0x110 + SH, 0xf, 0xf, true)); }
; template <int SH> __device__ __forceinline__ float row_shl(float v) { return __int_as_float(__builtin_amdgcn_update_dpp(0, __float_as_int(v), 0x100 + SH, 0xf, 0xf, true)); }
; template <int S> __device__ __forceinline__ void win_step(float (&c)[8], float (&p)[8]) {
; #pragma unroll
;     for (int j = 0; j < 8; ++j) { const float cn = c[j] + row_shr<S>(c[j]) + row_shl<16 - S>(p[j]); p[j] += row_shr<S>(p[j]); c[j] = cn; }
; }
; template <int W> __device__ __forceinline__ void pool_group(const bf16* zrow  , const bf16* pw  , bf16* orow  , int pos, bool prev_ok) {
;     ...
;     for (int kk = 0; kk < 4; ++kk) {
;         if (kk < 3) {
; #pragma unroll
;             for (int dt = 0; dt < 8; ++dt) aw[(kk + 1) & 1][dt] = *(const GAS v4u*)(pw + (size_t)16 * dt * 128 + 32 * (kk + 1)); }
;         float own[8], c[8], p[8];
;         unpack8(cw[kk], own); unpack8(pv[kk], p);
; #pragma unroll
;         for (int j = 0; j < 8; ++j) c[j] = own[j];
;         win_step<1>(c, p);
;         if (W >= 4) win_step<2>(c, p);
;         if (W >= 8) win_step<4>(c, p);
;         if (W >= 16) win_step<8>(c, p);
;         float pl[8];
; #pragma unroll
;         for (int j = 0; j < 8; ++j) pl[j] = c[j] * inv - own[j];
;         const v4u pwk = pack8(pl); const bf16x8 pf = __builtin_bit_cast(bf16x8, pwk);
; #pragma unroll
;         for (int dt = 0; dt < 8; ++dt) acc[dt] = __builtin_amdgcn_mfma_f32_16x16x32_bf16(__builtin_bit_cast(bf16x8, aw[kk & 1][dt]), pf, acc[dt], 0, 0, 0);
	s_nop 0
	v_mfma_f32_16x16x32_bf16 v[76:79], v[44:47], v[134:137], v[76:79]
	v_mfma_f32_16x16x32_bf16 v[80:83], v[48:51], v[134:137], v[80:83]
	v_mfma_f32_16x16x32_bf16 v[84:87], v[52:55], v[134:137], v[84:87]
	v_mfma_f32_16x16x32_bf16 v[88:91], v[56:59], v[134:137], v[88:91]
	v_mfma_f32_16x16x32_bf16 v[92:95], v[60:63], v[134:137], v[92:95]
	v_mfma_f32_16x16x32_bf16 v[96:99], v[64:67], v[134:137], v[96:99]
	v_mfma_f32_16x16x32_bf16 v[100:103], v[68:71], v[134:137], v[100:103]
	v_mfma_f32_16x16x32_bf16 v[104:107], v[72:75], v[134:137], v[104:107]
	v_add_u32_e32 v147, 32768, v145
	ds_read_b128 v[44:47], v147
	ds_read_b128 v[48:51], v147 offset:4096
	ds_read_b128 v[52:55], v147 offset:8192
	ds_read_b128 v[56:59], v147 offset:12288
	ds_read_b128 v[60:63], v147 offset:16384
	ds_read_b128 v[64:67], v147 offset:20480
	ds_read_b128 v[68:71], v147 offset:24576
	ds_read_b128 v[72:75], v147 offset:28672
	s_waitcnt vmcnt(14)
	v_lshlrev_b32_e32 v108, 16, v28
	v_and_b32_e32 v109, 0xffff0000, v28
	v_lshlrev_b32_e32 v110, 16, v29
	v_and_b32_e32 v111, 0xffff0000, v29
	v_lshlrev_b32_e32 v112, 16, v30
	v_and_b32_e32 v113, 0xffff0000, v30
	v_lshlrev_b32_e32 v114, 16, v31
	v_and_b32_e32 v115, 0xffff0000, v31
	v_lshlrev_b32_e32 v124, 16, v32
	v_and_b32_e32 v125, 0xffff0000, v32
	v_lshlrev_b32_e32 v126, 16, v33
	v_and_b32_e32 v127, 0xffff0000, v33
	v_lshlrev_b32_e32 v128, 16, v34
	v_and_b32_e32 v129, 0xffff0000, v34
	v_lshlrev_b32_e32 v130, 16, v35
	v_and_b32_e32 v131, 0xffff0000, v35
	v_cndmask_b32_e64 v124, 0, v124, s[40:41]
	v_cndmask_b32_e64 v125, 0, v125, s[40:41]
	v_cndmask_b32_e64 v126, 0, v126, s[40:41]
	v_cndmask_b32_e64 v127, 0, v127, s[40:41]
	v_cndmask_b32_e64 v128, 0, v128, s[40:41]
	v_cndmask_b32_e64 v129, 0, v129, s[40:41]
	v_cndmask_b32_e64 v130, 0, v130, s[40:41]
	v_cndmask_b32_e64 v131, 0, v131, s[40:41]
	global_load_dwordx4 v[28:31], v11, s[38:39] offset:640
	global_load_dwordx4 v[32:35], v11, s[48:49] offset:640
	v_mov_b32_e32 v116, v108
	v_mov_b32_e32 v117, v109
	v_mov_b32_e32 v118, v110
	v_mov_b32_e32 v119, v111
	v_mov_b32_e32 v120, v112
	v_mov_b32_e32 v121, v113
	v_mov_b32_e32 v122, v114
	v_mov_b32_e32 v123, v115
	v_add_f32_dpp v132, v116, v116 row_shr:1 row_mask:0xf bank_mask:0xf bound_ctrl:1
	v_add_f32_dpp v116, v124, v132 row_shl:15 row_mask:0xf bank_mask:0xf bound_ctrl:1
	v_add_f32_dpp v124, v124, v124 row_shr:1 row_mask:0xf bank_mask:0xf bound_ctrl:1
	v_add_f32_dpp v132, v117, v117 row_shr:1 row_mask:0xf bank_mask:0xf bound_ctrl:1
	v_add_f32_dpp v117, v125, v132 row_shl:15 row_mask:0xf bank_mask:0xf bound_ctrl:1
	v_add_f32_dpp v125, v125, v125 row_shr:1 row_mask:0xf bank_mask:0xf bound_ctrl:1
	v_add_f32_dpp v132, v118, v118 row_shr:1 row_mask:0xf bank_mask:0xf bound_ctrl:1
	v_add_f32_dpp v118, v126, v132 row_shl:15 row_mask:0xf bank_mask:0xf bound_ctrl:1
	v_add_f32_dpp v126, v126, v126 row_shr:1 row_mask:0xf bank_mask:0xf bound_ctrl:1
	v_add_f32_dpp v132, v119, v119 row_shr:1 row_mask:0xf bank_mask:0xf bound_ctrl:1
	v_add_f32_dpp v119, v127, v132 row_shl:15 row_mask:0xf bank_mask:0xf bound_ctrl:1
	v_add_f32_dpp v127, v127, v127 row_shr:1 row_mask:0xf bank_mask:0xf bound_ctrl:1
	v_add_f32_dpp v132, v120, v120 row_shr:1 row_mask:0xf bank_mask:0xf bound_ctrl:1
	v_add_f32_dpp v120, v128, v132 row_shl:15 row_mask:0xf bank_mask:0xf bound_ctrl:1
	v_add_f32_dpp v128, v128, v128 row_shr:1 row_mask:0xf bank_mask:0xf bound_ctrl:1
	v_add_f32_dpp v132, v121, v121 row_shr:1 row_mask:0xf bank_mask:0xf bound_ctrl:1
	v_add_f32_dpp v121, v129, v132 row_shl:15 row_mask:0xf bank_mask:0xf bound_ctrl:1
	v_add_f32_dpp v129, v129, v129 row_shr:1 row_mask:0xf bank_mask:0xf bound_ctrl:1
	v_add_f32_dpp v132, v122, v122 row_shr:1 row_mask:0xf bank_mask:0xf bound_ctrl:1
	v_add_f32_dpp v122, v130, v132 row_shl:15 row_mask:0xf bank_mask:0xf bound_ctrl:1
	v_add_f32_dpp v130, v130, v130 row_shr:1 row_mask:0xf bank_mask:0xf bound_ctrl:1
	v_add_f32_dpp v132, v123, v123 row_shr:1 row_mask:0xf bank_mask:0xf bound_ctrl:1
	v_add_f32_dpp v123, v131, v132 row_shl:15 row_mask:0xf bank_mask:0xf bound_ctrl:1
	v_add_f32_dpp v131, v131, v131 row_shr:1 row_mask:0xf bank_mask:0xf bound_ctrl:1
	v_add_f32_dpp v132, v116, v116 row_shr:2 row_mask:0xf bank_mask:0xf bound_ctrl:1
	v_add_f32_dpp v116, v124, v132 row_shl:14 row_mask:0xf bank_mask:0xf bound_ctrl:1
	v_add_f32_dpp v124, v124, v124 row_shr:2 row_mask:0xf bank_mask:0xf bound_ctrl:1
	v_add_f32_dpp v132, v117, v117 row_shr:2 row_mask:0xf bank_mask:0xf bound_ctrl:1
	v_add_f32_dpp v117, v125, v132 row_shl:14 row_mask:0xf bank_mask:0xf bound_ctrl:1
	v_add_f32_dpp v125, v125, v125 row_shr:2 row_mask:0xf bank_mask:0xf bound_ctrl:1
	v_add_f32_dpp v132, v118, v118 row_shr:2 row_mask:0xf bank_mask:0xf bound_ctrl:1
	v_add_f32_dpp v118, v126, v132 row_shl:14 row_mask:0xf bank_mask:0xf bound_ctrl:1
	v_add_f32_dpp v126, v126, v126 row_shr:2 row_mask:0xf bank_mask:0xf bound_ctrl:1
	v_add_f32_dpp v132, v119, v119 row_shr:2 row_mask:0xf bank_mask:0xf bound_ctrl:1
	v_add_f32_dpp v119, v127, v132 row_shl:14 row_mask:0xf bank_mask:0xf bound_ctrl:1
	v_add_f32_dpp v127, v127, v127 row_shr:2 row_mask:0xf bank_mask:0xf bound_ctrl:1
	v_add_f32_dpp v132, v120, v120 row_shr:2 row_mask:0xf bank_mask:0xf bound_ctrl:1
	v_add_f32_dpp v120, v128, v132 row_shl:14 row_mask:0xf bank_mask:0xf bound_ctrl:1
	v_add_f32_dpp v128, v128, v128 row_shr:2 row_mask:0xf bank_mask:0xf bound_ctrl:1
	v_add_f32_dpp v132, v121, v121 row_shr:2 row_mask:0xf bank_mask:0xf bound_ctrl:1
	v_add_f32_dpp v121, v129, v132 row_shl:14 row_mask:0xf bank_mask:0xf bound_ctrl:1
	v_add_f32_dpp v129, v129, v129 row_shr:2 row_mask:0xf bank_mask:0xf bound_ctrl:1
	v_add_f32_dpp v132, v122, v122 row_shr:2 row_mask:0xf bank_mask:0xf bound_ctrl:1
	v_add_f32_dpp v122, v130, v132 row_shl:14 row_mask:0xf bank_mask:0xf bound_ctrl:1
	v_add_f32_dpp v130, v130, v130 row_shr:2 row_mask:0xf bank_mask:0xf bound_ctrl:1
	v_add_f32_dpp v132, v123, v123 row_shr:2 row_mask:0xf bank_mask:0xf bound_ctrl:1
	v_add_f32_dpp v123, v131, v132 row_shl:14 row_mask:0xf bank_mask:0xf bound_ctrl:1
	v_add_f32_dpp v131, v131, v131 row_shr:2 row_mask:0xf bank_mask:0xf bound_ctrl:1
	v_fma_f32 v116, v116, v138, -v108
	v_fma_f32 v117, v117, v138, -v109
	v_fma_f32 v118, v118, v138, -v110
	v_fma_f32 v119, v119, v138, -v111
	v_fma_f32 v120, v120, v138, -v112
	v_fma_f32 v121, v121, v138, -v113
	v_fma_f32 v122, v122, v138, -v114
	v_fma_f32 v123, v123, v138, -v115
	v_cvt_pk_bf16_f32 v134, v116, v117
	v_cvt_pk_bf16_f32 v135, v118, v119
	v_cvt_pk_bf16_f32 v136, v120, v121
	v_cvt_pk_bf16_f32 v137, v122, v123
	s_waitcnt lgkmcnt(0)
; #define GAS __attribute__((address_space(1)))
; __device__ __forceinline__ void unpack8(const v4u w, float (&f)[8]) { f[0] = bf_lo(w.x); f[1] = bf_hi(w.x); f[2] = bf_lo(w.y); f[3] = bf_hi(w.y); f[4] = bf_lo(w.z); f[5] = bf_hi(w.z); f[6] = bf_lo(w.w); f[7] = bf_hi(w.w); }
; __device__ __forceinline__ v4u pack8(const float (&f)[8]) { v4u w; w.x = cvt_pk_bf16(f[0], f[1]); w.y = cvt_pk_bf16(f[2], f[3]); w.z = cvt_pk_bf16(f[4], f[5]); w.w = cvt_pk_bf16(f[6], f[7]); return w; }
; template <int SH> __device__ __forceinline__ float row_shr(float v) { return __int_as_float(__builtin_amdgcn_update_dpp(0, __float_as_int(v), 0x110 + SH, 0xf, 0xf, true)); }
; template <int SH> __device__ __forceinline__ float row_shl(float v) { return __int_as_float(__builtin_amdgcn_update_dpp(0, __float_as_int(v), 0x100 + SH, 0xf, 0xf, true)); }
; template <int S> __device__ __forceinline__ void win_step(float (&c)[8], float (&p)[8]) {
; #pragma unroll
;     for (int j = 0; j < 8; ++j) { const float cn = c[j] + row_shr<S>(c[j]) + row_shl<16 - S>(p[j]); p[j] += row_shr<S>(p[j]); c[j] = cn; }
; }
; template <int W> __device__ __forceinline__ void pool_group(const bf16* zrow  , const bf16* pw  , bf16* orow  , int pos, bool prev_ok) {
;     ...
;     for (int kk = 0; kk < 4; ++kk) {
;         if (kk < 3) {
; #pragma unroll
;             for (int dt = 0; dt < 8; ++dt) aw[(kk + 1) & 1][dt] = *(const GAS v4u*)(pw + (size_t)16 * dt * 128 + 32 * (kk + 1)); }
;         float own[8], c[8], p[8];
;         unpack8(cw[kk], own); unpack8(pv[kk], p);
; #pragma unroll
;         for (int j = 0; j < 8; ++j) c[j] = own[j];
;         win_step<1>(c, p);
;         if (W >= 4) win_step<2>(c, p);
;         if (W >= 8) win_step<4>(c, p);
;         if (W >= 16) win_step<8>(c, p);
;         float pl[8];
; #pragma unroll
;         for (int j = 0; j < 8; ++j) pl[j] = c[j] * inv - own[j];
;         const v4u pwk = pack8(pl); const bf16x8 pf = __builtin_bit_cast(bf16x8, pwk);
; #pragma unroll
;         for (int dt = 0; dt < 8; ++dt) acc[dt] = __builtin_amdgcn_mfma_f32_16x16x32_bf16(__builtin_bit_cast(bf16x8, aw[kk & 1][dt]), pf, acc[dt], 0, 0, 0);
	s_nop 0
	v_mfma_f32_16x16x32_bf16 v[76:79], v[44:47], v[134:137], v[76:79]
	v_mfma_f32_16x16x32_bf16 v[80:83], v[48:51], v[134:137], v[80:83]
	v_mfma_f32_16x16x32_bf16 v[84:87], v[52:55], v[134:137], v[84:87]
	v_mfma_f32_16x16x32_bf16 v[88:91], v[56:59], v[134:137], v[88:91]
	v_mfma_f32_16x16x32_bf16 v[92:95], v[60:63], v[134:137], v[92:95]
	v_mfma_f32_16x16x32_bf16 v[96:99], v[64:67], v[134:137], v[96:99]
	v_mfma_f32_16x16x32_bf16 v[100:103], v[68:71], v[134:137], v[100:103]
	v_mfma_f32_16x16x32_bf16 v[104:107], v[72:75], v[134:137], v[104:107]
	v_add_u32_e32 v147, 32768, v146
	ds_read_b128 v[44:47], v147
	ds_read_b128 v[48:51], v147 offset:4096
	ds_read_b128 v[52:55], v147 offset:8192
	ds_read_b128 v[56:59], v147 offset:12288
	ds_read_b128 v[60:63], v147 offset:16384
	ds_read_b128 v[64:67], v147 offset:20480
	ds_read_b128 v[68:71], v147 offset:24576
	ds_read_b128 v[72:75], v147 offset:28672
	s_waitcnt vmcnt(14)
	v_lshlrev_b32_e32 v108, 16, v36
	v_and_b32_e32 v109, 0xffff0000, v36
	v_lshlrev_b32_e32 v110, 16, v37
	v_and_b32_e32 v111, 0xffff0000, v37
	v_lshlrev_b32_e32 v112, 16, v38
	v_and_b32_e32 v113, 0xffff0000, v38
	v_lshlrev_b32_e32 v114, 16, v39
	v_and_b32_e32 v115, 0xffff0000, v39
	v_lshlrev_b32_e32 v124, 16, v40
	v_and_b32_e32 v125, 0xffff0000, v40
	v_lshlrev_b32_e32 v126, 16, v41
	v_and_b32_e32 v127, 0xffff0000, v41
	v_lshlrev_b32_e32 v128, 16, v42
	v_and_b32_e32 v129, 0xffff0000, v42
	v_lshlrev_b32_e32 v130, 16, v43
	v_and_b32_e32 v131, 0xffff0000, v43
	v_cndmask_b32_e64 v124, 0, v124, s[40:41]
	v_cndmask_b32_e64 v125, 0, v125, s[40:41]
	v_cndmask_b32_e64 v126, 0, v126, s[40:41]
	v_cndmask_b32_e64 v127, 0, v127, s[40:41]
	v_cndmask_b32_e64 v128, 0, v128, s[40:41]
	v_cndmask_b32_e64 v129, 0, v129, s[40:41]
	v_cndmask_b32_e64 v130, 0, v130, s[40:41]
	v_cndmask_b32_e64 v131, 0, v131, s[40:41]
	global_load_dwordx4 v[36:39], v11, s[38:39] offset:704
	global_load_dwordx4 v[40:43], v11, s[48:49] offset:704
	v_mov_b32_e32 v116, v108
	v_mov_b32_e32 v117, v109
	v_mov_b32_e32 v118, v110
	v_mov_b32_e32 v119, v111
	v_mov_b32_e32 v120, v112
	v_mov_b32_e32 v121, v113
	v_mov_b32_e32 v122, v114
	v_mov_b32_e32 v123, v115
	v_add_f32_dpp v132, v116, v116 row_shr:1 row_mask:0xf bank_mask:0xf bound_ctrl:1
	v_add_f32_dpp v116, v124, v132 row_shl:15 row_mask:0xf bank_mask:0xf bound_ctrl:1
	v_add_f32_dpp v124, v124, v124 row_shr:1 row_mask:0xf bank_mask:0xf bound_ctrl:1
	v_add_f32_dpp v132, v117, v117 row_shr:1 row_mask:0xf bank_mask:0xf bound_ctrl:1
	v_add_f32_dpp v117, v125, v132 row_shl:15 row_mask:0xf bank_mask:0xf bound_ctrl:1
	v_add_f32_dpp v125, v125, v125 row_shr:1 row_mask:0xf bank_mask:0xf bound_ctrl:1
	v_add_f32_dpp v132, v118, v118 row_shr:1 row_mask:0xf bank_mask:0xf bound_ctrl:1
	v_add_f32_dpp v118, v126, v132 row_shl:15 row_mask:0xf bank_mask:0xf bound_ctrl:1
	v_add_f32_dpp v126, v126, v126 row_shr:1 row_mask:0xf bank_mask:0xf bound_ctrl:1
	v_add_f32_dpp v132, v119, v119 row_shr:1 row_mask:0xf bank_mask:0xf bound_ctrl:1
	v_add_f32_dpp v119, v127, v132 row_shl:15 row_mask:0xf bank_mask:0xf bound_ctrl:1
	v_add_f32_dpp v127, v127, v127 row_shr:1 row_mask:0xf bank_mask:0xf bound_ctrl:1
	v_add_f32_dpp v132, v120, v120 row_shr:1 row_mask:0xf bank_mask:0xf bound_ctrl:1
	v_add_f32_dpp v120, v128, v132 row_shl:15 row_mask:0xf bank_mask:0xf bound_ctrl:1
	v_add_f32_dpp v128, v128, v128 row_shr:1 row_mask:0xf bank_mask:0xf bound_ctrl:1
	v_add_f32_dpp v132, v121, v121 row_shr:1 row_mask:0xf bank_mask:0xf bound_ctrl:1
	v_add_f32_dpp v121, v129, v132 row_shl:15 row_mask:0xf bank_mask:0xf bound_ctrl:1
	v_add_f32_dpp v129, v129, v129 row_shr:1 row_mask:0xf bank_mask:0xf bound_ctrl:1
	v_add_f32_dpp v132, v122, v122 row_shr:1 row_mask:0xf bank_mask:0xf bound_ctrl:1
	v_add_f32_dpp v122, v130, v132 row_shl:15 row_mask:0xf bank_mask:0xf bound_ctrl:1
	v_add_f32_dpp v130, v130, v130 row_shr:1 row_mask:0xf bank_mask:0xf bound_ctrl:1
	v_add_f32_dpp v132, v123, v123 row_shr:1 row_mask:0xf bank_mask:0xf bound_ctrl:1
	v_add_f32_dpp v123, v131, v132 row_shl:15 row_mask:0xf bank_mask:0xf bound_ctrl:1
	v_add_f32_dpp v131, v131, v131 row_shr:1 row_mask:0xf bank_mask:0xf bound_ctrl:1
	v_add_f32_dpp v132, v116, v116 row_shr:2 row_mask:0xf bank_mask:0xf bound_ctrl:1
	v_add_f32_dpp v116, v124, v132 row_shl:14 row_mask:0xf bank_mask:0xf bound_ctrl:1
	v_add_f32_dpp v124, v124, v124 row_shr:2 row_mask:0xf bank_mask:0xf bound_ctrl:1
	v_add_f32_dpp v132, v117, v117 row_shr:2 row_mask:0xf bank_mask:0xf bound_ctrl:1
	v_add_f32_dpp v117, v125, v132 row_shl:14 row_mask:0xf bank_mask:0xf bound_ctrl:1
	v_add_f32_dpp v125, v125, v125 row_shr:2 row_mask:0xf bank_mask:0xf bound_ctrl:1
	v_add_f32_dpp v132, v118, v118 row_shr:2 row_mask:0xf bank_mask:0xf bound_ctrl:1
	v_add_f32_dpp v118, v126, v132 row_shl:14 row_mask:0xf bank_mask:0xf bound_ctrl:1
	v_add_f32_dpp v126, v126, v126 row_shr:2 row_mask:0xf bank_mask:0xf bound_ctrl:1
	v_add_f32_dpp v132, v119, v119 row_shr:2 row_mask:0xf bank_mask:0xf bound_ctrl:1
	v_add_f32_dpp v119, v127, v132 row_shl:14 row_mask:0xf bank_mask:0xf bound_ctrl:1
	v_add_f32_dpp v127, v127, v127 row_shr:2 row_mask:0xf bank_mask:0xf bound_ctrl:1
	v_add_f32_dpp v132, v120, v120 row_shr:2 row_mask:0xf bank_mask:0xf bound_ctrl:1
	v_add_f32_dpp v120, v128, v132 row_shl:14 row_mask:0xf bank_mask:0xf bound_ctrl:1
	v_add_f32_dpp v128, v128, v128 row_shr:2 row_mask:0xf bank_mask:0xf bound_ctrl:1
	v_add_f32_dpp v132, v121, v121 row_shr:2 row_mask:0xf bank_mask:0xf bound_ctrl:1
	v_add_f32_dpp v121, v129, v132 row_shl:14 row_mask:0xf bank_mask:0xf bound_ctrl:1
	v_add_f32_dpp v129, v129, v129 row_shr:2 row_mask:0xf bank_mask:0xf bound_ctrl:1
	v_add_f32_dpp v132, v122, v122 row_shr:2 row_mask:0xf bank_mask:0xf bound_ctrl:1
	v_add_f32_dpp v122, v130, v132 row_shl:14 row_mask:0xf bank_mask:0xf bound_ctrl:1
	v_add_f32_dpp v130, v130, v130 row_shr:2 row_mask:0xf bank_mask:0xf bound_ctrl:1
	v_add_f32_dpp v132, v123, v123 row_shr:2 row_mask:0xf bank_mask:0xf bound_ctrl:1
	v_add_f32_dpp v123, v131, v132 row_shl:14 row_mask:0xf bank_mask:0xf bound_ctrl:1
	v_add_f32_dpp v131, v131, v131 row_shr:2 row_mask:0xf bank_mask:0xf bound_ctrl:1
	v_fma_f32 v116, v116, v138, -v108
	v_fma_f32 v117, v117, v138, -v109
	v_fma_f32 v118, v118, v138, -v110
	v_fma_f32 v119, v119, v138, -v111
	v_fma_f32 v120, v120, v138, -v112
	v_fma_f32 v121, v121, v138, -v113
	v_fma_f32 v122, v122, v138, -v114
	v_fma_f32 v123, v123, v138, -v115
	v_cvt_pk_bf16_f32 v134, v116, v117
	v_cvt_pk_bf16_f32 v135, v118, v119
	v_cvt_pk_bf16_f32 v136, v120, v121
	v_cvt_pk_bf16_f32 v137, v122, v123
	s_waitcnt lgkmcnt(0)
; __device__ __forceinline__ unsigned cvt_pk_bf16(float lo, float hi) { return __builtin_bit_cast(unsigned, __builtin_convertvector((f32x2_t){lo, hi}, bf16x2_t)); }
; #define GAS __attribute__((address_space(1)))
; __device__ __forceinline__ void unpack8(const v4u w, float (&f)[8]) { f[0] = bf_lo(w.x); f[1] = bf_hi(w.x); f[2] = bf_lo(w.y); f[3] = bf_hi(w.y); f[4] = bf_lo(w.z); f[5] = bf_hi(w.z); f[6] = bf_lo(w.w); f[7] = bf_hi(w.w); }
; __device__ __forceinline__ v4u pack8(const float (&f)[8]) { v4u w; w.x = cvt_pk_bf16(f[0], f[1]); w.y = cvt_pk_bf16(f[2], f[3]); w.z = cvt_pk_bf16(f[4], f[5]); w.w = cvt_pk_bf16(f[6], f[7]); return w; }
; template <int SH> __device__ __forceinline__ float row_shr(float v) { return __int_as_float(__builtin_amdgcn_update_dpp(0, __float_as_int(v), 0x110 + SH, 0xf, 0xf, true)); }
; template <int S> __device__ __forceinline__ void win_step(float (&c)[8], float (&p)[8]) {
; #pragma unroll
;     for (int j = 0; j < 8; ++j) { const float cn = c[j] + row_shr<S>(c[j]) + row_shl<16 - S>(p[j]); p[j] += row_shr<S>(p[j]); c[j] = cn; }
; }
; template <int W> __device__ __forceinline__ void pool_group(const bf16* zrow  , const bf16* pw  , bf16* orow  , int pos, bool prev_ok) {
;     const float inv = 1.0f / (float)((pos + 1) < W ? (pos + 1) : W);
;     ...
;     for (int kk = 0; kk < 4; ++kk) {
;         if (kk < 3) {
; #pragma unroll
;             for (int dt = 0; dt < 8; ++dt) aw[(kk + 1) & 1][dt] = *(const GAS v4u*)(pw + (size_t)16 * dt * 128 + 32 * (kk + 1)); }
;         float own[8], c[8], p[8];
;         unpack8(cw[kk], own); unpack8(pv[kk], p);
; #pragma unroll
;         for (int j = 0; j < 8; ++j) c[j] = own[j];
;         win_step<1>(c, p);
;         if (W >= 4) win_step<2>(c, p);
;         if (W >= 8) win_step<4>(c, p);
;         if (W >= 16) win_step<8>(c, p);
;         float pl[8];
; #pragma unroll
;         for (int j = 0; j < 8; ++j) pl[j] = c[j] * inv - own[j];
;         const v4u pwk = pack8(pl); const bf16x8 pf = __builtin_bit_cast(bf16x8, pwk);
; #pragma unroll
;         for (int dt = 0; dt < 8; ++dt) acc[dt] = __builtin_amdgcn_mfma_f32_16x16x32_bf16(__builtin_bit_cast(bf16x8, aw[kk & 1][dt]), pf, acc[dt], 0, 0, 0);
;     }
; #pragma unroll
;     for (int dt = 0; dt < 8; ++dt) { v2u w; w.x = cvt_pk_bf16(acc[dt][0], acc[dt][1]); w.y = cvt_pk_bf16(acc[dt][2], acc[dt][3]); *(GAS v2u*)(orow + 16 * dt) = w; }
	s_nop 0
	v_mfma_f32_16x16x32_bf16 v[76:79], v[44:47], v[134:137], v[76:79]
	v_mfma_f32_16x16x32_bf16 v[80:83], v[48:51], v[134:137], v[80:83]
	v_mfma_f32_16x16x32_bf16 v[84:87], v[52:55], v[134:137], v[84:87]
	v_mfma_f32_16x16x32_bf16 v[88:91], v[56:59], v[134:137], v[88:91]
	v_mfma_f32_16x16x32_bf16 v[92:95], v[60:63], v[134:137], v[92:95]
	v_mfma_f32_16x16x32_bf16 v[96:99], v[64:67], v[134:137], v[96:99]
	v_mfma_f32_16x16x32_bf16 v[100:103], v[68:71], v[134:137], v[100:103]
	v_mfma_f32_16x16x32_bf16 v[104:107], v[72:75], v[134:137], v[104:107]
	s_nop 7
	s_nop 1
	v_cvt_pk_bf16_f32 v132, v76, v77
	v_cvt_pk_bf16_f32 v133, v78, v79
	global_store_dwordx2 v142, v[132:133], s[46:47] offset:256
	s_nop 0
	v_cvt_pk_bf16_f32 v132, v80, v81
	v_cvt_pk_bf16_f32 v133, v82, v83
	global_store_dwordx2 v142, v[132:133], s[46:47] offset:288
	s_nop 0
	v_cvt_pk_bf16_f32 v132, v84, v85
	v_cvt_pk_bf16_f32 v133, v86, v87
	global_store_dwordx2 v142, v[132:133], s[46:47] offset:320
	s_nop 0
	v_cvt_pk_bf16_f32 v132, v88, v89
	v_cvt_pk_bf16_f32 v133, v90, v91
	global_store_dwordx2 v142, v[132:133], s[46:47] offset:352
	s_nop 0
	v_cvt_pk_bf16_f32 v132, v92, v93
	v_cvt_pk_bf16_f32 v133, v94, v95
	global_store_dwordx2 v142, v[132:133], s[46:47] offset:384
	s_nop 0
	v_cvt_pk_bf16_f32 v132, v96, v97
	v_cvt_pk_bf16_f32 v133, v98, v99
	global_store_dwordx2 v142, v[132:133], s[46:47] offset:416
	s_nop 0
	v_cvt_pk_bf16_f32 v132, v100, v101
	v_cvt_pk_bf16_f32 v133, v102, v103
	global_store_dwordx2 v142, v[132:133], s[46:47] offset:448
	s_nop 0
	v_cvt_pk_bf16_f32 v132, v104, v105
	v_cvt_pk_bf16_f32 v133, v106, v107
	global_store_dwordx2 v142, v[132:133], s[46:47] offset:480
	s_nop 0
	v_min_i32_e32 v139, 8, v140
	v_cvt_f32_i32_e32 v139, v139
	v_div_scale_f32 v1, s[42:43], v139, v139, 1.0
	v_rcp_f32_e32 v2, v1
	s_nop 0
	v_fma_f32 v7, -v1, v2, 1.0
	v_fmac_f32_e32 v2, v7, v2
	v_div_scale_f32 v3, vcc, 1.0, v139, 1.0
	v_mul_f32_e32 v6, v3, v2
	v_fma_f32 v7, -v1, v6, v3
	v_fmac_f32_e32 v6, v7, v2
	v_fma_f32 v1, -v1, v6, v3
	s_nop 1
	v_div_fmas_f32 v1, v1, v2, v6
	v_div_fixup_f32 v138, v1, v139, 1.0
	v_add_u32_e32 v147, 65536, v143
	ds_read_b128 v[44:47], v147
	ds_read_b128 v[48:51], v147 offset:4096
	ds_read_b128 v[52:55], v147 offset:8192
	ds_read_b128 v[56:59], v147 offset:12288
	ds_read_b128 v[60:63], v147 offset:16384
	ds_read_b128 v[64:67], v147 offset:20480
	ds_read_b128 v[68:71], v147 offset:24576
	ds_read_b128 v[72:75], v147 offset:28672
	s_waitcnt vmcnt(14)
	v_lshlrev_b32_e32 v108, 16, v12
	v_and_b32_e32 v109, 0xffff0000, v12
	v_lshlrev_b32_e32 v110, 16, v13
	v_and_b32_e32 v111, 0xffff0000, v13
	v_lshlrev_b32_e32 v112, 16, v14
	v_and_b32_e32 v113, 0xffff0000, v14
	v_lshlrev_b32_e32 v114, 16, v15
	v_and_b32_e32 v115, 0xffff0000, v15
	v_lshlrev_b32_e32 v124, 16, v16
	v_and_b32_e32 v125, 0xffff0000, v16
	v_lshlrev_b32_e32 v126, 16, v17
	v_and_b32_e32 v127, 0xffff0000, v17
	v_lshlrev_b32_e32 v128, 16, v18
	v_and_b32_e32 v129, 0xffff0000, v18
	v_lshlrev_b32_e32 v130, 16, v19
	v_and_b32_e32 v131, 0xffff0000, v19
	v_cndmask_b32_e64 v124, 0, v124, s[40:41]
	v_cndmask_b32_e64 v125, 0, v125, s[40:41]
	v_cndmask_b32_e64 v126, 0, v126, s[40:41]
	v_cndmask_b32_e64 v127, 0, v127, s[40:41]
	v_cndmask_b32_e64 v128, 0, v128, s[40:41]
	v_cndmask_b32_e64 v129, 0, v129, s[40:41]
	v_cndmask_b32_e64 v130, 0, v130, s[40:41]
	v_cndmask_b32_e64 v131, 0, v131, s[40:41]
	global_load_dwordx4 v[12:15], v11, s[38:39] offset:768
	global_load_dwordx4 v[16:19], v11, s[48:49] offset:768
	v_mov_b32_e32 v116, v108
	v_mov_b32_e32 v117, v109
	v_mov_b32_e32 v118, v110
	v_mov_b32_e32 v119, v111
	v_mov_b32_e32 v120, v112
	v_mov_b32_e32 v121, v113
	v_mov_b32_e32 v122, v114
	v_mov_b32_e32 v123, v115
	v_add_f32_dpp v132, v116, v116 row_shr:1 row_mask:0xf bank_mask:0xf bound_ctrl:1
	v_add_f32_dpp v116, v124, v132 row_shl:15 row_mask:0xf bank_mask:0xf bound_ctrl:1
	v_add_f32_dpp v124, v124, v124 row_shr:1 row_mask:0xf bank_mask:0xf bound_ctrl:1
	v_add_f32_dpp v132, v117, v117 row_shr:1 row_mask:0xf bank_mask:0xf bound_ctrl:1
	v_add_f32_dpp v117, v125, v132 row_shl:15 row_mask:0xf bank_mask:0xf bound_ctrl:1
	v_add_f32_dpp v125, v125, v125 row_shr:1 row_mask:0xf bank_mask:0xf bound_ctrl:1
	v_add_f32_dpp v132, v118, v118 row_shr:1 row_mask:0xf bank_mask:0xf bound_ctrl:1
	v_add_f32_dpp v118, v126, v132 row_shl:15 row_mask:0xf bank_mask:0xf bound_ctrl:1
	v_add_f32_dpp v126, v126, v126 row_shr:1 row_mask:0xf bank_mask:0xf bound_ctrl:1
	v_add_f32_dpp v132, v119, v119 row_shr:1 row_mask:0xf bank_mask:0xf bound_ctrl:1
	v_add_f32_dpp v119, v127, v132 row_shl:15 row_mask:0xf bank_mask:0xf bound_ctrl:1
	v_add_f32_dpp v127, v127, v127 row_shr:1 row_mask:0xf bank_mask:0xf bound_ctrl:1
	v_add_f32_dpp v132, v120, v120 row_shr:1 row_mask:0xf bank_mask:0xf bound_ctrl:1
	v_add_f32_dpp v120, v128, v132 row_shl:15 row_mask:0xf bank_mask:0xf bound_ctrl:1
	v_add_f32_dpp v128, v128, v128 row_shr:1 row_mask:0xf bank_mask:0xf bound_ctrl:1
	v_add_f32_dpp v132, v121, v121 row_shr:1 row_mask:0xf bank_mask:0xf bound_ctrl:1
	v_add_f32_dpp v121, v129, v132 row_shl:15 row_mask:0xf bank_mask:0xf bound_ctrl:1
	v_add_f32_dpp v129, v129, v129 row_shr:1 row_mask:0xf bank_mask:0xf bound_ctrl:1
	v_add_f32_dpp v132, v122, v122 row_shr:1 row_mask:0xf bank_mask:0xf bound_ctrl:1
	v_add_f32_dpp v122, v130, v132 row_shl:15 row_mask:0xf bank_mask:0xf bound_ctrl:1
	v_add_f32_dpp v130, v130, v130 row_shr:1 row_mask:0xf bank_mask:0xf bound_ctrl:1
	v_add_f32_dpp v132, v123, v123 row_shr:1 row_mask:0xf bank_mask:0xf bound_ctrl:1
	v_add_f32_dpp v123, v131, v132 row_shl:15 row_mask:0xf bank_mask:0xf bound_ctrl:1
	v_add_f32_dpp v131, v131, v131 row_shr:1 row_mask:0xf bank_mask:0xf bound_ctrl:1
; #define GAS __attribute__((address_space(1)))
; __device__ __forceinline__ void unpack8(const v4u w, float (&f)[8]) { f[0] = bf_lo(w.x); f[1] = bf_hi(w.x); f[2] = bf_lo(w.y); f[3] = bf_hi(w.y); f[4] = bf_lo(w.z); f[5] = bf_hi(w.z); f[6] = bf_lo(w.w); f[7] = bf_hi(w.w); }
; __device__ __forceinline__ v4u pack8(const float (&f)[8]) { v4u w; w.x = cvt_pk_bf16(f[0], f[1]); w.y = cvt_pk_bf16(f[2], f[3]); w.z = cvt_pk_bf16(f[4], f[5]); w.w = cvt_pk_bf16(f[6], f[7]); return w; }
; template <int SH> __device__ __forceinline__ float row_shr(float v) { return __int_as_float(__builtin_amdgcn_update_dpp(0, __float_as_int(v), 0x110 + SH, 0xf, 0xf, true)); }
; template <int SH> __device__ __forceinline__ float row_shl(float v) { return __int_as_float(__builtin_amdgcn_update_dpp(0, __float_as_int(v), 0x100 + SH, 0xf, 0xf, true)); }
; template <int S> __device__ __forceinline__ void win_step(float (&c)[8], float (&p)[8]) {
; #pragma unroll
;     for (int j = 0; j < 8; ++j) { const float cn = c[j] + row_shr<S>(c[j]) + row_shl<16 - S>(p[j]); p[j] += row_shr<S>(p[j]); c[j] = cn; }
; }
; template <int W> __device__ __forceinline__ void pool_group(const bf16* zrow  , const bf16* pw  , bf16* orow  , int pos, bool prev_ok) {
;     ...
;     for (int kk = 0; kk < 4; ++kk) {
;         if (kk < 3) {
; #pragma unroll
;             for (int dt = 0; dt < 8; ++dt) aw[(kk + 1) & 1][dt] = *(const GAS v4u*)(pw + (size_t)16 * dt * 128 + 32 * (kk + 1)); }
;         float own[8], c[8], p[8];
;         unpack8(cw[kk], own); unpack8(pv[kk], p);
; #pragma unroll
;         for (int j = 0; j < 8; ++j) c[j] = own[j];
;         win_step<1>(c, p);
;         if (W >= 4) win_step<2>(c, p);
;         if (W >= 8) win_step<4>(c, p);
;         if (W >= 16) win_step<8>(c, p);
;         float pl[8];
; #pragma unroll
;         for (int j = 0; j < 8; ++j) pl[j] = c[j] * inv - own[j];
;         const v4u pwk = pack8(pl); const bf16x8 pf = __builtin_bit_cast(bf16x8, pwk);
; #pragma unroll
;         for (int dt = 0; dt < 8; ++dt) acc[dt] = __builtin_amdgcn_mfma_f32_16x16x32_bf16(__builtin_bit_cast(bf16x8, aw[kk & 1][dt]), pf, acc[dt], 0, 0, 0);
	v_add_f32_dpp v132, v116, v116 row_shr:2 row_mask:0xf bank_mask:0xf bound_ctrl:1
	v_add_f32_dpp v116, v124, v132 row_shl:14 row_mask:0xf bank_mask:0xf bound_ctrl:1
	v_add_f32_dpp v124, v124, v124 row_shr:2 row_mask:0xf bank_mask:0xf bound_ctrl:1
	v_add_f32_dpp v132, v117, v117 row_shr:2 row_mask:0xf bank_mask:0xf bound_ctrl:1
	v_add_f32_dpp v117, v125, v132 row_shl:14 row_mask:0xf bank_mask:0xf bound_ctrl:1
	v_add_f32_dpp v125, v125, v125 row_shr:2 row_mask:0xf bank_mask:0xf bound_ctrl:1
	v_add_f32_dpp v132, v118, v118 row_shr:2 row_mask:0xf bank_mask:0xf bound_ctrl:1
	v_add_f32_dpp v118, v126, v132 row_shl:14 row_mask:0xf bank_mask:0xf bound_ctrl:1
	v_add_f32_dpp v126, v126, v126 row_shr:2 row_mask:0xf bank_mask:0xf bound_ctrl:1
	v_add_f32_dpp v132, v119, v119 row_shr:2 row_mask:0xf bank_mask:0xf bound_ctrl:1
	v_add_f32_dpp v119, v127, v132 row_shl:14 row_mask:0xf bank_mask:0xf bound_ctrl:1
	v_add_f32_dpp v127, v127, v127 row_shr:2 row_mask:0xf bank_mask:0xf bound_ctrl:1
	v_add_f32_dpp v132, v120, v120 row_shr:2 row_mask:0xf bank_mask:0xf bound_ctrl:1
	v_add_f32_dpp v120, v128, v132 row_shl:14 row_mask:0xf bank_mask:0xf bound_ctrl:1
	v_add_f32_dpp v128, v128, v128 row_shr:2 row_mask:0xf bank_mask:0xf bound_ctrl:1
	v_add_f32_dpp v132, v121, v121 row_shr:2 row_mask:0xf bank_mask:0xf bound_ctrl:1
	v_add_f32_dpp v121, v129, v132 row_shl:14 row_mask:0xf bank_mask:0xf bound_ctrl:1
	v_add_f32_dpp v129, v129, v129 row_shr:2 row_mask:0xf bank_mask:0xf bound_ctrl:1
	v_add_f32_dpp v132, v122, v122 row_shr:2 row_mask:0xf bank_mask:0xf bound_ctrl:1
	v_add_f32_dpp v122, v130, v132 row_shl:14 row_mask:0xf bank_mask:0xf bound_ctrl:1
	v_add_f32_dpp v130, v130, v130 row_shr:2 row_mask:0xf bank_mask:0xf bound_ctrl:1
	v_add_f32_dpp v132, v123, v123 row_shr:2 row_mask:0xf bank_mask:0xf bound_ctrl:1
	v_add_f32_dpp v123, v131, v132 row_shl:14 row_mask:0xf bank_mask:0xf bound_ctrl:1
	v_add_f32_dpp v131, v131, v131 row_shr:2 row_mask:0xf bank_mask:0xf bound_ctrl:1
	v_add_f32_dpp v132, v116, v116 row_shr:4 row_mask:0xf bank_mask:0xf bound_ctrl:1
	v_add_f32_dpp v116, v124, v132 row_shl:12 row_mask:0xf bank_mask:0xf bound_ctrl:1
	v_add_f32_dpp v124, v124, v124 row_shr:4 row_mask:0xf bank_mask:0xf bound_ctrl:1
	v_add_f32_dpp v132, v117, v117 row_shr:4 row_mask:0xf bank_mask:0xf bound_ctrl:1
	v_add_f32_dpp v117, v125, v132 row_shl:12 row_mask:0xf bank_mask:0xf bound_ctrl:1
	v_add_f32_dpp v125, v125, v125 row_shr:4 row_mask:0xf bank_mask:0xf bound_ctrl:1
	v_add_f32_dpp v132, v118, v118 row_shr:4 row_mask:0xf bank_mask:0xf bound_ctrl:1
	v_add_f32_dpp v118, v126, v132 row_shl:12 row_mask:0xf bank_mask:0xf bound_ctrl:1
	v_add_f32_dpp v126, v126, v126 row_shr:4 row_mask:0xf bank_mask:0xf bound_ctrl:1
	v_add_f32_dpp v132, v119, v119 row_shr:4 row_mask:0xf bank_mask:0xf bound_ctrl:1
	v_add_f32_dpp v119, v127, v132 row_shl:12 row_mask:0xf bank_mask:0xf bound_ctrl:1
	v_add_f32_dpp v127, v127, v127 row_shr:4 row_mask:0xf bank_mask:0xf bound_ctrl:1
	v_add_f32_dpp v132, v120, v120 row_shr:4 row_mask:0xf bank_mask:0xf bound_ctrl:1
	v_add_f32_dpp v120, v128, v132 row_shl:12 row_mask:0xf bank_mask:0xf bound_ctrl:1
	v_add_f32_dpp v128, v128, v128 row_shr:4 row_mask:0xf bank_mask:0xf bound_ctrl:1
	v_add_f32_dpp v132, v121, v121 row_shr:4 row_mask:0xf bank_mask:0xf bound_ctrl:1
	v_add_f32_dpp v121, v129, v132 row_shl:12 row_mask:0xf bank_mask:0xf bound_ctrl:1
	v_add_f32_dpp v129, v129, v129 row_shr:4 row_mask:0xf bank_mask:0xf bound_ctrl:1
	v_add_f32_dpp v132, v122, v122 row_shr:4 row_mask:0xf bank_mask:0xf bound_ctrl:1
	v_add_f32_dpp v122, v130, v132 row_shl:12 row_mask:0xf bank_mask:0xf bound_ctrl:1
	v_add_f32_dpp v130, v130, v130 row_shr:4 row_mask:0xf bank_mask:0xf bound_ctrl:1
	v_add_f32_dpp v132, v123, v123 row_shr:4 row_mask:0xf bank_mask:0xf bound_ctrl:1
	v_add_f32_dpp v123, v131, v132 row_shl:12 row_mask:0xf bank_mask:0xf bound_ctrl:1
	v_add_f32_dpp v131, v131, v131 row_shr:4 row_mask:0xf bank_mask:0xf bound_ctrl:1
	v_fma_f32 v116, v116, v138, -v108
	v_fma_f32 v117, v117, v138, -v109
	v_fma_f32 v118, v118, v138, -v110
	v_fma_f32 v119, v119, v138, -v111
	v_fma_f32 v120, v120, v138, -v112
	v_fma_f32 v121, v121, v138, -v113
	v_fma_f32 v122, v122, v138, -v114
	v_fma_f32 v123, v123, v138, -v115
	v_cvt_pk_bf16_f32 v134, v116, v117
	v_cvt_pk_bf16_f32 v135, v118, v119
	v_cvt_pk_bf16_f32 v136, v120, v121
	v_cvt_pk_bf16_f32 v137, v122, v123
	s_waitcnt lgkmcnt(0)
	s_nop 0
	v_mfma_f32_16x16x32_bf16 v[76:79], v[44:47], v[134:137], 0
	v_mfma_f32_16x16x32_bf16 v[80:83], v[48:51], v[134:137], 0
	v_mfma_f32_16x16x32_bf16 v[84:87], v[52:55], v[134:137], 0
	v_mfma_f32_16x16x32_bf16 v[88:91], v[56:59], v[134:137], 0
	v_mfma_f32_16x16x32_bf16 v[92:95], v[60:63], v[134:137], 0
	v_mfma_f32_16x16x32_bf16 v[96:99], v[64:67], v[134:137], 0
	v_mfma_f32_16x16x32_bf16 v[100:103], v[68:71], v[134:137], 0
	v_mfma_f32_16x16x32_bf16 v[104:107], v[72:75], v[134:137], 0
	v_add_u32_e32 v147, 65536, v144
	ds_read_b128 v[44:47], v147
	ds_read_b128 v[48:51], v147 offset:4096
	ds_read_b128 v[52:55], v147 offset:8192
	ds_read_b128 v[56:59], v147 offset:12288
	ds_read_b128 v[60:63], v147 offset:16384
	ds_read_b128 v[64:67], v147 offset:20480
	ds_read_b128 v[68:71], v147 offset:24576
	ds_read_b128 v[72:75], v147 offset:28672
	s_waitcnt vmcnt(14)
; #define GAS __attribute__((address_space(1)))
; __device__ __forceinline__ void unpack8(const v4u w, float (&f)[8]) { f[0] = bf_lo(w.x); f[1] = bf_hi(w.x); f[2] = bf_lo(w.y); f[3] = bf_hi(w.y); f[4] = bf_lo(w.z); f[5] = bf_hi(w.z); f[6] = bf_lo(w.w); f[7] = bf_hi(w.w); }
; __device__ __forceinline__ v4u pack8(const float (&f)[8]) { v4u w; w.x = cvt_pk_bf16(f[0], f[1]); w.y = cvt_pk_bf16(f[2], f[3]); w.z = cvt_pk_bf16(f[4], f[5]); w.w = cvt_pk_bf16(f[6], f[7]); return w; }
; template <int SH> __device__ __forceinline__ float row_shr(float v) { return __int_as_float(__builtin_amdgcn_update_dpp(0, __float_as_int(v), 0x110 + SH, 0xf, 0xf, true)); }
; template <int SH> __device__ __forceinline__ float row_shl(float v) { return __int_as_float(__builtin_amdgcn_update_dpp(0, __float_as_int(v), 0x100 + SH, 0xf, 0xf, true)); }
; template <int S> __device__ __forceinline__ void win_step(float (&c)[8], float (&p)[8]) {
; #pragma unroll
;     for (int j = 0; j < 8; ++j) { const float cn = c[j] + row_shr<S>(c[j]) + row_shl<16 - S>(p[j]); p[j] += row_shr<S>(p[j]); c[j] = cn; }
; }
; template <int W> __device__ __forceinline__ void pool_group(const bf16* zrow  , const bf16* pw  , bf16* orow  , int pos, bool prev_ok) {
;     ...
;     for (int kk = 0; kk < 4; ++kk) {
;         if (kk < 3) {
; #pragma unroll
;             for (int dt = 0; dt < 8; ++dt) aw[(kk + 1) & 1][dt] = *(const GAS v4u*)(pw + (size_t)16 * dt * 128 + 32 * (kk + 1)); }
;         float own[8], c[8], p[8];
;         unpack8(cw[kk], own); unpack8(pv[kk], p);
; #pragma unroll
;         for (int j = 0; j < 8; ++j) c[j] = own[j];
;         win_step<1>(c, p);
;         if (W >= 4) win_step<2>(c, p);
;         if (W >= 8) win_step<4>(c, p);
;         if (W >= 16) win_step<8>(c, p);
;         float pl[8];
; #pragma unroll
;         for (int j = 0; j < 8; ++j) pl[j] = c[j] * inv - own[j];
;         const v4u pwk = pack8(pl); const bf16x8 pf = __builtin_bit_cast(bf16x8, pwk);
; #pragma unroll
;         for (int dt = 0; dt < 8; ++dt) acc[dt] = __builtin_amdgcn_mfma_f32_16x16x32_bf16(__builtin_bit_cast(bf16x8, aw[kk & 1][dt]), pf, acc[dt], 0, 0, 0);
	v_lshlrev_b32_e32 v108, 16, v20
	v_and_b32_e32 v109, 0xffff0000, v20
	v_lshlrev_b32_e32 v110, 16, v21
	v_and_b32_e32 v111, 0xffff0000, v21
	v_lshlrev_b32_e32 v112, 16, v22
	v_and_b32_e32 v113, 0xffff0000, v22
	v_lshlrev_b32_e32 v114, 16, v23
	v_and_b32_e32 v115, 0xffff0000, v23
	v_lshlrev_b32_e32 v124, 16, v24
	v_and_b32_e32 v125, 0xffff0000, v24
	v_lshlrev_b32_e32 v126, 16, v25
	v_and_b32_e32 v127, 0xffff0000, v25
	v_lshlrev_b32_e32 v128, 16, v26
	v_and_b32_e32 v129, 0xffff0000, v26
	v_lshlrev_b32_e32 v130, 16, v27
	v_and_b32_e32 v131, 0xffff0000, v27
	v_cndmask_b32_e64 v124, 0, v124, s[40:41]
	v_cndmask_b32_e64 v125, 0, v125, s[40:41]
	v_cndmask_b32_e64 v126, 0, v126, s[40:41]
	v_cndmask_b32_e64 v127, 0, v127, s[40:41]
	v_cndmask_b32_e64 v128, 0, v128, s[40:41]
	v_cndmask_b32_e64 v129, 0, v129, s[40:41]
	v_cndmask_b32_e64 v130, 0, v130, s[40:41]
	v_cndmask_b32_e64 v131, 0, v131, s[40:41]
	global_load_dwordx4 v[20:23], v11, s[38:39] offset:832
	global_load_dwordx4 v[24:27], v11, s[48:49] offset:832
	v_mov_b32_e32 v116, v108
	v_mov_b32_e32 v117, v109
	v_mov_b32_e32 v118, v110
	v_mov_b32_e32 v119, v111
	v_mov_b32_e32 v120, v112
	v_mov_b32_e32 v121, v113
	v_mov_b32_e32 v122, v114
	v_mov_b32_e32 v123, v115
	v_add_f32_dpp v132, v116, v116 row_shr:1 row_mask:0xf bank_mask:0xf bound_ctrl:1
	v_add_f32_dpp v116, v124, v132 row_shl:15 row_mask:0xf bank_mask:0xf bound_ctrl:1
	v_add_f32_dpp v124, v124, v124 row_shr:1 row_mask:0xf bank_mask:0xf bound_ctrl:1
	v_add_f32_dpp v132, v117, v117 row_shr:1 row_mask:0xf bank_mask:0xf bound_ctrl:1
	v_add_f32_dpp v117, v125, v132 row_shl:15 row_mask:0xf bank_mask:0xf bound_ctrl:1
	v_add_f32_dpp v125, v125, v125 row_shr:1 row_mask:0xf bank_mask:0xf bound_ctrl:1
	v_add_f32_dpp v132, v118, v118 row_shr:1 row_mask:0xf bank_mask:0xf bound_ctrl:1
	v_add_f32_dpp v118, v126, v132 row_shl:15 row_mask:0xf bank_mask:0xf bound_ctrl:1
	v_add_f32_dpp v126, v126, v126 row_shr:1 row_mask:0xf bank_mask:0xf bound_ctrl:1
	v_add_f32_dpp v132, v119, v119 row_shr:1 row_mask:0xf bank_mask:0xf bound_ctrl:1
	v_add_f32_dpp v119, v127, v132 row_shl:15 row_mask:0xf bank_mask:0xf bound_ctrl:1
	v_add_f32_dpp v127, v127, v127 row_shr:1 row_mask:0xf bank_mask:0xf bound_ctrl:1
	v_add_f32_dpp v132, v120, v120 row_shr:1 row_mask:0xf bank_mask:0xf bound_ctrl:1
	v_add_f32_dpp v120, v128, v132 row_shl:15 row_mask:0xf bank_mask:0xf bound_ctrl:1
	v_add_f32_dpp v128, v128, v128 row_shr:1 row_mask:0xf bank_mask:0xf bound_ctrl:1
	v_add_f32_dpp v132, v121, v121 row_shr:1 row_mask:0xf bank_mask:0xf bound_ctrl:1
	v_add_f32_dpp v121, v129, v132 row_shl:15 row_mask:0xf bank_mask:0xf bound_ctrl:1
	v_add_f32_dpp v129, v129, v129 row_shr:1 row_mask:0xf bank_mask:0xf bound_ctrl:1
	v_add_f32_dpp v132, v122, v122 row_shr:1 row_mask:0xf bank_mask:0xf bound_ctrl:1
	v_add_f32_dpp v122, v130, v132 row_shl:15 row_mask:0xf bank_mask:0xf bound_ctrl:1
	v_add_f32_dpp v130, v130, v130 row_shr:1 row_mask:0xf bank_mask:0xf bound_ctrl:1
	v_add_f32_dpp v132, v123, v123 row_shr:1 row_mask:0xf bank_mask:0xf bound_ctrl:1
	v_add_f32_dpp v123, v131, v132 row_shl:15 row_mask:0xf bank_mask:0xf bound_ctrl:1
	v_add_f32_dpp v131, v131, v131 row_shr:1 row_mask:0xf bank_mask:0xf bound_ctrl:1
	v_add_f32_dpp v132, v116, v116 row_shr:2 row_mask:0xf bank_mask:0xf bound_ctrl:1
	v_add_f32_dpp v116, v124, v132 row_shl:14 row_mask:0xf bank_mask:0xf bound_ctrl:1
	v_add_f32_dpp v124, v124, v124 row_shr:2 row_mask:0xf bank_mask:0xf bound_ctrl:1
	v_add_f32_dpp v132, v117, v117 row_shr:2 row_mask:0xf bank_mask:0xf bound_ctrl:1
	v_add_f32_dpp v117, v125, v132 row_shl:14 row_mask:0xf bank_mask:0xf bound_ctrl:1
	v_add_f32_dpp v125, v125, v125 row_shr:2 row_mask:0xf bank_mask:0xf bound_ctrl:1
	v_add_f32_dpp v132, v118, v118 row_shr:2 row_mask:0xf bank_mask:0xf bound_ctrl:1
	v_add_f32_dpp v118, v126, v132 row_shl:14 row_mask:0xf bank_mask:0xf bound_ctrl:1
	v_add_f32_dpp v126, v126, v126 row_shr:2 row_mask:0xf bank_mask:0xf bound_ctrl:1
	v_add_f32_dpp v132, v119, v119 row_shr:2 row_mask:0xf bank_mask:0xf bound_ctrl:1
	v_add_f32_dpp v119, v127, v132 row_shl:14 row_mask:0xf bank_mask:0xf bound_ctrl:1
	v_add_f32_dpp v127, v127, v127 row_shr:2 row_mask:0xf bank_mask:0xf bound_ctrl:1
	v_add_f32_dpp v132, v120, v120 row_shr:2 row_mask:0xf bank_mask:0xf bound_ctrl:1
	v_add_f32_dpp v120, v128, v132 row_shl:14 row_mask:0xf bank_mask:0xf bound_ctrl:1
	v_add_f32_dpp v128, v128, v128 row_shr:2 row_mask:0xf bank_mask:0xf bound_ctrl:1
	v_add_f32_dpp v132, v121, v121 row_shr:2 row_mask:0xf bank_mask:0xf bound_ctrl:1
	v_add_f32_dpp v121, v129, v132 row_shl:14 row_mask:0xf bank_mask:0xf bound_ctrl:1
	v_add_f32_dpp v129, v129, v129 row_shr:2 row_mask:0xf bank_mask:0xf bound_ctrl:1
	v_add_f32_dpp v132, v122, v122 row_shr:2 row_mask:0xf bank_mask:0xf bound_ctrl:1
	v_add_f32_dpp v122, v130, v132 row_shl:14 row_mask:0xf bank_mask:0xf bound_ctrl:1
	v_add_f32_dpp v130, v130, v130 row_shr:2 row_mask:0xf bank_mask:0xf bound_ctrl:1
	v_add_f32_dpp v132, v123, v123 row_shr:2 row_mask:0xf bank_mask:0xf bound_ctrl:1
	v_add_f32_dpp v123, v131, v132 row_shl:14 row_mask:0xf bank_mask:0xf bound_ctrl:1
	v_add_f32_dpp v131, v131, v131 row_shr:2 row_mask:0xf bank_mask:0xf bound_ctrl:1
	v_add_f32_dpp v132, v116, v116 row_shr:4 row_mask:0xf bank_mask:0xf bound_ctrl:1
	v_add_f32_dpp v116, v124, v132 row_shl:12 row_mask:0xf bank_mask:0xf bound_ctrl:1
	v_add_f32_dpp v124, v124, v124 row_shr:4 row_mask:0xf bank_mask:0xf bound_ctrl:1
	v_add_f32_dpp v132, v117, v117 row_shr:4 row_mask:0xf bank_mask:0xf bound_ctrl:1
	v_add_f32_dpp v117, v125, v132 row_shl:12 row_mask:0xf bank_mask:0xf bound_ctrl:1
	v_add_f32_dpp v125, v125, v125 row_shr:4 row_mask:0xf bank_mask:0xf bound_ctrl:1
; #define GAS __attribute__((address_space(1)))
; __device__ __forceinline__ void unpack8(const v4u w, float (&f)[8]) { f[0] = bf_lo(w.x); f[1] = bf_hi(w.x); f[2] = bf_lo(w.y); f[3] = bf_hi(w.y); f[4] = bf_lo(w.z); f[5] = bf_hi(w.z); f[6] = bf_lo(w.w); f[7] = bf_hi(w.w); }
; __device__ __forceinline__ v4u pack8(const float (&f)[8]) { v4u w; w.x = cvt_pk_bf16(f[0], f[1]); w.y = cvt_pk_bf16(f[2], f[3]); w.z = cvt_pk_bf16(f[4], f[5]); w.w = cvt_pk_bf16(f[6], f[7]); return w; }
; template <int SH> __device__ __forceinline__ float row_shr(float v) { return __int_as_float(__builtin_amdgcn_update_dpp(0, __float_as_int(v), 0x110 + SH, 0xf, 0xf, true)); }
; template <int SH> __device__ __forceinline__ float row_shl(float v) { return __int_as_float(__builtin_amdgcn_update_dpp(0, __float_as_int(v), 0x100 + SH, 0xf, 0xf, true)); }
; template <int S> __device__ __forceinline__ void win_step(float (&c)[8], float (&p)[8]) {
; #pragma unroll
;     for (int j = 0; j < 8; ++j) { const float cn = c[j] + row_shr<S>(c[j]) + row_shl<16 - S>(p[j]); p[j] += row_shr<S>(p[j]); c[j] = cn; }
; }
; template <int W> __device__ __forceinline__ void pool_group(const bf16* zrow  , const bf16* pw  , bf16* orow  , int pos, bool prev_ok) {
;     ...
;     for (int kk = 0; kk < 4; ++kk) {
;         if (kk < 3) {
; #pragma unroll
;             for (int dt = 0; dt < 8; ++dt) aw[(kk + 1) & 1][dt] = *(const GAS v4u*)(pw + (size_t)16 * dt * 128 + 32 * (kk + 1)); }
;         float own[8], c[8], p[8];
;         unpack8(cw[kk], own); unpack8(pv[kk], p);
; #pragma unroll
;         for (int j = 0; j < 8; ++j) c[j] = own[j];
;         win_step<1>(c, p);
;         if (W >= 4) win_step<2>(c, p);
;         if (W >= 8) win_step<4>(c, p);
;         if (W >= 16) win_step<8>(c, p);
;         float pl[8];
; #pragma unroll
;         for (int j = 0; j < 8; ++j) pl[j] = c[j] * inv - own[j];
;         const v4u pwk = pack8(pl); const bf16x8 pf = __builtin_bit_cast(bf16x8, pwk);
; #pragma unroll
;         for (int dt = 0; dt < 8; ++dt) acc[dt] = __builtin_amdgcn_mfma_f32_16x16x32_bf16(__builtin_bit_cast(bf16x8, aw[kk & 1][dt]), pf, acc[dt], 0, 0, 0);
	v_add_f32_dpp v132, v118, v118 row_shr:4 row_mask:0xf bank_mask:0xf bound_ctrl:1
	v_add_f32_dpp v118, v126, v132 row_shl:12 row_mask:0xf bank_mask:0xf bound_ctrl:1
	v_add_f32_dpp v126, v126, v126 row_shr:4 row_mask:0xf bank_mask:0xf bound_ctrl:1
	v_add_f32_dpp v132, v119, v119 row_shr:4 row_mask:0xf bank_mask:0xf bound_ctrl:1
	v_add_f32_dpp v119, v127, v132 row_shl:12 row_mask:0xf bank_mask:0xf bound_ctrl:1
	v_add_f32_dpp v127, v127, v127 row_shr:4 row_mask:0xf bank_mask:0xf bound_ctrl:1
	v_add_f32_dpp v132, v120, v120 row_shr:4 row_mask:0xf bank_mask:0xf bound_ctrl:1
	v_add_f32_dpp v120, v128, v132 row_shl:12 row_mask:0xf bank_mask:0xf bound_ctrl:1
	v_add_f32_dpp v128, v128, v128 row_shr:4 row_mask:0xf bank_mask:0xf bound_ctrl:1
	v_add_f32_dpp v132, v121, v121 row_shr:4 row_mask:0xf bank_mask:0xf bound_ctrl:1
	v_add_f32_dpp v121, v129, v132 row_shl:12 row_mask:0xf bank_mask:0xf bound_ctrl:1
	v_add_f32_dpp v129, v129, v129 row_shr:4 row_mask:0xf bank_mask:0xf bound_ctrl:1
	v_add_f32_dpp v132, v122, v122 row_shr:4 row_mask:0xf bank_mask:0xf bound_ctrl:1
	v_add_f32_dpp v122, v130, v132 row_shl:12 row_mask:0xf bank_mask:0xf bound_ctrl:1
	v_add_f32_dpp v130, v130, v130 row_shr:4 row_mask:0xf bank_mask:0xf bound_ctrl:1
	v_add_f32_dpp v132, v123, v123 row_shr:4 row_mask:0xf bank_mask:0xf bound_ctrl:1
	v_add_f32_dpp v123, v131, v132 row_shl:12 row_mask:0xf bank_mask:0xf bound_ctrl:1
	v_add_f32_dpp v131, v131, v131 row_shr:4 row_mask:0xf bank_mask:0xf bound_ctrl:1
	v_fma_f32 v116, v116, v138, -v108
	v_fma_f32 v117, v117, v138, -v109
	v_fma_f32 v118, v118, v138, -v110
	v_fma_f32 v119, v119, v138, -v111
	v_fma_f32 v120, v120, v138, -v112
	v_fma_f32 v121, v121, v138, -v113
	v_fma_f32 v122, v122, v138, -v114
	v_fma_f32 v123, v123, v138, -v115
	v_cvt_pk_bf16_f32 v134, v116, v117
	v_cvt_pk_bf16_f32 v135, v118, v119
	v_cvt_pk_bf16_f32 v136, v120, v121
	v_cvt_pk_bf16_f32 v137, v122, v123
	s_waitcnt lgkmcnt(0)
	s_nop 0
	v_mfma_f32_16x16x32_bf16 v[76:79], v[44:47], v[134:137], v[76:79]
	v_mfma_f32_16x16x32_bf16 v[80:83], v[48:51], v[134:137], v[80:83]
	v_mfma_f32_16x16x32_bf16 v[84:87], v[52:55], v[134:137], v[84:87]
	v_mfma_f32_16x16x32_bf16 v[88:91], v[56:59], v[134:137], v[88:91]
	v_mfma_f32_16x16x32_bf16 v[92:95], v[60:63], v[134:137], v[92:95]
	v_mfma_f32_16x16x32_bf16 v[96:99], v[64:67], v[134:137], v[96:99]
	v_mfma_f32_16x16x32_bf16 v[100:103], v[68:71], v[134:137], v[100:103]
	v_mfma_f32_16x16x32_bf16 v[104:107], v[72:75], v[134:137], v[104:107]
	v_add_u32_e32 v147, 65536, v145
	ds_read_b128 v[44:47], v147
	ds_read_b128 v[48:51], v147 offset:4096
	ds_read_b128 v[52:55], v147 offset:8192
	ds_read_b128 v[56:59], v147 offset:12288
	ds_read_b128 v[60:63], v147 offset:16384
	ds_read_b128 v[64:67], v147 offset:20480
	ds_read_b128 v[68:71], v147 offset:24576
	ds_read_b128 v[72:75], v147 offset:28672
	s_waitcnt vmcnt(14)
	v_lshlrev_b32_e32 v108, 16, v28
	v_and_b32_e32 v109, 0xffff0000, v28
	v_lshlrev_b32_e32 v110, 16, v29
	v_and_b32_e32 v111, 0xffff0000, v29
	v_lshlrev_b32_e32 v112, 16, v30
	v_and_b32_e32 v113, 0xffff0000, v30
	v_lshlrev_b32_e32 v114, 16, v31
	v_and_b32_e32 v115, 0xffff0000, v31
	v_lshlrev_b32_e32 v124, 16, v32
	v_and_b32_e32 v125, 0xffff0000, v32
	v_lshlrev_b32_e32 v126, 16, v33
	v_and_b32_e32 v127, 0xffff0000, v33
	v_lshlrev_b32_e32 v128, 16, v34
	v_and_b32_e32 v129, 0xffff0000, v34
	v_lshlrev_b32_e32 v130, 16, v35
	v_and_b32_e32 v131, 0xffff0000, v35
	v_cndmask_b32_e64 v124, 0, v124, s[40:41]
	v_cndmask_b32_e64 v125, 0, v125, s[40:41]
	v_cndmask_b32_e64 v126, 0, v126, s[40:41]
	v_cndmask_b32_e64 v127, 0, v127, s[40:41]
	v_cndmask_b32_e64 v128, 0, v128, s[40:41]
	v_cndmask_b32_e64 v129, 0, v129, s[40:41]
	v_cndmask_b32_e64 v130, 0, v130, s[40:41]
	v_cndmask_b32_e64 v131, 0, v131, s[40:41]
	global_load_dwordx4 v[28:31], v11, s[38:39] offset:896
	global_load_dwordx4 v[32:35], v11, s[48:49] offset:896
	v_mov_b32_e32 v116, v108
	v_mov_b32_e32 v117, v109
	v_mov_b32_e32 v118, v110
	v_mov_b32_e32 v119, v111
	v_mov_b32_e32 v120, v112
	v_mov_b32_e32 v121, v113
	v_mov_b32_e32 v122, v114
	v_mov_b32_e32 v123, v115
	v_add_f32_dpp v132, v116, v116 row_shr:1 row_mask:0xf bank_mask:0xf bound_ctrl:1
	v_add_f32_dpp v116, v124, v132 row_shl:15 row_mask:0xf bank_mask:0xf bound_ctrl:1
	v_add_f32_dpp v124, v124, v124 row_shr:1 row_mask:0xf bank_mask:0xf bound_ctrl:1
	v_add_f32_dpp v132, v117, v117 row_shr:1 row_mask:0xf bank_mask:0xf bound_ctrl:1
	v_add_f32_dpp v117, v125, v132 row_shl:15 row_mask:0xf bank_mask:0xf bound_ctrl:1
	v_add_f32_dpp v125, v125, v125 row_shr:1 row_mask:0xf bank_mask:0xf bound_ctrl:1
	v_add_f32_dpp v132, v118, v118 row_shr:1 row_mask:0xf bank_mask:0xf bound_ctrl:1
	v_add_f32_dpp v118, v126, v132 row_shl:15 row_mask:0xf bank_mask:0xf bound_ctrl:1
	v_add_f32_dpp v126, v126, v126 row_shr:1 row_mask:0xf bank_mask:0xf bound_ctrl:1
	v_add_f32_dpp v132, v119, v119 row_shr:1 row_mask:0xf bank_mask:0xf bound_ctrl:1
	v_add_f32_dpp v119, v127, v132 row_shl:15 row_mask:0xf bank_mask:0xf bound_ctrl:1
	v_add_f32_dpp v127, v127, v127 row_shr:1 row_mask:0xf bank_mask:0xf bound_ctrl:1
	v_add_f32_dpp v132, v120, v120 row_shr:1 row_mask:0xf bank_mask:0xf bound_ctrl:1
	v_add_f32_dpp v120, v128, v132 row_shl:15 row_mask:0xf bank_mask:0xf bound_ctrl:1
	v_add_f32_dpp v128, v128, v128 row_shr:1 row_mask:0xf bank_mask:0xf bound_ctrl:1
	v_add_f32_dpp v132, v121, v121 row_shr:1 row_mask:0xf bank_mask:0xf bound_ctrl:1
	v_add_f32_dpp v121, v129, v132 row_shl:15 row_mask:0xf bank_mask:0xf bound_ctrl:1
	v_add_f32_dpp v129, v129, v129 row_shr:1 row_mask:0xf bank_mask:0xf bound_ctrl:1
	v_add_f32_dpp v132, v122, v122 row_shr:1 row_mask:0xf bank_mask:0xf bound_ctrl:1
; #define GAS __attribute__((address_space(1)))
; __device__ __forceinline__ void unpack8(const v4u w, float (&f)[8]) { f[0] = bf_lo(w.x); f[1] = bf_hi(w.x); f[2] = bf_lo(w.y); f[3] = bf_hi(w.y); f[4] = bf_lo(w.z); f[5] = bf_hi(w.z); f[6] = bf_lo(w.w); f[7] = bf_hi(w.w); }
; __device__ __forceinline__ v4u pack8(const float (&f)[8]) { v4u w; w.x = cvt_pk_bf16(f[0], f[1]); w.y = cvt_pk_bf16(f[2], f[3]); w.z = cvt_pk_bf16(f[4], f[5]); w.w = cvt_pk_bf16(f[6], f[7]); return w; }
; template <int SH> __device__ __forceinline__ float row_shr(float v) { return __int_as_float(__builtin_amdgcn_update_dpp(0, __float_as_int(v), 0x110 + SH, 0xf, 0xf, true)); }
; template <int SH> __device__ __forceinline__ float row_shl(float v) { return __int_as_float(__builtin_amdgcn_update_dpp(0, __float_as_int(v), 0x100 + SH, 0xf, 0xf, true)); }
; template <int S> __device__ __forceinline__ void win_step(float (&c)[8], float (&p)[8]) {
; #pragma unroll
;     for (int j = 0; j < 8; ++j) { const float cn = c[j] + row_shr<S>(c[j]) + row_shl<16 - S>(p[j]); p[j] += row_shr<S>(p[j]); c[j] = cn; }
; }
; template <int W> __device__ __forceinline__ void pool_group(const bf16* zrow  , const bf16* pw  , bf16* orow  , int pos, bool prev_ok) {
;     ...
;     for (int kk = 0; kk < 4; ++kk) {
;         if (kk < 3) {
; #pragma unroll
;             for (int dt = 0; dt < 8; ++dt) aw[(kk + 1) & 1][dt] = *(const GAS v4u*)(pw + (size_t)16 * dt * 128 + 32 * (kk + 1)); }
;         float own[8], c[8], p[8];
;         unpack8(cw[kk], own); unpack8(pv[kk], p);
; #pragma unroll
;         for (int j = 0; j < 8; ++j) c[j] = own[j];
;         win_step<1>(c, p);
;         if (W >= 4) win_step<2>(c, p);
;         if (W >= 8) win_step<4>(c, p);
;         if (W >= 16) win_step<8>(c, p);
;         float pl[8];
; #pragma unroll
;         for (int j = 0; j < 8; ++j) pl[j] = c[j] * inv - own[j];
;         const v4u pwk = pack8(pl); const bf16x8 pf = __builtin_bit_cast(bf16x8, pwk);
; #pragma unroll
;         for (int dt = 0; dt < 8; ++dt) acc[dt] = __builtin_amdgcn_mfma_f32_16x16x32_bf16(__builtin_bit_cast(bf16x8, aw[kk & 1][dt]), pf, acc[dt], 0, 0, 0);
	v_add_f32_dpp v122, v130, v132 row_shl:15 row_mask:0xf bank_mask:0xf bound_ctrl:1
	v_add_f32_dpp v130, v130, v130 row_shr:1 row_mask:0xf bank_mask:0xf bound_ctrl:1
	v_add_f32_dpp v132, v123, v123 row_shr:1 row_mask:0xf bank_mask:0xf bound_ctrl:1
	v_add_f32_dpp v123, v131, v132 row_shl:15 row_mask:0xf bank_mask:0xf bound_ctrl:1
	v_add_f32_dpp v131, v131, v131 row_shr:1 row_mask:0xf bank_mask:0xf bound_ctrl:1
	v_add_f32_dpp v132, v116, v116 row_shr:2 row_mask:0xf bank_mask:0xf bound_ctrl:1
	v_add_f32_dpp v116, v124, v132 row_shl:14 row_mask:0xf bank_mask:0xf bound_ctrl:1
	v_add_f32_dpp v124, v124, v124 row_shr:2 row_mask:0xf bank_mask:0xf bound_ctrl:1
	v_add_f32_dpp v132, v117, v117 row_shr:2 row_mask:0xf bank_mask:0xf bound_ctrl:1
	v_add_f32_dpp v117, v125, v132 row_shl:14 row_mask:0xf bank_mask:0xf bound_ctrl:1
	v_add_f32_dpp v125, v125, v125 row_shr:2 row_mask:0xf bank_mask:0xf bound_ctrl:1
	v_add_f32_dpp v132, v118, v118 row_shr:2 row_mask:0xf bank_mask:0xf bound_ctrl:1
	v_add_f32_dpp v118, v126, v132 row_shl:14 row_mask:0xf bank_mask:0xf bound_ctrl:1
	v_add_f32_dpp v126, v126, v126 row_shr:2 row_mask:0xf bank_mask:0xf bound_ctrl:1
	v_add_f32_dpp v132, v119, v119 row_shr:2 row_mask:0xf bank_mask:0xf bound_ctrl:1
	v_add_f32_dpp v119, v127, v132 row_shl:14 row_mask:0xf bank_mask:0xf bound_ctrl:1
	v_add_f32_dpp v127, v127, v127 row_shr:2 row_mask:0xf bank_mask:0xf bound_ctrl:1
	v_add_f32_dpp v132, v120, v120 row_shr:2 row_mask:0xf bank_mask:0xf bound_ctrl:1
	v_add_f32_dpp v120, v128, v132 row_shl:14 row_mask:0xf bank_mask:0xf bound_ctrl:1
	v_add_f32_dpp v128, v128, v128 row_shr:2 row_mask:0xf bank_mask:0xf bound_ctrl:1
	v_add_f32_dpp v132, v121, v121 row_shr:2 row_mask:0xf bank_mask:0xf bound_ctrl:1
	v_add_f32_dpp v121, v129, v132 row_shl:14 row_mask:0xf bank_mask:0xf bound_ctrl:1
	v_add_f32_dpp v129, v129, v129 row_shr:2 row_mask:0xf bank_mask:0xf bound_ctrl:1
	v_add_f32_dpp v132, v122, v122 row_shr:2 row_mask:0xf bank_mask:0xf bound_ctrl:1
	v_add_f32_dpp v122, v130, v132 row_shl:14 row_mask:0xf bank_mask:0xf bound_ctrl:1
	v_add_f32_dpp v130, v130, v130 row_shr:2 row_mask:0xf bank_mask:0xf bound_ctrl:1
	v_add_f32_dpp v132, v123, v123 row_shr:2 row_mask:0xf bank_mask:0xf bound_ctrl:1
	v_add_f32_dpp v123, v131, v132 row_shl:14 row_mask:0xf bank_mask:0xf bound_ctrl:1
	v_add_f32_dpp v131, v131, v131 row_shr:2 row_mask:0xf bank_mask:0xf bound_ctrl:1
	v_add_f32_dpp v132, v116, v116 row_shr:4 row_mask:0xf bank_mask:0xf bound_ctrl:1
	v_add_f32_dpp v116, v124, v132 row_shl:12 row_mask:0xf bank_mask:0xf bound_ctrl:1
	v_add_f32_dpp v124, v124, v124 row_shr:4 row_mask:0xf bank_mask:0xf bound_ctrl:1
	v_add_f32_dpp v132, v117, v117 row_shr:4 row_mask:0xf bank_mask:0xf bound_ctrl:1
	v_add_f32_dpp v117, v125, v132 row_shl:12 row_mask:0xf bank_mask:0xf bound_ctrl:1
	v_add_f32_dpp v125, v125, v125 row_shr:4 row_mask:0xf bank_mask:0xf bound_ctrl:1
	v_add_f32_dpp v132, v118, v118 row_shr:4 row_mask:0xf bank_mask:0xf bound_ctrl:1
	v_add_f32_dpp v118, v126, v132 row_shl:12 row_mask:0xf bank_mask:0xf bound_ctrl:1
	v_add_f32_dpp v126, v126, v126 row_shr:4 row_mask:0xf bank_mask:0xf bound_ctrl:1
	v_add_f32_dpp v132, v119, v119 row_shr:4 row_mask:0xf bank_mask:0xf bound_ctrl:1
	v_add_f32_dpp v119, v127, v132 row_shl:12 row_mask:0xf bank_mask:0xf bound_ctrl:1
	v_add_f32_dpp v127, v127, v127 row_shr:4 row_mask:0xf bank_mask:0xf bound_ctrl:1
	v_add_f32_dpp v132, v120, v120 row_shr:4 row_mask:0xf bank_mask:0xf bound_ctrl:1
	v_add_f32_dpp v120, v128, v132 row_shl:12 row_mask:0xf bank_mask:0xf bound_ctrl:1
	v_add_f32_dpp v128, v128, v128 row_shr:4 row_mask:0xf bank_mask:0xf bound_ctrl:1
	v_add_f32_dpp v132, v121, v121 row_shr:4 row_mask:0xf bank_mask:0xf bound_ctrl:1
	v_add_f32_dpp v121, v129, v132 row_shl:12 row_mask:0xf bank_mask:0xf bound_ctrl:1
	v_add_f32_dpp v129, v129, v129 row_shr:4 row_mask:0xf bank_mask:0xf bound_ctrl:1
	v_add_f32_dpp v132, v122, v122 row_shr:4 row_mask:0xf bank_mask:0xf bound_ctrl:1
	v_add_f32_dpp v122, v130, v132 row_shl:12 row_mask:0xf bank_mask:0xf bound_ctrl:1
	v_add_f32_dpp v130, v130, v130 row_shr:4 row_mask:0xf bank_mask:0xf bound_ctrl:1
	v_add_f32_dpp v132, v123, v123 row_shr:4 row_mask:0xf bank_mask:0xf bound_ctrl:1
	v_add_f32_dpp v123, v131, v132 row_shl:12 row_mask:0xf bank_mask:0xf bound_ctrl:1
	v_add_f32_dpp v131, v131, v131 row_shr:4 row_mask:0xf bank_mask:0xf bound_ctrl:1
	v_fma_f32 v116, v116, v138, -v108
	v_fma_f32 v117, v117, v138, -v109
	v_fma_f32 v118, v118, v138, -v110
	v_fma_f32 v119, v119, v138, -v111
	v_fma_f32 v120, v120, v138, -v112
	v_fma_f32 v121, v121, v138, -v113
	v_fma_f32 v122, v122, v138, -v114
	v_fma_f32 v123, v123, v138, -v115
	v_cvt_pk_bf16_f32 v134, v116, v117
	v_cvt_pk_bf16_f32 v135, v118, v119
	v_cvt_pk_bf16_f32 v136, v120, v121
	v_cvt_pk_bf16_f32 v137, v122, v123
	s_waitcnt lgkmcnt(0)
	s_nop 0
	v_mfma_f32_16x16x32_bf16 v[76:79], v[44:47], v[134:137], v[76:79]
	v_mfma_f32_16x16x32_bf16 v[80:83], v[48:51], v[134:137], v[80:83]
	v_mfma_f32_16x16x32_bf16 v[84:87], v[52:55], v[134:137], v[84:87]
	v_mfma_f32_16x16x32_bf16 v[88:91], v[56:59], v[134:137], v[88:91]
	v_mfma_f32_16x16x32_bf16 v[92:95], v[60:63], v[134:137], v[92:95]
	v_mfma_f32_16x16x32_bf16 v[96:99], v[64:67], v[134:137], v[96:99]
	v_mfma_f32_16x16x32_bf16 v[100:103], v[68:71], v[134:137], v[100:103]
	v_mfma_f32_16x16x32_bf16 v[104:107], v[72:75], v[134:137], v[104:107]
	v_add_u32_e32 v147, 65536, v146
	ds_read_b128 v[44:47], v147
	ds_read_b128 v[48:51], v147 offset:4096
	ds_read_b128 v[52:55], v147 offset:8192
	ds_read_b128 v[56:59], v147 offset:12288
	ds_read_b128 v[60:63], v147 offset:16384
	ds_read_b128 v[64:67], v147 offset:20480
	ds_read_b128 v[68:71], v147 offset:24576
	ds_read_b128 v[72:75], v147 offset:28672
	s_waitcnt vmcnt(14)
; #define GAS __attribute__((address_space(1)))
; __device__ __forceinline__ void unpack8(const v4u w, float (&f)[8]) { f[0] = bf_lo(w.x); f[1] = bf_hi(w.x); f[2] = bf_lo(w.y); f[3] = bf_hi(w.y); f[4] = bf_lo(w.z); f[5] = bf_hi(w.z); f[6] = bf_lo(w.w); f[7] = bf_hi(w.w); }
; __device__ __forceinline__ v4u pack8(const float (&f)[8]) { v4u w; w.x = cvt_pk_bf16(f[0], f[1]); w.y = cvt_pk_bf16(f[2], f[3]); w.z = cvt_pk_bf16(f[4], f[5]); w.w = cvt_pk_bf16(f[6], f[7]); return w; }
; template <int SH> __device__ __forceinline__ float row_shr(float v) { return __int_as_float(__builtin_amdgcn_update_dpp(0, __float_as_int(v), 0x110 + SH, 0xf, 0xf, true)); }
; template <int SH> __device__ __forceinline__ float row_shl(float v) { return __int_as_float(__builtin_amdgcn_update_dpp(0, __float_as_int(v), 0x100 + SH, 0xf, 0xf, true)); }
; template <int S> __device__ __forceinline__ void win_step(float (&c)[8], float (&p)[8]) {
; #pragma unroll
;     for (int j = 0; j < 8; ++j) { const float cn = c[j] + row_shr<S>(c[j]) + row_shl<16 - S>(p[j]); p[j] += row_shr<S>(p[j]); c[j] = cn; }
; }
; template <int W> __device__ __forceinline__ void pool_group(const bf16* zrow  , const bf16* pw  , bf16* orow  , int pos, bool prev_ok) {
;     ...
;     for (int kk = 0; kk < 4; ++kk) {
;         if (kk < 3) {
; #pragma unroll
;             for (int dt = 0; dt < 8; ++dt) aw[(kk + 1) & 1][dt] = *(const GAS v4u*)(pw + (size_t)16 * dt * 128 + 32 * (kk + 1)); }
;         float own[8], c[8], p[8];
;         unpack8(cw[kk], own); unpack8(pv[kk], p);
; #pragma unroll
;         for (int j = 0; j < 8; ++j) c[j] = own[j];
;         win_step<1>(c, p);
;         if (W >= 4) win_step<2>(c, p);
;         if (W >= 8) win_step<4>(c, p);
;         if (W >= 16) win_step<8>(c, p);
;         float pl[8];
; #pragma unroll
;         for (int j = 0; j < 8; ++j) pl[j] = c[j] * inv - own[j];
;         const v4u pwk = pack8(pl); const bf16x8 pf = __builtin_bit_cast(bf16x8, pwk);
; #pragma unroll
;         for (int dt = 0; dt < 8; ++dt) acc[dt] = __builtin_amdgcn_mfma_f32_16x16x32_bf16(__builtin_bit_cast(bf16x8, aw[kk & 1][dt]), pf, acc[dt], 0, 0, 0);
	v_lshlrev_b32_e32 v108, 16, v36
	v_and_b32_e32 v109, 0xffff0000, v36
	v_lshlrev_b32_e32 v110, 16, v37
	v_and_b32_e32 v111, 0xffff0000, v37
	v_lshlrev_b32_e32 v112, 16, v38
	v_and_b32_e32 v113, 0xffff0000, v38
	v_lshlrev_b32_e32 v114, 16, v39
	v_and_b32_e32 v115, 0xffff0000, v39
	v_lshlrev_b32_e32 v124, 16, v40
	v_and_b32_e32 v125, 0xffff0000, v40
	v_lshlrev_b32_e32 v126, 16, v41
	v_and_b32_e32 v127, 0xffff0000, v41
	v_lshlrev_b32_e32 v128, 16, v42
	v_and_b32_e32 v129, 0xffff0000, v42
	v_lshlrev_b32_e32 v130, 16, v43
	v_and_b32_e32 v131, 0xffff0000, v43
	v_cndmask_b32_e64 v124, 0, v124, s[40:41]
	v_cndmask_b32_e64 v125, 0, v125, s[40:41]
	v_cndmask_b32_e64 v126, 0, v126, s[40:41]
	v_cndmask_b32_e64 v127, 0, v127, s[40:41]
	v_cndmask_b32_e64 v128, 0, v128, s[40:41]
	v_cndmask_b32_e64 v129, 0, v129, s[40:41]
	v_cndmask_b32_e64 v130, 0, v130, s[40:41]
	v_cndmask_b32_e64 v131, 0, v131, s[40:41]
	global_load_dwordx4 v[36:39], v11, s[38:39] offset:960
	global_load_dwordx4 v[40:43], v11, s[48:49] offset:960
	v_mov_b32_e32 v116, v108
	v_mov_b32_e32 v117, v109
	v_mov_b32_e32 v118, v110
	v_mov_b32_e32 v119, v111
	v_mov_b32_e32 v120, v112
	v_mov_b32_e32 v121, v113
	v_mov_b32_e32 v122, v114
	v_mov_b32_e32 v123, v115
	v_add_f32_dpp v132, v116, v116 row_shr:1 row_mask:0xf bank_mask:0xf bound_ctrl:1
	v_add_f32_dpp v116, v124, v132 row_shl:15 row_mask:0xf bank_mask:0xf bound_ctrl:1
	v_add_f32_dpp v124, v124, v124 row_shr:1 row_mask:0xf bank_mask:0xf bound_ctrl:1
	v_add_f32_dpp v132, v117, v117 row_shr:1 row_mask:0xf bank_mask:0xf bound_ctrl:1
	v_add_f32_dpp v117, v125, v132 row_shl:15 row_mask:0xf bank_mask:0xf bound_ctrl:1
	v_add_f32_dpp v125, v125, v125 row_shr:1 row_mask:0xf bank_mask:0xf bound_ctrl:1
	v_add_f32_dpp v132, v118, v118 row_shr:1 row_mask:0xf bank_mask:0xf bound_ctrl:1
	v_add_f32_dpp v118, v126, v132 row_shl:15 row_mask:0xf bank_mask:0xf bound_ctrl:1
	v_add_f32_dpp v126, v126, v126 row_shr:1 row_mask:0xf bank_mask:0xf bound_ctrl:1
	v_add_f32_dpp v132, v119, v119 row_shr:1 row_mask:0xf bank_mask:0xf bound_ctrl:1
	v_add_f32_dpp v119, v127, v132 row_shl:15 row_mask:0xf bank_mask:0xf bound_ctrl:1
	v_add_f32_dpp v127, v127, v127 row_shr:1 row_mask:0xf bank_mask:0xf bound_ctrl:1
	v_add_f32_dpp v132, v120, v120 row_shr:1 row_mask:0xf bank_mask:0xf bound_ctrl:1
	v_add_f32_dpp v120, v128, v132 row_shl:15 row_mask:0xf bank_mask:0xf bound_ctrl:1
	v_add_f32_dpp v128, v128, v128 row_shr:1 row_mask:0xf bank_mask:0xf bound_ctrl:1
	v_add_f32_dpp v132, v121, v121 row_shr:1 row_mask:0xf bank_mask:0xf bound_ctrl:1
	v_add_f32_dpp v121, v129, v132 row_shl:15 row_mask:0xf bank_mask:0xf bound_ctrl:1
	v_add_f32_dpp v129, v129, v129 row_shr:1 row_mask:0xf bank_mask:0xf bound_ctrl:1
	v_add_f32_dpp v132, v122, v122 row_shr:1 row_mask:0xf bank_mask:0xf bound_ctrl:1
	v_add_f32_dpp v122, v130, v132 row_shl:15 row_mask:0xf bank_mask:0xf bound_ctrl:1
	v_add_f32_dpp v130, v130, v130 row_shr:1 row_mask:0xf bank_mask:0xf bound_ctrl:1
	v_add_f32_dpp v132, v123, v123 row_shr:1 row_mask:0xf bank_mask:0xf bound_ctrl:1
	v_add_f32_dpp v123, v131, v132 row_shl:15 row_mask:0xf bank_mask:0xf bound_ctrl:1
	v_add_f32_dpp v131, v131, v131 row_shr:1 row_mask:0xf bank_mask:0xf bound_ctrl:1
	v_add_f32_dpp v132, v116, v116 row_shr:2 row_mask:0xf bank_mask:0xf bound_ctrl:1
	v_add_f32_dpp v116, v124, v132 row_shl:14 row_mask:0xf bank_mask:0xf bound_ctrl:1
	v_add_f32_dpp v124, v124, v124 row_shr:2 row_mask:0xf bank_mask:0xf bound_ctrl:1
	v_add_f32_dpp v132, v117, v117 row_shr:2 row_mask:0xf bank_mask:0xf bound_ctrl:1
	v_add_f32_dpp v117, v125, v132 row_shl:14 row_mask:0xf bank_mask:0xf bound_ctrl:1
	v_add_f32_dpp v125, v125, v125 row_shr:2 row_mask:0xf bank_mask:0xf bound_ctrl:1
	v_add_f32_dpp v132, v118, v118 row_shr:2 row_mask:0xf bank_mask:0xf bound_ctrl:1
	v_add_f32_dpp v118, v126, v132 row_shl:14 row_mask:0xf bank_mask:0xf bound_ctrl:1
	v_add_f32_dpp v126, v126, v126 row_shr:2 row_mask:0xf bank_mask:0xf bound_ctrl:1
	v_add_f32_dpp v132, v119, v119 row_shr:2 row_mask:0xf bank_mask:0xf bound_ctrl:1
	v_add_f32_dpp v119, v127, v132 row_shl:14 row_mask:0xf bank_mask:0xf bound_ctrl:1
	v_add_f32_dpp v127, v127, v127 row_shr:2 row_mask:0xf bank_mask:0xf bound_ctrl:1
	v_add_f32_dpp v132, v120, v120 row_shr:2 row_mask:0xf bank_mask:0xf bound_ctrl:1
	v_add_f32_dpp v120, v128, v132 row_shl:14 row_mask:0xf bank_mask:0xf bound_ctrl:1
	v_add_f32_dpp v128, v128, v128 row_shr:2 row_mask:0xf bank_mask:0xf bound_ctrl:1
	v_add_f32_dpp v132, v121, v121 row_shr:2 row_mask:0xf bank_mask:0xf bound_ctrl:1
	v_add_f32_dpp v121, v129, v132 row_shl:14 row_mask:0xf bank_mask:0xf bound_ctrl:1
	v_add_f32_dpp v129, v129, v129 row_shr:2 row_mask:0xf bank_mask:0xf bound_ctrl:1
	v_add_f32_dpp v132, v122, v122 row_shr:2 row_mask:0xf bank_mask:0xf bound_ctrl:1
	v_add_f32_dpp v122, v130, v132 row_shl:14 row_mask:0xf bank_mask:0xf bound_ctrl:1
	v_add_f32_dpp v130, v130, v130 row_shr:2 row_mask:0xf bank_mask:0xf bound_ctrl:1
	v_add_f32_dpp v132, v123, v123 row_shr:2 row_mask:0xf bank_mask:0xf bound_ctrl:1
	v_add_f32_dpp v123, v131, v132 row_shl:14 row_mask:0xf bank_mask:0xf bound_ctrl:1
	v_add_f32_dpp v131, v131, v131 row_shr:2 row_mask:0xf bank_mask:0xf bound_ctrl:1
	v_add_f32_dpp v132, v116, v116 row_shr:4 row_mask:0xf bank_mask:0xf bound_ctrl:1
	v_add_f32_dpp v116, v124, v132 row_shl:12 row_mask:0xf bank_mask:0xf bound_ctrl:1
	v_add_f32_dpp v124, v124, v124 row_shr:4 row_mask:0xf bank_mask:0xf bound_ctrl:1
	v_add_f32_dpp v132, v117, v117 row_shr:4 row_mask:0xf bank_mask:0xf bound_ctrl:1
	v_add_f32_dpp v117, v125, v132 row_shl:12 row_mask:0xf bank_mask:0xf bound_ctrl:1
	v_add_f32_dpp v125, v125, v125 row_shr:4 row_mask:0xf bank_mask:0xf bound_ctrl:1
; __device__ __forceinline__ unsigned cvt_pk_bf16(float lo, float hi) { return __builtin_bit_cast(unsigned, __builtin_convertvector((f32x2_t){lo, hi}, bf16x2_t)); }
; #define GAS __attribute__((address_space(1)))
; __device__ __forceinline__ void unpack8(const v4u w, float (&f)[8]) { f[0] = bf_lo(w.x); f[1] = bf_hi(w.x); f[2] = bf_lo(w.y); f[3] = bf_hi(w.y); f[4] = bf_lo(w.z); f[5] = bf_hi(w.z); f[6] = bf_lo(w.w); f[7] = bf_hi(w.w); }
; __device__ __forceinline__ v4u pack8(const float (&f)[8]) { v4u w; w.x = cvt_pk_bf16(f[0], f[1]); w.y = cvt_pk_bf16(f[2], f[3]); w.z = cvt_pk_bf16(f[4], f[5]); w.w = cvt_pk_bf16(f[6], f[7]); return w; }
; template <int W> __device__ __forceinline__ void pool_group(const bf16* zrow  , const bf16* pw  , bf16* orow  , int pos, bool prev_ok) {
;     const float inv = 1.0f / (float)((pos + 1) < W ? (pos + 1) : W);
;     ...
;     for (int kk = 0; kk < 4; ++kk) {
;         if (kk < 3) {
; #pragma unroll
;             for (int dt = 0; dt < 8; ++dt) aw[(kk + 1) & 1][dt] = *(const GAS v4u*)(pw + (size_t)16 * dt * 128 + 32 * (kk + 1)); }
;         float own[8], c[8], p[8];
;         unpack8(cw[kk], own); unpack8(pv[kk], p);
; #pragma unroll
;         for (int j = 0; j < 8; ++j) c[j] = own[j];
;         win_step<1>(c, p);
;         if (W >= 4) win_step<2>(c, p);
;         if (W >= 8) win_step<4>(c, p);
;         if (W >= 16) win_step<8>(c, p);
;         float pl[8];
; #pragma unroll
;         for (int j = 0; j < 8; ++j) pl[j] = c[j] * inv - own[j];
;         const v4u pwk = pack8(pl); const bf16x8 pf = __builtin_bit_cast(bf16x8, pwk);
; #pragma unroll
;         for (int dt = 0; dt < 8; ++dt) acc[dt] = __builtin_amdgcn_mfma_f32_16x16x32_bf16(__builtin_bit_cast(bf16x8, aw[kk & 1][dt]), pf, acc[dt], 0, 0, 0);
;     }
; #pragma unroll
;     for (int dt = 0; dt < 8; ++dt) { v2u w; w.x = cvt_pk_bf16(acc[dt][0], acc[dt][1]); w.y = cvt_pk_bf16(acc[dt][2], acc[dt][3]); *(GAS v2u*)(orow + 16 * dt) = w; }
	v_add_f32_dpp v132, v118, v118 row_shr:4 row_mask:0xf bank_mask:0xf bound_ctrl:1
	v_add_f32_dpp v118, v126, v132 row_shl:12 row_mask:0xf bank_mask:0xf bound_ctrl:1
	v_add_f32_dpp v126, v126, v126 row_shr:4 row_mask:0xf bank_mask:0xf bound_ctrl:1
	v_add_f32_dpp v132, v119, v119 row_shr:4 row_mask:0xf bank_mask:0xf bound_ctrl:1
	v_add_f32_dpp v119, v127, v132 row_shl:12 row_mask:0xf bank_mask:0xf bound_ctrl:1
	v_add_f32_dpp v127, v127, v127 row_shr:4 row_mask:0xf bank_mask:0xf bound_ctrl:1
	v_add_f32_dpp v132, v120, v120 row_shr:4 row_mask:0xf bank_mask:0xf bound_ctrl:1
	v_add_f32_dpp v120, v128, v132 row_shl:12 row_mask:0xf bank_mask:0xf bound_ctrl:1
	v_add_f32_dpp v128, v128, v128 row_shr:4 row_mask:0xf bank_mask:0xf bound_ctrl:1
	v_add_f32_dpp v132, v121, v121 row_shr:4 row_mask:0xf bank_mask:0xf bound_ctrl:1
	v_add_f32_dpp v121, v129, v132 row_shl:12 row_mask:0xf bank_mask:0xf bound_ctrl:1
	v_add_f32_dpp v129, v129, v129 row_shr:4 row_mask:0xf bank_mask:0xf bound_ctrl:1
	v_add_f32_dpp v132, v122, v122 row_shr:4 row_mask:0xf bank_mask:0xf bound_ctrl:1
	v_add_f32_dpp v122, v130, v132 row_shl:12 row_mask:0xf bank_mask:0xf bound_ctrl:1
	v_add_f32_dpp v130, v130, v130 row_shr:4 row_mask:0xf bank_mask:0xf bound_ctrl:1
	v_add_f32_dpp v132, v123, v123 row_shr:4 row_mask:0xf bank_mask:0xf bound_ctrl:1
	v_add_f32_dpp v123, v131, v132 row_shl:12 row_mask:0xf bank_mask:0xf bound_ctrl:1
	v_add_f32_dpp v131, v131, v131 row_shr:4 row_mask:0xf bank_mask:0xf bound_ctrl:1
	v_fma_f32 v116, v116, v138, -v108
	v_fma_f32 v117, v117, v138, -v109
	v_fma_f32 v118, v118, v138, -v110
	v_fma_f32 v119, v119, v138, -v111
	v_fma_f32 v120, v120, v138, -v112
	v_fma_f32 v121, v121, v138, -v113
	v_fma_f32 v122, v122, v138, -v114
	v_fma_f32 v123, v123, v138, -v115
	v_cvt_pk_bf16_f32 v134, v116, v117
	v_cvt_pk_bf16_f32 v135, v118, v119
	v_cvt_pk_bf16_f32 v136, v120, v121
	v_cvt_pk_bf16_f32 v137, v122, v123
	s_waitcnt lgkmcnt(0)
	s_nop 0
	v_mfma_f32_16x16x32_bf16 v[76:79], v[44:47], v[134:137], v[76:79]
	v_mfma_f32_16x16x32_bf16 v[80:83], v[48:51], v[134:137], v[80:83]
	v_mfma_f32_16x16x32_bf16 v[84:87], v[52:55], v[134:137], v[84:87]
	v_mfma_f32_16x16x32_bf16 v[88:91], v[56:59], v[134:137], v[88:91]
	v_mfma_f32_16x16x32_bf16 v[92:95], v[60:63], v[134:137], v[92:95]
	v_mfma_f32_16x16x32_bf16 v[96:99], v[64:67], v[134:137], v[96:99]
	v_mfma_f32_16x16x32_bf16 v[100:103], v[68:71], v[134:137], v[100:103]
	v_mfma_f32_16x16x32_bf16 v[104:107], v[72:75], v[134:137], v[104:107]
	s_nop 7
	s_nop 1
	v_cvt_pk_bf16_f32 v132, v76, v77
	v_cvt_pk_bf16_f32 v133, v78, v79
	global_store_dwordx2 v142, v[132:133], s[46:47] offset:512
	s_nop 0
	v_cvt_pk_bf16_f32 v132, v80, v81
	v_cvt_pk_bf16_f32 v133, v82, v83
	global_store_dwordx2 v142, v[132:133], s[46:47] offset:544
	s_nop 0
	v_cvt_pk_bf16_f32 v132, v84, v85
	v_cvt_pk_bf16_f32 v133, v86, v87
	global_store_dwordx2 v142, v[132:133], s[46:47] offset:576
	s_nop 0
	v_cvt_pk_bf16_f32 v132, v88, v89
	v_cvt_pk_bf16_f32 v133, v90, v91
	global_store_dwordx2 v142, v[132:133], s[46:47] offset:608
	s_nop 0
	v_cvt_pk_bf16_f32 v132, v92, v93
	v_cvt_pk_bf16_f32 v133, v94, v95
	global_store_dwordx2 v142, v[132:133], s[46:47] offset:640
	s_nop 0
	v_cvt_pk_bf16_f32 v132, v96, v97
	v_cvt_pk_bf16_f32 v133, v98, v99
	global_store_dwordx2 v142, v[132:133], s[46:47] offset:672
	s_nop 0
	v_cvt_pk_bf16_f32 v132, v100, v101
	v_cvt_pk_bf16_f32 v133, v102, v103
	global_store_dwordx2 v142, v[132:133], s[46:47] offset:704
	s_nop 0
	v_cvt_pk_bf16_f32 v132, v104, v105
	v_cvt_pk_bf16_f32 v133, v106, v107
	global_store_dwordx2 v142, v[132:133], s[46:47] offset:736
	s_nop 0
	v_min_i32_e32 v139, 16, v140
	v_cvt_f32_i32_e32 v139, v139
	v_div_scale_f32 v1, s[42:43], v139, v139, 1.0
	v_rcp_f32_e32 v2, v1
	s_nop 0
	v_fma_f32 v7, -v1, v2, 1.0
	v_fmac_f32_e32 v2, v7, v2
	v_div_scale_f32 v3, vcc, 1.0, v139, 1.0
	v_mul_f32_e32 v6, v3, v2
	v_fma_f32 v7, -v1, v6, v3
	v_fmac_f32_e32 v6, v7, v2
	v_fma_f32 v1, -v1, v6, v3
	s_nop 1
	v_div_fmas_f32 v1, v1, v2, v6
	v_div_fixup_f32 v138, v1, v139, 1.0
	v_add_u32_e32 v147, 98304, v143
	ds_read_b128 v[44:47], v147
	ds_read_b128 v[48:51], v147 offset:4096
	ds_read_b128 v[52:55], v147 offset:8192
	ds_read_b128 v[56:59], v147 offset:12288
	ds_read_b128 v[60:63], v147 offset:16384
	ds_read_b128 v[64:67], v147 offset:20480
	ds_read_b128 v[68:71], v147 offset:24576
	ds_read_b128 v[72:75], v147 offset:28672
	s_waitcnt vmcnt(14)
; #define GAS __attribute__((address_space(1)))
; __device__ __forceinline__ void unpack8(const v4u w, float (&f)[8]) { f[0] = bf_lo(w.x); f[1] = bf_hi(w.x); f[2] = bf_lo(w.y); f[3] = bf_hi(w.y); f[4] = bf_lo(w.z); f[5] = bf_hi(w.z); f[6] = bf_lo(w.w); f[7] = bf_hi(w.w); }
; __device__ __forceinline__ v4u pack8(const float (&f)[8]) { v4u w; w.x = cvt_pk_bf16(f[0], f[1]); w.y = cvt_pk_bf16(f[2], f[3]); w.z = cvt_pk_bf16(f[4], f[5]); w.w = cvt_pk_bf16(f[6], f[7]); return w; }
; template <int SH> __device__ __forceinline__ float row_shr(float v) { return __int_as_float(__builtin_amdgcn_update_dpp(0, __float_as_int(v), 0x110 + SH, 0xf, 0xf, true)); }
; template <int SH> __device__ __forceinline__ float row_shl(float v) { return __int_as_float(__builtin_amdgcn_update_dpp(0, __float_as_int(v), 0x100 + SH, 0xf, 0xf, true)); }
; template <int S> __device__ __forceinline__ void win_step(float (&c)[8], float (&p)[8]) {
; #pragma unroll
;     for (int j = 0; j < 8; ++j) { const float cn = c[j] + row_shr<S>(c[j]) + row_shl<16 - S>(p[j]); p[j] += row_shr<S>(p[j]); c[j] = cn; }
; }
; template <int W> __device__ __forceinline__ void pool_group(const bf16* zrow  , const bf16* pw  , bf16* orow  , int pos, bool prev_ok) {
;     ...
;     for (int kk = 0; kk < 4; ++kk) {
;         if (kk < 3) {
; #pragma unroll
;             for (int dt = 0; dt < 8; ++dt) aw[(kk + 1) & 1][dt] = *(const GAS v4u*)(pw + (size_t)16 * dt * 128 + 32 * (kk + 1)); }
;         float own[8], c[8], p[8];
;         unpack8(cw[kk], own); unpack8(pv[kk], p);
; #pragma unroll
;         for (int j = 0; j < 8; ++j) c[j] = own[j];
;         win_step<1>(c, p);
;         if (W >= 4) win_step<2>(c, p);
;         if (W >= 8) win_step<4>(c, p);
;         if (W >= 16) win_step<8>(c, p);
;         float pl[8];
; #pragma unroll
;         for (int j = 0; j < 8; ++j) pl[j] = c[j] * inv - own[j];
;         const v4u pwk = pack8(pl); const bf16x8 pf = __builtin_bit_cast(bf16x8, pwk);
	v_lshlrev_b32_e32 v108, 16, v12
	v_and_b32_e32 v109, 0xffff0000, v12
	v_lshlrev_b32_e32 v110, 16, v13
	v_and_b32_e32 v111, 0xffff0000, v13
	v_lshlrev_b32_e32 v112, 16, v14
	v_and_b32_e32 v113, 0xffff0000, v14
	v_lshlrev_b32_e32 v114, 16, v15
	v_and_b32_e32 v115, 0xffff0000, v15
	v_lshlrev_b32_e32 v124, 16, v16
	v_and_b32_e32 v125, 0xffff0000, v16
	v_lshlrev_b32_e32 v126, 16, v17
	v_and_b32_e32 v127, 0xffff0000, v17
	v_lshlrev_b32_e32 v128, 16, v18
	v_and_b32_e32 v129, 0xffff0000, v18
	v_lshlrev_b32_e32 v130, 16, v19
	v_and_b32_e32 v131, 0xffff0000, v19
	v_cndmask_b32_e64 v124, 0, v124, s[40:41]
	v_cndmask_b32_e64 v125, 0, v125, s[40:41]
	v_cndmask_b32_e64 v126, 0, v126, s[40:41]
	v_cndmask_b32_e64 v127, 0, v127, s[40:41]
	v_cndmask_b32_e64 v128, 0, v128, s[40:41]
	v_cndmask_b32_e64 v129, 0, v129, s[40:41]
	v_cndmask_b32_e64 v130, 0, v130, s[40:41]
	v_cndmask_b32_e64 v131, 0, v131, s[40:41]
	v_mov_b32_e32 v116, v108
	v_mov_b32_e32 v117, v109
	v_mov_b32_e32 v118, v110
	v_mov_b32_e32 v119, v111
	v_mov_b32_e32 v120, v112
	v_mov_b32_e32 v121, v113
	v_mov_b32_e32 v122, v114
	v_mov_b32_e32 v123, v115
	v_add_f32_dpp v132, v116, v116 row_shr:1 row_mask:0xf bank_mask:0xf bound_ctrl:1
	v_add_f32_dpp v116, v124, v132 row_shl:15 row_mask:0xf bank_mask:0xf bound_ctrl:1
	v_add_f32_dpp v124, v124, v124 row_shr:1 row_mask:0xf bank_mask:0xf bound_ctrl:1
	v_add_f32_dpp v132, v117, v117 row_shr:1 row_mask:0xf bank_mask:0xf bound_ctrl:1
	v_add_f32_dpp v117, v125, v132 row_shl:15 row_mask:0xf bank_mask:0xf bound_ctrl:1
	v_add_f32_dpp v125, v125, v125 row_shr:1 row_mask:0xf bank_mask:0xf bound_ctrl:1
	v_add_f32_dpp v132, v118, v118 row_shr:1 row_mask:0xf bank_mask:0xf bound_ctrl:1
	v_add_f32_dpp v118, v126, v132 row_shl:15 row_mask:0xf bank_mask:0xf bound_ctrl:1
	v_add_f32_dpp v126, v126, v126 row_shr:1 row_mask:0xf bank_mask:0xf bound_ctrl:1
	v_add_f32_dpp v132, v119, v119 row_shr:1 row_mask:0xf bank_mask:0xf bound_ctrl:1
	v_add_f32_dpp v119, v127, v132 row_shl:15 row_mask:0xf bank_mask:0xf bound_ctrl:1
	v_add_f32_dpp v127, v127, v127 row_shr:1 row_mask:0xf bank_mask:0xf bound_ctrl:1
	v_add_f32_dpp v132, v120, v120 row_shr:1 row_mask:0xf bank_mask:0xf bound_ctrl:1
	v_add_f32_dpp v120, v128, v132 row_shl:15 row_mask:0xf bank_mask:0xf bound_ctrl:1
	v_add_f32_dpp v128, v128, v128 row_shr:1 row_mask:0xf bank_mask:0xf bound_ctrl:1
	v_add_f32_dpp v132, v121, v121 row_shr:1 row_mask:0xf bank_mask:0xf bound_ctrl:1
	v_add_f32_dpp v121, v129, v132 row_shl:15 row_mask:0xf bank_mask:0xf bound_ctrl:1
	v_add_f32_dpp v129, v129, v129 row_shr:1 row_mask:0xf bank_mask:0xf bound_ctrl:1
	v_add_f32_dpp v132, v122, v122 row_shr:1 row_mask:0xf bank_mask:0xf bound_ctrl:1
	v_add_f32_dpp v122, v130, v132 row_shl:15 row_mask:0xf bank_mask:0xf bound_ctrl:1
	v_add_f32_dpp v130, v130, v130 row_shr:1 row_mask:0xf bank_mask:0xf bound_ctrl:1
	v_add_f32_dpp v132, v123, v123 row_shr:1 row_mask:0xf bank_mask:0xf bound_ctrl:1
	v_add_f32_dpp v123, v131, v132 row_shl:15 row_mask:0xf bank_mask:0xf bound_ctrl:1
	v_add_f32_dpp v131, v131, v131 row_shr:1 row_mask:0xf bank_mask:0xf bound_ctrl:1
	v_add_f32_dpp v132, v116, v116 row_shr:2 row_mask:0xf bank_mask:0xf bound_ctrl:1
	v_add_f32_dpp v116, v124, v132 row_shl:14 row_mask:0xf bank_mask:0xf bound_ctrl:1
	v_add_f32_dpp v124, v124, v124 row_shr:2 row_mask:0xf bank_mask:0xf bound_ctrl:1
	v_add_f32_dpp v132, v117, v117 row_shr:2 row_mask:0xf bank_mask:0xf bound_ctrl:1
	v_add_f32_dpp v117, v125, v132 row_shl:14 row_mask:0xf bank_mask:0xf bound_ctrl:1
	v_add_f32_dpp v125, v125, v125 row_shr:2 row_mask:0xf bank_mask:0xf bound_ctrl:1
	v_add_f32_dpp v132, v118, v118 row_shr:2 row_mask:0xf bank_mask:0xf bound_ctrl:1
	v_add_f32_dpp v118, v126, v132 row_shl:14 row_mask:0xf bank_mask:0xf bound_ctrl:1
	v_add_f32_dpp v126, v126, v126 row_shr:2 row_mask:0xf bank_mask:0xf bound_ctrl:1
	v_add_f32_dpp v132, v119, v119 row_shr:2 row_mask:0xf bank_mask:0xf bound_ctrl:1
	v_add_f32_dpp v119, v127, v132 row_shl:14 row_mask:0xf bank_mask:0xf bound_ctrl:1
	v_add_f32_dpp v127, v127, v127 row_shr:2 row_mask:0xf bank_mask:0xf bound_ctrl:1
	v_add_f32_dpp v132, v120, v120 row_shr:2 row_mask:0xf bank_mask:0xf bound_ctrl:1
	v_add_f32_dpp v120, v128, v132 row_shl:14 row_mask:0xf bank_mask:0xf bound_ctrl:1
	v_add_f32_dpp v128, v128, v128 row_shr:2 row_mask:0xf bank_mask:0xf bound_ctrl:1
	v_add_f32_dpp v132, v121, v121 row_shr:2 row_mask:0xf bank_mask:0xf bound_ctrl:1
	v_add_f32_dpp v121, v129, v132 row_shl:14 row_mask:0xf bank_mask:0xf bound_ctrl:1
	v_add_f32_dpp v129, v129, v129 row_shr:2 row_mask:0xf bank_mask:0xf bound_ctrl:1
	v_add_f32_dpp v132, v122, v122 row_shr:2 row_mask:0xf bank_mask:0xf bound_ctrl:1
	v_add_f32_dpp v122, v130, v132 row_shl:14 row_mask:0xf bank_mask:0xf bound_ctrl:1
	v_add_f32_dpp v130, v130, v130 row_shr:2 row_mask:0xf bank_mask:0xf bound_ctrl:1
	v_add_f32_dpp v132, v123, v123 row_shr:2 row_mask:0xf bank_mask:0xf bound_ctrl:1
	v_add_f32_dpp v123, v131, v132 row_shl:14 row_mask:0xf bank_mask:0xf bound_ctrl:1
	v_add_f32_dpp v131, v131, v131 row_shr:2 row_mask:0xf bank_mask:0xf bound_ctrl:1
	v_add_f32_dpp v132, v116, v116 row_shr:4 row_mask:0xf bank_mask:0xf bound_ctrl:1
	v_add_f32_dpp v116, v124, v132 row_shl:12 row_mask:0xf bank_mask:0xf bound_ctrl:1
	v_add_f32_dpp v124, v124, v124 row_shr:4 row_mask:0xf bank_mask:0xf bound_ctrl:1
	v_add_f32_dpp v132, v117, v117 row_shr:4 row_mask:0xf bank_mask:0xf bound_ctrl:1
	v_add_f32_dpp v117, v125, v132 row_shl:12 row_mask:0xf bank_mask:0xf bound_ctrl:1
	v_add_f32_dpp v125, v125, v125 row_shr:4 row_mask:0xf bank_mask:0xf bound_ctrl:1
	v_add_f32_dpp v132, v118, v118 row_shr:4 row_mask:0xf bank_mask:0xf bound_ctrl:1
; #define GAS __attribute__((address_space(1)))
; __device__ __forceinline__ void unpack8(const v4u w, float (&f)[8]) { f[0] = bf_lo(w.x); f[1] = bf_hi(w.x); f[2] = bf_lo(w.y); f[3] = bf_hi(w.y); f[4] = bf_lo(w.z); f[5] = bf_hi(w.z); f[6] = bf_lo(w.w); f[7] = bf_hi(w.w); }
; __device__ __forceinline__ v4u pack8(const float (&f)[8]) { v4u w; w.x = cvt_pk_bf16(f[0], f[1]); w.y = cvt_pk_bf16(f[2], f[3]); w.z = cvt_pk_bf16(f[4], f[5]); w.w = cvt_pk_bf16(f[6], f[7]); return w; }
; template <int SH> __device__ __forceinline__ float row_shr(float v) { return __int_as_float(__builtin_amdgcn_update_dpp(0, __float_as_int(v), 0x110 + SH, 0xf, 0xf, true)); }
; template <int SH> __device__ __forceinline__ float row_shl(float v) { return __int_as_float(__builtin_amdgcn_update_dpp(0, __float_as_int(v), 0x100 + SH, 0xf, 0xf, true)); }
; template <int S> __device__ __forceinline__ void win_step(float (&c)[8], float (&p)[8]) {
; #pragma unroll
;     for (int j = 0; j < 8; ++j) { const float cn = c[j] + row_shr<S>(c[j]) + row_shl<16 - S>(p[j]); p[j] += row_shr<S>(p[j]); c[j] = cn; }
; }
; template <int W> __device__ __forceinline__ void pool_group(const bf16* zrow  , const bf16* pw  , bf16* orow  , int pos, bool prev_ok) {
;     ...
;     for (int kk = 0; kk < 4; ++kk) {
;         if (kk < 3) {
; #pragma unroll
;             for (int dt = 0; dt < 8; ++dt) aw[(kk + 1) & 1][dt] = *(const GAS v4u*)(pw + (size_t)16 * dt * 128 + 32 * (kk + 1)); }
;         float own[8], c[8], p[8];
;         unpack8(cw[kk], own); unpack8(pv[kk], p);
; #pragma unroll
;         for (int j = 0; j < 8; ++j) c[j] = own[j];
;         win_step<1>(c, p);
;         if (W >= 4) win_step<2>(c, p);
;         if (W >= 8) win_step<4>(c, p);
;         if (W >= 16) win_step<8>(c, p);
;         float pl[8];
; #pragma unroll
;         for (int j = 0; j < 8; ++j) pl[j] = c[j] * inv - own[j];
;         const v4u pwk = pack8(pl); const bf16x8 pf = __builtin_bit_cast(bf16x8, pwk);
; #pragma unroll
;         for (int dt = 0; dt < 8; ++dt) acc[dt] = __builtin_amdgcn_mfma_f32_16x16x32_bf16(__builtin_bit_cast(bf16x8, aw[kk & 1][dt]), pf, acc[dt], 0, 0, 0);
	v_add_f32_dpp v118, v126, v132 row_shl:12 row_mask:0xf bank_mask:0xf bound_ctrl:1
	v_add_f32_dpp v126, v126, v126 row_shr:4 row_mask:0xf bank_mask:0xf bound_ctrl:1
	v_add_f32_dpp v132, v119, v119 row_shr:4 row_mask:0xf bank_mask:0xf bound_ctrl:1
	v_add_f32_dpp v119, v127, v132 row_shl:12 row_mask:0xf bank_mask:0xf bound_ctrl:1
	v_add_f32_dpp v127, v127, v127 row_shr:4 row_mask:0xf bank_mask:0xf bound_ctrl:1
	v_add_f32_dpp v132, v120, v120 row_shr:4 row_mask:0xf bank_mask:0xf bound_ctrl:1
	v_add_f32_dpp v120, v128, v132 row_shl:12 row_mask:0xf bank_mask:0xf bound_ctrl:1
	v_add_f32_dpp v128, v128, v128 row_shr:4 row_mask:0xf bank_mask:0xf bound_ctrl:1
	v_add_f32_dpp v132, v121, v121 row_shr:4 row_mask:0xf bank_mask:0xf bound_ctrl:1
	v_add_f32_dpp v121, v129, v132 row_shl:12 row_mask:0xf bank_mask:0xf bound_ctrl:1
	v_add_f32_dpp v129, v129, v129 row_shr:4 row_mask:0xf bank_mask:0xf bound_ctrl:1
	v_add_f32_dpp v132, v122, v122 row_shr:4 row_mask:0xf bank_mask:0xf bound_ctrl:1
	v_add_f32_dpp v122, v130, v132 row_shl:12 row_mask:0xf bank_mask:0xf bound_ctrl:1
	v_add_f32_dpp v130, v130, v130 row_shr:4 row_mask:0xf bank_mask:0xf bound_ctrl:1
	v_add_f32_dpp v132, v123, v123 row_shr:4 row_mask:0xf bank_mask:0xf bound_ctrl:1
	v_add_f32_dpp v123, v131, v132 row_shl:12 row_mask:0xf bank_mask:0xf bound_ctrl:1
	v_add_f32_dpp v131, v131, v131 row_shr:4 row_mask:0xf bank_mask:0xf bound_ctrl:1
	v_add_f32_dpp v132, v116, v116 row_shr:8 row_mask:0xf bank_mask:0xf bound_ctrl:1
	v_add_f32_dpp v116, v124, v132 row_shl:8 row_mask:0xf bank_mask:0xf bound_ctrl:1
	v_add_f32_dpp v124, v124, v124 row_shr:8 row_mask:0xf bank_mask:0xf bound_ctrl:1
	v_add_f32_dpp v132, v117, v117 row_shr:8 row_mask:0xf bank_mask:0xf bound_ctrl:1
	v_add_f32_dpp v117, v125, v132 row_shl:8 row_mask:0xf bank_mask:0xf bound_ctrl:1
	v_add_f32_dpp v125, v125, v125 row_shr:8 row_mask:0xf bank_mask:0xf bound_ctrl:1
	v_add_f32_dpp v132, v118, v118 row_shr:8 row_mask:0xf bank_mask:0xf bound_ctrl:1
	v_add_f32_dpp v118, v126, v132 row_shl:8 row_mask:0xf bank_mask:0xf bound_ctrl:1
	v_add_f32_dpp v126, v126, v126 row_shr:8 row_mask:0xf bank_mask:0xf bound_ctrl:1
	v_add_f32_dpp v132, v119, v119 row_shr:8 row_mask:0xf bank_mask:0xf bound_ctrl:1
	v_add_f32_dpp v119, v127, v132 row_shl:8 row_mask:0xf bank_mask:0xf bound_ctrl:1
	v_add_f32_dpp v127, v127, v127 row_shr:8 row_mask:0xf bank_mask:0xf bound_ctrl:1
	v_add_f32_dpp v132, v120, v120 row_shr:8 row_mask:0xf bank_mask:0xf bound_ctrl:1
	v_add_f32_dpp v120, v128, v132 row_shl:8 row_mask:0xf bank_mask:0xf bound_ctrl:1
	v_add_f32_dpp v128, v128, v128 row_shr:8 row_mask:0xf bank_mask:0xf bound_ctrl:1
	v_add_f32_dpp v132, v121, v121 row_shr:8 row_mask:0xf bank_mask:0xf bound_ctrl:1
	v_add_f32_dpp v121, v129, v132 row_shl:8 row_mask:0xf bank_mask:0xf bound_ctrl:1
	v_add_f32_dpp v129, v129, v129 row_shr:8 row_mask:0xf bank_mask:0xf bound_ctrl:1
	v_add_f32_dpp v132, v122, v122 row_shr:8 row_mask:0xf bank_mask:0xf bound_ctrl:1
	v_add_f32_dpp v122, v130, v132 row_shl:8 row_mask:0xf bank_mask:0xf bound_ctrl:1
	v_add_f32_dpp v130, v130, v130 row_shr:8 row_mask:0xf bank_mask:0xf bound_ctrl:1
	v_add_f32_dpp v132, v123, v123 row_shr:8 row_mask:0xf bank_mask:0xf bound_ctrl:1
	v_add_f32_dpp v123, v131, v132 row_shl:8 row_mask:0xf bank_mask:0xf bound_ctrl:1
	v_add_f32_dpp v131, v131, v131 row_shr:8 row_mask:0xf bank_mask:0xf bound_ctrl:1
	v_fma_f32 v116, v116, v138, -v108
	v_fma_f32 v117, v117, v138, -v109
	v_fma_f32 v118, v118, v138, -v110
	v_fma_f32 v119, v119, v138, -v111
	v_fma_f32 v120, v120, v138, -v112
	v_fma_f32 v121, v121, v138, -v113
	v_fma_f32 v122, v122, v138, -v114
	v_fma_f32 v123, v123, v138, -v115
	v_cvt_pk_bf16_f32 v134, v116, v117
	v_cvt_pk_bf16_f32 v135, v118, v119
	v_cvt_pk_bf16_f32 v136, v120, v121
	v_cvt_pk_bf16_f32 v137, v122, v123
	s_waitcnt lgkmcnt(0)
	s_nop 0
	v_mfma_f32_16x16x32_bf16 v[76:79], v[44:47], v[134:137], 0
	v_mfma_f32_16x16x32_bf16 v[80:83], v[48:51], v[134:137], 0
	v_mfma_f32_16x16x32_bf16 v[84:87], v[52:55], v[134:137], 0
	v_mfma_f32_16x16x32_bf16 v[88:91], v[56:59], v[134:137], 0
	v_mfma_f32_16x16x32_bf16 v[92:95], v[60:63], v[134:137], 0
	v_mfma_f32_16x16x32_bf16 v[96:99], v[64:67], v[134:137], 0
	v_mfma_f32_16x16x32_bf16 v[100:103], v[68:71], v[134:137], 0
	v_mfma_f32_16x16x32_bf16 v[104:107], v[72:75], v[134:137], 0
	v_add_u32_e32 v147, 98304, v144
	ds_read_b128 v[44:47], v147
	ds_read_b128 v[48:51], v147 offset:4096
	ds_read_b128 v[52:55], v147 offset:8192
	ds_read_b128 v[56:59], v147 offset:12288
	ds_read_b128 v[60:63], v147 offset:16384
	ds_read_b128 v[64:67], v147 offset:20480
	ds_read_b128 v[68:71], v147 offset:24576
	ds_read_b128 v[72:75], v147 offset:28672
	s_waitcnt vmcnt(12)
; #define GAS __attribute__((address_space(1)))
; __device__ __forceinline__ void unpack8(const v4u w, float (&f)[8]) { f[0] = bf_lo(w.x); f[1] = bf_hi(w.x); f[2] = bf_lo(w.y); f[3] = bf_hi(w.y); f[4] = bf_lo(w.z); f[5] = bf_hi(w.z); f[6] = bf_lo(w.w); f[7] = bf_hi(w.w); }
; __device__ __forceinline__ v4u pack8(const float (&f)[8]) { v4u w; w.x = cvt_pk_bf16(f[0], f[1]); w.y = cvt_pk_bf16(f[2], f[3]); w.z = cvt_pk_bf16(f[4], f[5]); w.w = cvt_pk_bf16(f[6], f[7]); return w; }
; template <int SH> __device__ __forceinline__ float row_shr(float v) { return __int_as_float(__builtin_amdgcn_update_dpp(0, __float_as_int(v), 0x110 + SH, 0xf, 0xf, true)); }
; template <int SH> __device__ __forceinline__ float row_shl(float v) { return __int_as_float(__builtin_amdgcn_update_dpp(0, __float_as_int(v), 0x100 + SH, 0xf, 0xf, true)); }
; template <int S> __device__ __forceinline__ void win_step(float (&c)[8], float (&p)[8]) {
; #pragma unroll
;     for (int j = 0; j < 8; ++j) { const float cn = c[j] + row_shr<S>(c[j]) + row_shl<16 - S>(p[j]); p[j] += row_shr<S>(p[j]); c[j] = cn; }
; }
; template <int W> __device__ __forceinline__ void pool_group(const bf16* zrow  , const bf16* pw  , bf16* orow  , int pos, bool prev_ok) {
;     ...
;     for (int kk = 0; kk < 4; ++kk) {
;         if (kk < 3) {
; #pragma unroll
;             for (int dt = 0; dt < 8; ++dt) aw[(kk + 1) & 1][dt] = *(const GAS v4u*)(pw + (size_t)16 * dt * 128 + 32 * (kk + 1)); }
;         float own[8], c[8], p[8];
;         unpack8(cw[kk], own); unpack8(pv[kk], p);
; #pragma unroll
;         for (int j = 0; j < 8; ++j) c[j] = own[j];
;         win_step<1>(c, p);
;         if (W >= 4) win_step<2>(c, p);
;         if (W >= 8) win_step<4>(c, p);
;         if (W >= 16) win_step<8>(c, p);
;         float pl[8];
; #pragma unroll
;         for (int j = 0; j < 8; ++j) pl[j] = c[j] * inv - own[j];
;         const v4u pwk = pack8(pl); const bf16x8 pf = __builtin_bit_cast(bf16x8, pwk);
	v_lshlrev_b32_e32 v108, 16, v20
	v_and_b32_e32 v109, 0xffff0000, v20
	v_lshlrev_b32_e32 v110, 16, v21
	v_and_b32_e32 v111, 0xffff0000, v21
	v_lshlrev_b32_e32 v112, 16, v22
	v_and_b32_e32 v113, 0xffff0000, v22
	v_lshlrev_b32_e32 v114, 16, v23
	v_and_b32_e32 v115, 0xffff0000, v23
	v_lshlrev_b32_e32 v124, 16, v24
	v_and_b32_e32 v125, 0xffff0000, v24
	v_lshlrev_b32_e32 v126, 16, v25
	v_and_b32_e32 v127, 0xffff0000, v25
	v_lshlrev_b32_e32 v128, 16, v26
	v_and_b32_e32 v129, 0xffff0000, v26
	v_lshlrev_b32_e32 v130, 16, v27
	v_and_b32_e32 v131, 0xffff0000, v27
	v_cndmask_b32_e64 v124, 0, v124, s[40:41]
	v_cndmask_b32_e64 v125, 0, v125, s[40:41]
	v_cndmask_b32_e64 v126, 0, v126, s[40:41]
	v_cndmask_b32_e64 v127, 0, v127, s[40:41]
	v_cndmask_b32_e64 v128, 0, v128, s[40:41]
	v_cndmask_b32_e64 v129, 0, v129, s[40:41]
	v_cndmask_b32_e64 v130, 0, v130, s[40:41]
	v_cndmask_b32_e64 v131, 0, v131, s[40:41]
	v_mov_b32_e32 v116, v108
	v_mov_b32_e32 v117, v109
	v_mov_b32_e32 v118, v110
	v_mov_b32_e32 v119, v111
	v_mov_b32_e32 v120, v112
	v_mov_b32_e32 v121, v113
	v_mov_b32_e32 v122, v114
	v_mov_b32_e32 v123, v115
	v_add_f32_dpp v132, v116, v116 row_shr:1 row_mask:0xf bank_mask:0xf bound_ctrl:1
	v_add_f32_dpp v116, v124, v132 row_shl:15 row_mask:0xf bank_mask:0xf bound_ctrl:1
	v_add_f32_dpp v124, v124, v124 row_shr:1 row_mask:0xf bank_mask:0xf bound_ctrl:1
	v_add_f32_dpp v132, v117, v117 row_shr:1 row_mask:0xf bank_mask:0xf bound_ctrl:1
	v_add_f32_dpp v117, v125, v132 row_shl:15 row_mask:0xf bank_mask:0xf bound_ctrl:1
	v_add_f32_dpp v125, v125, v125 row_shr:1 row_mask:0xf bank_mask:0xf bound_ctrl:1
	v_add_f32_dpp v132, v118, v118 row_shr:1 row_mask:0xf bank_mask:0xf bound_ctrl:1
	v_add_f32_dpp v118, v126, v132 row_shl:15 row_mask:0xf bank_mask:0xf bound_ctrl:1
	v_add_f32_dpp v126, v126, v126 row_shr:1 row_mask:0xf bank_mask:0xf bound_ctrl:1
	v_add_f32_dpp v132, v119, v119 row_shr:1 row_mask:0xf bank_mask:0xf bound_ctrl:1
	v_add_f32_dpp v119, v127, v132 row_shl:15 row_mask:0xf bank_mask:0xf bound_ctrl:1
	v_add_f32_dpp v127, v127, v127 row_shr:1 row_mask:0xf bank_mask:0xf bound_ctrl:1
	v_add_f32_dpp v132, v120, v120 row_shr:1 row_mask:0xf bank_mask:0xf bound_ctrl:1
	v_add_f32_dpp v120, v128, v132 row_shl:15 row_mask:0xf bank_mask:0xf bound_ctrl:1
	v_add_f32_dpp v128, v128, v128 row_shr:1 row_mask:0xf bank_mask:0xf bound_ctrl:1
	v_add_f32_dpp v132, v121, v121 row_shr:1 row_mask:0xf bank_mask:0xf bound_ctrl:1
	v_add_f32_dpp v121, v129, v132 row_shl:15 row_mask:0xf bank_mask:0xf bound_ctrl:1
	v_add_f32_dpp v129, v129, v129 row_shr:1 row_mask:0xf bank_mask:0xf bound_ctrl:1
	v_add_f32_dpp v132, v122, v122 row_shr:1 row_mask:0xf bank_mask:0xf bound_ctrl:1
	v_add_f32_dpp v122, v130, v132 row_shl:15 row_mask:0xf bank_mask:0xf bound_ctrl:1
	v_add_f32_dpp v130, v130, v130 row_shr:1 row_mask:0xf bank_mask:0xf bound_ctrl:1
	v_add_f32_dpp v132, v123, v123 row_shr:1 row_mask:0xf bank_mask:0xf bound_ctrl:1
	v_add_f32_dpp v123, v131, v132 row_shl:15 row_mask:0xf bank_mask:0xf bound_ctrl:1
	v_add_f32_dpp v131, v131, v131 row_shr:1 row_mask:0xf bank_mask:0xf bound_ctrl:1
	v_add_f32_dpp v132, v116, v116 row_shr:2 row_mask:0xf bank_mask:0xf bound_ctrl:1
	v_add_f32_dpp v116, v124, v132 row_shl:14 row_mask:0xf bank_mask:0xf bound_ctrl:1
	v_add_f32_dpp v124, v124, v124 row_shr:2 row_mask:0xf bank_mask:0xf bound_ctrl:1
	v_add_f32_dpp v132, v117, v117 row_shr:2 row_mask:0xf bank_mask:0xf bound_ctrl:1
	v_add_f32_dpp v117, v125, v132 row_shl:14 row_mask:0xf bank_mask:0xf bound_ctrl:1
	v_add_f32_dpp v125, v125, v125 row_shr:2 row_mask:0xf bank_mask:0xf bound_ctrl:1
	v_add_f32_dpp v132, v118, v118 row_shr:2 row_mask:0xf bank_mask:0xf bound_ctrl:1
	v_add_f32_dpp v118, v126, v132 row_shl:14 row_mask:0xf bank_mask:0xf bound_ctrl:1
	v_add_f32_dpp v126, v126, v126 row_shr:2 row_mask:0xf bank_mask:0xf bound_ctrl:1
	v_add_f32_dpp v132, v119, v119 row_shr:2 row_mask:0xf bank_mask:0xf bound_ctrl:1
	v_add_f32_dpp v119, v127, v132 row_shl:14 row_mask:0xf bank_mask:0xf bound_ctrl:1
	v_add_f32_dpp v127, v127, v127 row_shr:2 row_mask:0xf bank_mask:0xf bound_ctrl:1
	v_add_f32_dpp v132, v120, v120 row_shr:2 row_mask:0xf bank_mask:0xf bound_ctrl:1
	v_add_f32_dpp v120, v128, v132 row_shl:14 row_mask:0xf bank_mask:0xf bound_ctrl:1
	v_add_f32_dpp v128, v128, v128 row_shr:2 row_mask:0xf bank_mask:0xf bound_ctrl:1
	v_add_f32_dpp v132, v121, v121 row_shr:2 row_mask:0xf bank_mask:0xf bound_ctrl:1
	v_add_f32_dpp v121, v129, v132 row_shl:14 row_mask:0xf bank_mask:0xf bound_ctrl:1
	v_add_f32_dpp v129, v129, v129 row_shr:2 row_mask:0xf bank_mask:0xf bound_ctrl:1
	v_add_f32_dpp v132, v122, v122 row_shr:2 row_mask:0xf bank_mask:0xf bound_ctrl:1
	v_add_f32_dpp v122, v130, v132 row_shl:14 row_mask:0xf bank_mask:0xf bound_ctrl:1
	v_add_f32_dpp v130, v130, v130 row_shr:2 row_mask:0xf bank_mask:0xf bound_ctrl:1
	v_add_f32_dpp v132, v123, v123 row_shr:2 row_mask:0xf bank_mask:0xf bound_ctrl:1
	v_add_f32_dpp v123, v131, v132 row_shl:14 row_mask:0xf bank_mask:0xf bound_ctrl:1
	v_add_f32_dpp v131, v131, v131 row_shr:2 row_mask:0xf bank_mask:0xf bound_ctrl:1
	v_add_f32_dpp v132, v116, v116 row_shr:4 row_mask:0xf bank_mask:0xf bound_ctrl:1
	v_add_f32_dpp v116, v124, v132 row_shl:12 row_mask:0xf bank_mask:0xf bound_ctrl:1
	v_add_f32_dpp v124, v124, v124 row_shr:4 row_mask:0xf bank_mask:0xf bound_ctrl:1
	v_add_f32_dpp v132, v117, v117 row_shr:4 row_mask:0xf bank_mask:0xf bound_ctrl:1
	v_add_f32_dpp v117, v125, v132 row_shl:12 row_mask:0xf bank_mask:0xf bound_ctrl:1
	v_add_f32_dpp v125, v125, v125 row_shr:4 row_mask:0xf bank_mask:0xf bound_ctrl:1
	v_add_f32_dpp v132, v118, v118 row_shr:4 row_mask:0xf bank_mask:0xf bound_ctrl:1
; #define GAS __attribute__((address_space(1)))
; __device__ __forceinline__ void unpack8(const v4u w, float (&f)[8]) { f[0] = bf_lo(w.x); f[1] = bf_hi(w.x); f[2] = bf_lo(w.y); f[3] = bf_hi(w.y); f[4] = bf_lo(w.z); f[5] = bf_hi(w.z); f[6] = bf_lo(w.w); f[7] = bf_hi(w.w); }
; __device__ __forceinline__ v4u pack8(const float (&f)[8]) { v4u w; w.x = cvt_pk_bf16(f[0], f[1]); w.y = cvt_pk_bf16(f[2], f[3]); w.z = cvt_pk_bf16(f[4], f[5]); w.w = cvt_pk_bf16(f[6], f[7]); return w; }
; template <int S> __device__ __forceinline__ void win_step(float (&c)[8], float (&p)[8]) {
; #pragma unroll
;     for (int j = 0; j < 8; ++j) { const float cn = c[j] + row_shr<S>(c[j]) + row_shl<16 - S>(p[j]); p[j] += row_shr<S>(p[j]); c[j] = cn; }
; }
; template <int W> __device__ __forceinline__ void pool_group(const bf16* zrow  , const bf16* pw  , bf16* orow  , int pos, bool prev_ok) {
;     const float inv = 1.0f / (float)((pos + 1) < W ? (pos + 1) : W);
;     f32x4 acc[8];
; #pragma unroll
;     for (int dt = 0; dt < 8; ++dt) acc[dt] = (f32x4){0.f, 0.f, 0.f, 0.f};
;     v4u cw[4], pv[4], aw[2][8];
; #pragma unroll
;     for (int kk = 0; kk < 4; ++kk) { cw[kk] = *(const GAS v4u*)(zrow + 32 * kk); pv[kk] = prev_ok ? *(const GAS v4u*)(zrow + 32 * kk - (ptrdiff_t)16 * ZC) : (v4u){0u, 0u, 0u, 0u}; }
; #pragma unroll
;     for (int dt = 0; dt < 8; ++dt) aw[0][dt] = *(const GAS v4u*)(pw + (size_t)16 * dt * 128);
; #pragma unroll
;     for (int kk = 0; kk < 4; ++kk) {
;         if (kk < 3) {
; #pragma unroll
;             for (int dt = 0; dt < 8; ++dt) aw[(kk + 1) & 1][dt] = *(const GAS v4u*)(pw + (size_t)16 * dt * 128 + 32 * (kk + 1)); }
;         float own[8], c[8], p[8];
;         unpack8(cw[kk], own); unpack8(pv[kk], p);
; #pragma unroll
;         for (int j = 0; j < 8; ++j) c[j] = own[j];
;         win_step<1>(c, p);
;         if (W >= 4) win_step<2>(c, p);
;         if (W >= 8) win_step<4>(c, p);
;         if (W >= 16) win_step<8>(c, p);
;         float pl[8];
; #pragma unroll
;         for (int j = 0; j < 8; ++j) pl[j] = c[j] * inv - own[j];
;         const v4u pwk = pack8(pl); const bf16x8 pf = __builtin_bit_cast(bf16x8, pwk);
; #pragma unroll
;         for (int dt = 0; dt < 8; ++dt) acc[dt] = __builtin_amdgcn_mfma_f32_16x16x32_bf16(__builtin_bit_cast(bf16x8, aw[kk & 1][dt]), pf, acc[dt], 0, 0, 0);
	v_add_f32_dpp v118, v126, v132 row_shl:12 row_mask:0xf bank_mask:0xf bound_ctrl:1
	v_add_f32_dpp v126, v126, v126 row_shr:4 row_mask:0xf bank_mask:0xf bound_ctrl:1
	v_add_f32_dpp v132, v119, v119 row_shr:4 row_mask:0xf bank_mask:0xf bound_ctrl:1
	v_add_f32_dpp v119, v127, v132 row_shl:12 row_mask:0xf bank_mask:0xf bound_ctrl:1
	v_add_f32_dpp v127, v127, v127 row_shr:4 row_mask:0xf bank_mask:0xf bound_ctrl:1
	v_add_f32_dpp v132, v120, v120 row_shr:4 row_mask:0xf bank_mask:0xf bound_ctrl:1
	v_add_f32_dpp v120, v128, v132 row_shl:12 row_mask:0xf bank_mask:0xf bound_ctrl:1
	v_add_f32_dpp v128, v128, v128 row_shr:4 row_mask:0xf bank_mask:0xf bound_ctrl:1
	v_add_f32_dpp v132, v121, v121 row_shr:4 row_mask:0xf bank_mask:0xf bound_ctrl:1
	v_add_f32_dpp v121, v129, v132 row_shl:12 row_mask:0xf bank_mask:0xf bound_ctrl:1
	v_add_f32_dpp v129, v129, v129 row_shr:4 row_mask:0xf bank_mask:0xf bound_ctrl:1
	v_add_f32_dpp v132, v122, v122 row_shr:4 row_mask:0xf bank_mask:0xf bound_ctrl:1
	v_add_f32_dpp v122, v130, v132 row_shl:12 row_mask:0xf bank_mask:0xf bound_ctrl:1
	v_add_f32_dpp v130, v130, v130 row_shr:4 row_mask:0xf bank_mask:0xf bound_ctrl:1
	v_add_f32_dpp v132, v123, v123 row_shr:4 row_mask:0xf bank_mask:0xf bound_ctrl:1
	v_add_f32_dpp v123, v131, v132 row_shl:12 row_mask:0xf bank_mask:0xf bound_ctrl:1
	v_add_f32_dpp v131, v131, v131 row_shr:4 row_mask:0xf bank_mask:0xf bound_ctrl:1
	v_add_f32_dpp v132, v116, v116 row_shr:8 row_mask:0xf bank_mask:0xf bound_ctrl:1
	v_add_f32_dpp v116, v124, v132 row_shl:8 row_mask:0xf bank_mask:0xf bound_ctrl:1
	v_add_f32_dpp v124, v124, v124 row_shr:8 row_mask:0xf bank_mask:0xf bound_ctrl:1
	v_add_f32_dpp v132, v117, v117 row_shr:8 row_mask:0xf bank_mask:0xf bound_ctrl:1
	v_add_f32_dpp v117, v125, v132 row_shl:8 row_mask:0xf bank_mask:0xf bound_ctrl:1
	v_add_f32_dpp v125, v125, v125 row_shr:8 row_mask:0xf bank_mask:0xf bound_ctrl:1
	v_add_f32_dpp v132, v118, v118 row_shr:8 row_mask:0xf bank_mask:0xf bound_ctrl:1
	v_add_f32_dpp v118, v126, v132 row_shl:8 row_mask:0xf bank_mask:0xf bound_ctrl:1
	v_add_f32_dpp v126, v126, v126 row_shr:8 row_mask:0xf bank_mask:0xf bound_ctrl:1
	v_add_f32_dpp v132, v119, v119 row_shr:8 row_mask:0xf bank_mask:0xf bound_ctrl:1
	v_add_f32_dpp v119, v127, v132 row_shl:8 row_mask:0xf bank_mask:0xf bound_ctrl:1
	v_add_f32_dpp v127, v127, v127 row_shr:8 row_mask:0xf bank_mask:0xf bound_ctrl:1
	v_add_f32_dpp v132, v120, v120 row_shr:8 row_mask:0xf bank_mask:0xf bound_ctrl:1
	v_add_f32_dpp v120, v128, v132 row_shl:8 row_mask:0xf bank_mask:0xf bound_ctrl:1
	v_add_f32_dpp v128, v128, v128 row_shr:8 row_mask:0xf bank_mask:0xf bound_ctrl:1
	v_add_f32_dpp v132, v121, v121 row_shr:8 row_mask:0xf bank_mask:0xf bound_ctrl:1
	v_add_f32_dpp v121, v129, v132 row_shl:8 row_mask:0xf bank_mask:0xf bound_ctrl:1
	v_add_f32_dpp v129, v129, v129 row_shr:8 row_mask:0xf bank_mask:0xf bound_ctrl:1
	v_add_f32_dpp v132, v122, v122 row_shr:8 row_mask:0xf bank_mask:0xf bound_ctrl:1
	v_add_f32_dpp v122, v130, v132 row_shl:8 row_mask:0xf bank_mask:0xf bound_ctrl:1
	v_add_f32_dpp v130, v130, v130 row_shr:8 row_mask:0xf bank_mask:0xf bound_ctrl:1
	v_add_f32_dpp v132, v123, v123 row_shr:8 row_mask:0xf bank_mask:0xf bound_ctrl:1
	v_add_f32_dpp v123, v131, v132 row_shl:8 row_mask:0xf bank_mask:0xf bound_ctrl:1
	v_add_f32_dpp v131, v131, v131 row_shr:8 row_mask:0xf bank_mask:0xf bound_ctrl:1
	v_fma_f32 v116, v116, v138, -v108
	v_fma_f32 v117, v117, v138, -v109
	v_fma_f32 v118, v118, v138, -v110
	v_fma_f32 v119, v119, v138, -v111
	v_fma_f32 v120, v120, v138, -v112
	v_fma_f32 v121, v121, v138, -v113
	v_fma_f32 v122, v122, v138, -v114
	v_fma_f32 v123, v123, v138, -v115
	v_cvt_pk_bf16_f32 v134, v116, v117
	v_cvt_pk_bf16_f32 v135, v118, v119
	v_cvt_pk_bf16_f32 v136, v120, v121
	v_cvt_pk_bf16_f32 v137, v122, v123
	s_waitcnt lgkmcnt(0)
	s_nop 0
	v_mfma_f32_16x16x32_bf16 v[76:79], v[44:47], v[134:137], v[76:79]
	v_mfma_f32_16x16x32_bf16 v[80:83], v[48:51], v[134:137], v[80:83]
	v_mfma_f32_16x16x32_bf16 v[84:87], v[52:55], v[134:137], v[84:87]
	v_mfma_f32_16x16x32_bf16 v[88:91], v[56:59], v[134:137], v[88:91]
	v_mfma_f32_16x16x32_bf16 v[92:95], v[60:63], v[134:137], v[92:95]
	v_mfma_f32_16x16x32_bf16 v[96:99], v[64:67], v[134:137], v[96:99]
	v_mfma_f32_16x16x32_bf16 v[100:103], v[68:71], v[134:137], v[100:103]
	v_mfma_f32_16x16x32_bf16 v[104:107], v[72:75], v[134:137], v[104:107]
	v_add_u32_e32 v147, 98304, v145
	ds_read_b128 v[44:47], v147
	ds_read_b128 v[48:51], v147 offset:4096
	ds_read_b128 v[52:55], v147 offset:8192
	ds_read_b128 v[56:59], v147 offset:12288
	ds_read_b128 v[60:63], v147 offset:16384
	ds_read_b128 v[64:67], v147 offset:20480
	ds_read_b128 v[68:71], v147 offset:24576
	ds_read_b128 v[72:75], v147 offset:28672
	s_waitcnt vmcnt(10)
; #define GAS __attribute__((address_space(1)))
; __device__ __forceinline__ void unpack8(const v4u w, float (&f)[8]) { f[0] = bf_lo(w.x); f[1] = bf_hi(w.x); f[2] = bf_lo(w.y); f[3] = bf_hi(w.y); f[4] = bf_lo(w.z); f[5] = bf_hi(w.z); f[6] = bf_lo(w.w); f[7] = bf_hi(w.w); }
; template <int W> __device__ __forceinline__ void pool_group(const bf16* zrow  , const bf16* pw  , bf16* orow  , int pos, bool prev_ok) {
;     ...
;     for (int kk = 0; kk < 4; ++kk) {
;         if (kk < 3) {
; #pragma unroll
;             for (int dt = 0; dt < 8; ++dt) aw[(kk + 1) & 1][dt] = *(const GAS v4u*)(pw + (size_t)16 * dt * 128 + 32 * (kk + 1)); }
;         float own[8], c[8], p[8];
;         unpack8(cw[kk], own); unpack8(pv[kk], p);
; #pragma unroll
;         for (int j = 0; j < 8; ++j) c[j] = own[j];
;         win_step<1>(c, p);
;         if (W >= 4) win_step<2>(c, p);
;         if (W >= 8) win_step<4>(c, p);
;         if (W >= 16) win_step<8>(c, p);
	v_lshlrev_b32_e32 v108, 16, v28
	v_and_b32_e32 v109, 0xffff0000, v28
	v_lshlrev_b32_e32 v110, 16, v29
	v_and_b32_e32 v111, 0xffff0000, v29
	v_lshlrev_b32_e32 v112, 16, v30
	v_and_b32_e32 v113, 0xffff0000, v30
	v_lshlrev_b32_e32 v114, 16, v31
	v_and_b32_e32 v115, 0xffff0000, v31
	v_lshlrev_b32_e32 v124, 16, v32
	v_and_b32_e32 v125, 0xffff0000, v32
	v_lshlrev_b32_e32 v126, 16, v33
	v_and_b32_e32 v127, 0xffff0000, v33
	v_lshlrev_b32_e32 v128, 16, v34
	v_and_b32_e32 v129, 0xffff0000, v34
	v_lshlrev_b32_e32 v130, 16, v35
	v_and_b32_e32 v131, 0xffff0000, v35
	v_cndmask_b32_e64 v124, 0, v124, s[40:41]
	v_cndmask_b32_e64 v125, 0, v125, s[40:41]
	v_cndmask_b32_e64 v126, 0, v126, s[40:41]
	v_cndmask_b32_e64 v127, 0, v127, s[40:41]
	v_cndmask_b32_e64 v128, 0, v128, s[40:41]
	v_cndmask_b32_e64 v129, 0, v129, s[40:41]
	v_cndmask_b32_e64 v130, 0, v130, s[40:41]
	v_cndmask_b32_e64 v131, 0, v131, s[40:41]
	v_mov_b32_e32 v116, v108
	v_mov_b32_e32 v117, v109
	v_mov_b32_e32 v118, v110
	v_mov_b32_e32 v119, v111
	v_mov_b32_e32 v120, v112
	v_mov_b32_e32 v121, v113
	v_mov_b32_e32 v122, v114
	v_mov_b32_e32 v123, v115
	v_add_f32_dpp v132, v116, v116 row_shr:1 row_mask:0xf bank_mask:0xf bound_ctrl:1
	v_add_f32_dpp v116, v124, v132 row_shl:15 row_mask:0xf bank_mask:0xf bound_ctrl:1
	v_add_f32_dpp v124, v124, v124 row_shr:1 row_mask:0xf bank_mask:0xf bound_ctrl:1
	v_add_f32_dpp v132, v117, v117 row_shr:1 row_mask:0xf bank_mask:0xf bound_ctrl:1
	v_add_f32_dpp v117, v125, v132 row_shl:15 row_mask:0xf bank_mask:0xf bound_ctrl:1
	v_add_f32_dpp v125, v125, v125 row_shr:1 row_mask:0xf bank_mask:0xf bound_ctrl:1
	v_add_f32_dpp v132, v118, v118 row_shr:1 row_mask:0xf bank_mask:0xf bound_ctrl:1
	v_add_f32_dpp v118, v126, v132 row_shl:15 row_mask:0xf bank_mask:0xf bound_ctrl:1
	v_add_f32_dpp v126, v126, v126 row_shr:1 row_mask:0xf bank_mask:0xf bound_ctrl:1
	v_add_f32_dpp v132, v119, v119 row_shr:1 row_mask:0xf bank_mask:0xf bound_ctrl:1
	v_add_f32_dpp v119, v127, v132 row_shl:15 row_mask:0xf bank_mask:0xf bound_ctrl:1
	v_add_f32_dpp v127, v127, v127 row_shr:1 row_mask:0xf bank_mask:0xf bound_ctrl:1
	v_add_f32_dpp v132, v120, v120 row_shr:1 row_mask:0xf bank_mask:0xf bound_ctrl:1
	v_add_f32_dpp v120, v128, v132 row_shl:15 row_mask:0xf bank_mask:0xf bound_ctrl:1
	v_add_f32_dpp v128, v128, v128 row_shr:1 row_mask:0xf bank_mask:0xf bound_ctrl:1
	v_add_f32_dpp v132, v121, v121 row_shr:1 row_mask:0xf bank_mask:0xf bound_ctrl:1
	v_add_f32_dpp v121, v129, v132 row_shl:15 row_mask:0xf bank_mask:0xf bound_ctrl:1
	v_add_f32_dpp v129, v129, v129 row_shr:1 row_mask:0xf bank_mask:0xf bound_ctrl:1
	v_add_f32_dpp v132, v122, v122 row_shr:1 row_mask:0xf bank_mask:0xf bound_ctrl:1
	v_add_f32_dpp v122, v130, v132 row_shl:15 row_mask:0xf bank_mask:0xf bound_ctrl:1
	v_add_f32_dpp v130, v130, v130 row_shr:1 row_mask:0xf bank_mask:0xf bound_ctrl:1
	v_add_f32_dpp v132, v123, v123 row_shr:1 row_mask:0xf bank_mask:0xf bound_ctrl:1
	v_add_f32_dpp v123, v131, v132 row_shl:15 row_mask:0xf bank_mask:0xf bound_ctrl:1
	v_add_f32_dpp v131, v131, v131 row_shr:1 row_mask:0xf bank_mask:0xf bound_ctrl:1
	v_add_f32_dpp v132, v116, v116 row_shr:2 row_mask:0xf bank_mask:0xf bound_ctrl:1
	v_add_f32_dpp v116, v124, v132 row_shl:14 row_mask:0xf bank_mask:0xf bound_ctrl:1
	v_add_f32_dpp v124, v124, v124 row_shr:2 row_mask:0xf bank_mask:0xf bound_ctrl:1
	v_add_f32_dpp v132, v117, v117 row_shr:2 row_mask:0xf bank_mask:0xf bound_ctrl:1
	v_add_f32_dpp v117, v125, v132 row_shl:14 row_mask:0xf bank_mask:0xf bound_ctrl:1
	v_add_f32_dpp v125, v125, v125 row_shr:2 row_mask:0xf bank_mask:0xf bound_ctrl:1
	v_add_f32_dpp v132, v118, v118 row_shr:2 row_mask:0xf bank_mask:0xf bound_ctrl:1
	v_add_f32_dpp v118, v126, v132 row_shl:14 row_mask:0xf bank_mask:0xf bound_ctrl:1
	v_add_f32_dpp v126, v126, v126 row_shr:2 row_mask:0xf bank_mask:0xf bound_ctrl:1
	v_add_f32_dpp v132, v119, v119 row_shr:2 row_mask:0xf bank_mask:0xf bound_ctrl:1
	v_add_f32_dpp v119, v127, v132 row_shl:14 row_mask:0xf bank_mask:0xf bound_ctrl:1
	v_add_f32_dpp v127, v127, v127 row_shr:2 row_mask:0xf bank_mask:0xf bound_ctrl:1
	v_add_f32_dpp v132, v120, v120 row_shr:2 row_mask:0xf bank_mask:0xf bound_ctrl:1
	v_add_f32_dpp v120, v128, v132 row_shl:14 row_mask:0xf bank_mask:0xf bound_ctrl:1
	v_add_f32_dpp v128, v128, v128 row_shr:2 row_mask:0xf bank_mask:0xf bound_ctrl:1
	v_add_f32_dpp v132, v121, v121 row_shr:2 row_mask:0xf bank_mask:0xf bound_ctrl:1
	v_add_f32_dpp v121, v129, v132 row_shl:14 row_mask:0xf bank_mask:0xf bound_ctrl:1
	v_add_f32_dpp v129, v129, v129 row_shr:2 row_mask:0xf bank_mask:0xf bound_ctrl:1
	v_add_f32_dpp v132, v122, v122 row_shr:2 row_mask:0xf bank_mask:0xf bound_ctrl:1
	v_add_f32_dpp v122, v130, v132 row_shl:14 row_mask:0xf bank_mask:0xf bound_ctrl:1
	v_add_f32_dpp v130, v130, v130 row_shr:2 row_mask:0xf bank_mask:0xf bound_ctrl:1
	v_add_f32_dpp v132, v123, v123 row_shr:2 row_mask:0xf bank_mask:0xf bound_ctrl:1
	v_add_f32_dpp v123, v131, v132 row_shl:14 row_mask:0xf bank_mask:0xf bound_ctrl:1
	v_add_f32_dpp v131, v131, v131 row_shr:2 row_mask:0xf bank_mask:0xf bound_ctrl:1
	v_add_f32_dpp v132, v116, v116 row_shr:4 row_mask:0xf bank_mask:0xf bound_ctrl:1
	v_add_f32_dpp v116, v124, v132 row_shl:12 row_mask:0xf bank_mask:0xf bound_ctrl:1
	v_add_f32_dpp v124, v124, v124 row_shr:4 row_mask:0xf bank_mask:0xf bound_ctrl:1
	v_add_f32_dpp v132, v117, v117 row_shr:4 row_mask:0xf bank_mask:0xf bound_ctrl:1
	v_add_f32_dpp v117, v125, v132 row_shl:12 row_mask:0xf bank_mask:0xf bound_ctrl:1
	v_add_f32_dpp v125, v125, v125 row_shr:4 row_mask:0xf bank_mask:0xf bound_ctrl:1
	v_add_f32_dpp v132, v118, v118 row_shr:4 row_mask:0xf bank_mask:0xf bound_ctrl:1
; #define GAS __attribute__((address_space(1)))
; __device__ __forceinline__ void unpack8(const v4u w, float (&f)[8]) { f[0] = bf_lo(w.x); f[1] = bf_hi(w.x); f[2] = bf_lo(w.y); f[3] = bf_hi(w.y); f[4] = bf_lo(w.z); f[5] = bf_hi(w.z); f[6] = bf_lo(w.w); f[7] = bf_hi(w.w); }
; __device__ __forceinline__ v4u pack8(const float (&f)[8]) { v4u w; w.x = cvt_pk_bf16(f[0], f[1]); w.y = cvt_pk_bf16(f[2], f[3]); w.z = cvt_pk_bf16(f[4], f[5]); w.w = cvt_pk_bf16(f[6], f[7]); return w; }
; template <int S> __device__ __forceinline__ void win_step(float (&c)[8], float (&p)[8]) {
; #pragma unroll
;     for (int j = 0; j < 8; ++j) { const float cn = c[j] + row_shr<S>(c[j]) + row_shl<16 - S>(p[j]); p[j] += row_shr<S>(p[j]); c[j] = cn; }
; }
; template <int W> __device__ __forceinline__ void pool_group(const bf16* zrow  , const bf16* pw  , bf16* orow  , int pos, bool prev_ok) {
;     const float inv = 1.0f / (float)((pos + 1) < W ? (pos + 1) : W);
;     f32x4 acc[8];
; #pragma unroll
;     for (int dt = 0; dt < 8; ++dt) acc[dt] = (f32x4){0.f, 0.f, 0.f, 0.f};
;     v4u cw[4], pv[4], aw[2][8];
; #pragma unroll
;     for (int kk = 0; kk < 4; ++kk) { cw[kk] = *(const GAS v4u*)(zrow + 32 * kk); pv[kk] = prev_ok ? *(const GAS v4u*)(zrow + 32 * kk - (ptrdiff_t)16 * ZC) : (v4u){0u, 0u, 0u, 0u}; }
; #pragma unroll
;     for (int dt = 0; dt < 8; ++dt) aw[0][dt] = *(const GAS v4u*)(pw + (size_t)16 * dt * 128);
; #pragma unroll
;     for (int kk = 0; kk < 4; ++kk) {
;         if (kk < 3) {
; #pragma unroll
;             for (int dt = 0; dt < 8; ++dt) aw[(kk + 1) & 1][dt] = *(const GAS v4u*)(pw + (size_t)16 * dt * 128 + 32 * (kk + 1)); }
;         float own[8], c[8], p[8];
;         unpack8(cw[kk], own); unpack8(pv[kk], p);
; #pragma unroll
;         for (int j = 0; j < 8; ++j) c[j] = own[j];
;         win_step<1>(c, p);
;         if (W >= 4) win_step<2>(c, p);
;         if (W >= 8) win_step<4>(c, p);
;         if (W >= 16) win_step<8>(c, p);
;         float pl[8];
; #pragma unroll
;         for (int j = 0; j < 8; ++j) pl[j] = c[j] * inv - own[j];
;         const v4u pwk = pack8(pl); const bf16x8 pf = __builtin_bit_cast(bf16x8, pwk);
; #pragma unroll
;         for (int dt = 0; dt < 8; ++dt) acc[dt] = __builtin_amdgcn_mfma_f32_16x16x32_bf16(__builtin_bit_cast(bf16x8, aw[kk & 1][dt]), pf, acc[dt], 0, 0, 0);
	v_add_f32_dpp v118, v126, v132 row_shl:12 row_mask:0xf bank_mask:0xf bound_ctrl:1
	v_add_f32_dpp v126, v126, v126 row_shr:4 row_mask:0xf bank_mask:0xf bound_ctrl:1
	v_add_f32_dpp v132, v119, v119 row_shr:4 row_mask:0xf bank_mask:0xf bound_ctrl:1
	v_add_f32_dpp v119, v127, v132 row_shl:12 row_mask:0xf bank_mask:0xf bound_ctrl:1
	v_add_f32_dpp v127, v127, v127 row_shr:4 row_mask:0xf bank_mask:0xf bound_ctrl:1
	v_add_f32_dpp v132, v120, v120 row_shr:4 row_mask:0xf bank_mask:0xf bound_ctrl:1
	v_add_f32_dpp v120, v128, v132 row_shl:12 row_mask:0xf bank_mask:0xf bound_ctrl:1
	v_add_f32_dpp v128, v128, v128 row_shr:4 row_mask:0xf bank_mask:0xf bound_ctrl:1
	v_add_f32_dpp v132, v121, v121 row_shr:4 row_mask:0xf bank_mask:0xf bound_ctrl:1
	v_add_f32_dpp v121, v129, v132 row_shl:12 row_mask:0xf bank_mask:0xf bound_ctrl:1
	v_add_f32_dpp v129, v129, v129 row_shr:4 row_mask:0xf bank_mask:0xf bound_ctrl:1
	v_add_f32_dpp v132, v122, v122 row_shr:4 row_mask:0xf bank_mask:0xf bound_ctrl:1
	v_add_f32_dpp v122, v130, v132 row_shl:12 row_mask:0xf bank_mask:0xf bound_ctrl:1
	v_add_f32_dpp v130, v130, v130 row_shr:4 row_mask:0xf bank_mask:0xf bound_ctrl:1
	v_add_f32_dpp v132, v123, v123 row_shr:4 row_mask:0xf bank_mask:0xf bound_ctrl:1
	v_add_f32_dpp v123, v131, v132 row_shl:12 row_mask:0xf bank_mask:0xf bound_ctrl:1
	v_add_f32_dpp v131, v131, v131 row_shr:4 row_mask:0xf bank_mask:0xf bound_ctrl:1
	v_add_f32_dpp v132, v116, v116 row_shr:8 row_mask:0xf bank_mask:0xf bound_ctrl:1
	v_add_f32_dpp v116, v124, v132 row_shl:8 row_mask:0xf bank_mask:0xf bound_ctrl:1
	v_add_f32_dpp v124, v124, v124 row_shr:8 row_mask:0xf bank_mask:0xf bound_ctrl:1
	v_add_f32_dpp v132, v117, v117 row_shr:8 row_mask:0xf bank_mask:0xf bound_ctrl:1
	v_add_f32_dpp v117, v125, v132 row_shl:8 row_mask:0xf bank_mask:0xf bound_ctrl:1
	v_add_f32_dpp v125, v125, v125 row_shr:8 row_mask:0xf bank_mask:0xf bound_ctrl:1
	v_add_f32_dpp v132, v118, v118 row_shr:8 row_mask:0xf bank_mask:0xf bound_ctrl:1
	v_add_f32_dpp v118, v126, v132 row_shl:8 row_mask:0xf bank_mask:0xf bound_ctrl:1
	v_add_f32_dpp v126, v126, v126 row_shr:8 row_mask:0xf bank_mask:0xf bound_ctrl:1
	v_add_f32_dpp v132, v119, v119 row_shr:8 row_mask:0xf bank_mask:0xf bound_ctrl:1
	v_add_f32_dpp v119, v127, v132 row_shl:8 row_mask:0xf bank_mask:0xf bound_ctrl:1
	v_add_f32_dpp v127, v127, v127 row_shr:8 row_mask:0xf bank_mask:0xf bound_ctrl:1
	v_add_f32_dpp v132, v120, v120 row_shr:8 row_mask:0xf bank_mask:0xf bound_ctrl:1
	v_add_f32_dpp v120, v128, v132 row_shl:8 row_mask:0xf bank_mask:0xf bound_ctrl:1
	v_add_f32_dpp v128, v128, v128 row_shr:8 row_mask:0xf bank_mask:0xf bound_ctrl:1
	v_add_f32_dpp v132, v121, v121 row_shr:8 row_mask:0xf bank_mask:0xf bound_ctrl:1
	v_add_f32_dpp v121, v129, v132 row_shl:8 row_mask:0xf bank_mask:0xf bound_ctrl:1
	v_add_f32_dpp v129, v129, v129 row_shr:8 row_mask:0xf bank_mask:0xf bound_ctrl:1
	v_add_f32_dpp v132, v122, v122 row_shr:8 row_mask:0xf bank_mask:0xf bound_ctrl:1
	v_add_f32_dpp v122, v130, v132 row_shl:8 row_mask:0xf bank_mask:0xf bound_ctrl:1
	v_add_f32_dpp v130, v130, v130 row_shr:8 row_mask:0xf bank_mask:0xf bound_ctrl:1
	v_add_f32_dpp v132, v123, v123 row_shr:8 row_mask:0xf bank_mask:0xf bound_ctrl:1
	v_add_f32_dpp v123, v131, v132 row_shl:8 row_mask:0xf bank_mask:0xf bound_ctrl:1
	v_add_f32_dpp v131, v131, v131 row_shr:8 row_mask:0xf bank_mask:0xf bound_ctrl:1
	v_fma_f32 v116, v116, v138, -v108
	v_fma_f32 v117, v117, v138, -v109
	v_fma_f32 v118, v118, v138, -v110
	v_fma_f32 v119, v119, v138, -v111
	v_fma_f32 v120, v120, v138, -v112
	v_fma_f32 v121, v121, v138, -v113
	v_fma_f32 v122, v122, v138, -v114
	v_fma_f32 v123, v123, v138, -v115
	v_cvt_pk_bf16_f32 v134, v116, v117
	v_cvt_pk_bf16_f32 v135, v118, v119
	v_cvt_pk_bf16_f32 v136, v120, v121
	v_cvt_pk_bf16_f32 v137, v122, v123
	s_waitcnt lgkmcnt(0)
	s_nop 0
	v_mfma_f32_16x16x32_bf16 v[76:79], v[44:47], v[134:137], v[76:79]
	v_mfma_f32_16x16x32_bf16 v[80:83], v[48:51], v[134:137], v[80:83]
	v_mfma_f32_16x16x32_bf16 v[84:87], v[52:55], v[134:137], v[84:87]
	v_mfma_f32_16x16x32_bf16 v[88:91], v[56:59], v[134:137], v[88:91]
	v_mfma_f32_16x16x32_bf16 v[92:95], v[60:63], v[134:137], v[92:95]
	v_mfma_f32_16x16x32_bf16 v[96:99], v[64:67], v[134:137], v[96:99]
	v_mfma_f32_16x16x32_bf16 v[100:103], v[68:71], v[134:137], v[100:103]
	v_mfma_f32_16x16x32_bf16 v[104:107], v[72:75], v[134:137], v[104:107]
	v_add_u32_e32 v147, 98304, v146
	ds_read_b128 v[44:47], v147
	ds_read_b128 v[48:51], v147 offset:4096
	ds_read_b128 v[52:55], v147 offset:8192
	ds_read_b128 v[56:59], v147 offset:12288
	ds_read_b128 v[60:63], v147 offset:16384
	ds_read_b128 v[64:67], v147 offset:20480
	ds_read_b128 v[68:71], v147 offset:24576
	ds_read_b128 v[72:75], v147 offset:28672
	s_waitcnt vmcnt(8)
; #define GAS __attribute__((address_space(1)))
; __device__ __forceinline__ void unpack8(const v4u w, float (&f)[8]) { f[0] = bf_lo(w.x); f[1] = bf_hi(w.x); f[2] = bf_lo(w.y); f[3] = bf_hi(w.y); f[4] = bf_lo(w.z); f[5] = bf_hi(w.z); f[6] = bf_lo(w.w); f[7] = bf_hi(w.w); }
; template <int W> __device__ __forceinline__ void pool_group(const bf16* zrow  , const bf16* pw  , bf16* orow  , int pos, bool prev_ok) {
;     ...
;     for (int kk = 0; kk < 4; ++kk) {
;         if (kk < 3) {
; #pragma unroll
;             for (int dt = 0; dt < 8; ++dt) aw[(kk + 1) & 1][dt] = *(const GAS v4u*)(pw + (size_t)16 * dt * 128 + 32 * (kk + 1)); }
;         float own[8], c[8], p[8];
;         unpack8(cw[kk], own); unpack8(pv[kk], p);
; #pragma unroll
;         for (int j = 0; j < 8; ++j) c[j] = own[j];
;         win_step<1>(c, p);
;         if (W >= 4) win_step<2>(c, p);
;         if (W >= 8) win_step<4>(c, p);
;         if (W >= 16) win_step<8>(c, p);
	v_lshlrev_b32_e32 v108, 16, v36
	v_and_b32_e32 v109, 0xffff0000, v36
	v_lshlrev_b32_e32 v110, 16, v37
	v_and_b32_e32 v111, 0xffff0000, v37
	v_lshlrev_b32_e32 v112, 16, v38
	v_and_b32_e32 v113, 0xffff0000, v38
	v_lshlrev_b32_e32 v114, 16, v39
	v_and_b32_e32 v115, 0xffff0000, v39
	v_lshlrev_b32_e32 v124, 16, v40
	v_and_b32_e32 v125, 0xffff0000, v40
	v_lshlrev_b32_e32 v126, 16, v41
	v_and_b32_e32 v127, 0xffff0000, v41
	v_lshlrev_b32_e32 v128, 16, v42
	v_and_b32_e32 v129, 0xffff0000, v42
	v_lshlrev_b32_e32 v130, 16, v43
	v_and_b32_e32 v131, 0xffff0000, v43
	v_cndmask_b32_e64 v124, 0, v124, s[40:41]
	v_cndmask_b32_e64 v125, 0, v125, s[40:41]
	v_cndmask_b32_e64 v126, 0, v126, s[40:41]
	v_cndmask_b32_e64 v127, 0, v127, s[40:41]
	v_cndmask_b32_e64 v128, 0, v128, s[40:41]
	v_cndmask_b32_e64 v129, 0, v129, s[40:41]
	v_cndmask_b32_e64 v130, 0, v130, s[40:41]
	v_cndmask_b32_e64 v131, 0, v131, s[40:41]
	v_mov_b32_e32 v116, v108
	v_mov_b32_e32 v117, v109
	v_mov_b32_e32 v118, v110
	v_mov_b32_e32 v119, v111
	v_mov_b32_e32 v120, v112
	v_mov_b32_e32 v121, v113
	v_mov_b32_e32 v122, v114
	v_mov_b32_e32 v123, v115
	v_add_f32_dpp v132, v116, v116 row_shr:1 row_mask:0xf bank_mask:0xf bound_ctrl:1
	v_add_f32_dpp v116, v124, v132 row_shl:15 row_mask:0xf bank_mask:0xf bound_ctrl:1
	v_add_f32_dpp v124, v124, v124 row_shr:1 row_mask:0xf bank_mask:0xf bound_ctrl:1
	v_add_f32_dpp v132, v117, v117 row_shr:1 row_mask:0xf bank_mask:0xf bound_ctrl:1
	v_add_f32_dpp v117, v125, v132 row_shl:15 row_mask:0xf bank_mask:0xf bound_ctrl:1
	v_add_f32_dpp v125, v125, v125 row_shr:1 row_mask:0xf bank_mask:0xf bound_ctrl:1
	v_add_f32_dpp v132, v118, v118 row_shr:1 row_mask:0xf bank_mask:0xf bound_ctrl:1
	v_add_f32_dpp v118, v126, v132 row_shl:15 row_mask:0xf bank_mask:0xf bound_ctrl:1
	v_add_f32_dpp v126, v126, v126 row_shr:1 row_mask:0xf bank_mask:0xf bound_ctrl:1
	v_add_f32_dpp v132, v119, v119 row_shr:1 row_mask:0xf bank_mask:0xf bound_ctrl:1
	v_add_f32_dpp v119, v127, v132 row_shl:15 row_mask:0xf bank_mask:0xf bound_ctrl:1
	v_add_f32_dpp v127, v127, v127 row_shr:1 row_mask:0xf bank_mask:0xf bound_ctrl:1
	v_add_f32_dpp v132, v120, v120 row_shr:1 row_mask:0xf bank_mask:0xf bound_ctrl:1
	v_add_f32_dpp v120, v128, v132 row_shl:15 row_mask:0xf bank_mask:0xf bound_ctrl:1
	v_add_f32_dpp v128, v128, v128 row_shr:1 row_mask:0xf bank_mask:0xf bound_ctrl:1
	v_add_f32_dpp v132, v121, v121 row_shr:1 row_mask:0xf bank_mask:0xf bound_ctrl:1
	v_add_f32_dpp v121, v129, v132 row_shl:15 row_mask:0xf bank_mask:0xf bound_ctrl:1
	v_add_f32_dpp v129, v129, v129 row_shr:1 row_mask:0xf bank_mask:0xf bound_ctrl:1
	v_add_f32_dpp v132, v122, v122 row_shr:1 row_mask:0xf bank_mask:0xf bound_ctrl:1
	v_add_f32_dpp v122, v130, v132 row_shl:15 row_mask:0xf bank_mask:0xf bound_ctrl:1
	v_add_f32_dpp v130, v130, v130 row_shr:1 row_mask:0xf bank_mask:0xf bound_ctrl:1
	v_add_f32_dpp v132, v123, v123 row_shr:1 row_mask:0xf bank_mask:0xf bound_ctrl:1
	v_add_f32_dpp v123, v131, v132 row_shl:15 row_mask:0xf bank_mask:0xf bound_ctrl:1
	v_add_f32_dpp v131, v131, v131 row_shr:1 row_mask:0xf bank_mask:0xf bound_ctrl:1
	v_add_f32_dpp v132, v116, v116 row_shr:2 row_mask:0xf bank_mask:0xf bound_ctrl:1
	v_add_f32_dpp v116, v124, v132 row_shl:14 row_mask:0xf bank_mask:0xf bound_ctrl:1
	v_add_f32_dpp v124, v124, v124 row_shr:2 row_mask:0xf bank_mask:0xf bound_ctrl:1
	v_add_f32_dpp v132, v117, v117 row_shr:2 row_mask:0xf bank_mask:0xf bound_ctrl:1
	v_add_f32_dpp v117, v125, v132 row_shl:14 row_mask:0xf bank_mask:0xf bound_ctrl:1
	v_add_f32_dpp v125, v125, v125 row_shr:2 row_mask:0xf bank_mask:0xf bound_ctrl:1
	v_add_f32_dpp v132, v118, v118 row_shr:2 row_mask:0xf bank_mask:0xf bound_ctrl:1
	v_add_f32_dpp v118, v126, v132 row_shl:14 row_mask:0xf bank_mask:0xf bound_ctrl:1
	v_add_f32_dpp v126, v126, v126 row_shr:2 row_mask:0xf bank_mask:0xf bound_ctrl:1
	v_add_f32_dpp v132, v119, v119 row_shr:2 row_mask:0xf bank_mask:0xf bound_ctrl:1
	v_add_f32_dpp v119, v127, v132 row_shl:14 row_mask:0xf bank_mask:0xf bound_ctrl:1
	v_add_f32_dpp v127, v127, v127 row_shr:2 row_mask:0xf bank_mask:0xf bound_ctrl:1
	v_add_f32_dpp v132, v120, v120 row_shr:2 row_mask:0xf bank_mask:0xf bound_ctrl:1
	v_add_f32_dpp v120, v128, v132 row_shl:14 row_mask:0xf bank_mask:0xf bound_ctrl:1
	v_add_f32_dpp v128, v128, v128 row_shr:2 row_mask:0xf bank_mask:0xf bound_ctrl:1
	v_add_f32_dpp v132, v121, v121 row_shr:2 row_mask:0xf bank_mask:0xf bound_ctrl:1
	v_add_f32_dpp v121, v129, v132 row_shl:14 row_mask:0xf bank_mask:0xf bound_ctrl:1
	v_add_f32_dpp v129, v129, v129 row_shr:2 row_mask:0xf bank_mask:0xf bound_ctrl:1
	v_add_f32_dpp v132, v122, v122 row_shr:2 row_mask:0xf bank_mask:0xf bound_ctrl:1
	v_add_f32_dpp v122, v130, v132 row_shl:14 row_mask:0xf bank_mask:0xf bound_ctrl:1
	v_add_f32_dpp v130, v130, v130 row_shr:2 row_mask:0xf bank_mask:0xf bound_ctrl:1
	v_add_f32_dpp v132, v123, v123 row_shr:2 row_mask:0xf bank_mask:0xf bound_ctrl:1
	v_add_f32_dpp v123, v131, v132 row_shl:14 row_mask:0xf bank_mask:0xf bound_ctrl:1
	v_add_f32_dpp v131, v131, v131 row_shr:2 row_mask:0xf bank_mask:0xf bound_ctrl:1
	v_add_f32_dpp v132, v116, v116 row_shr:4 row_mask:0xf bank_mask:0xf bound_ctrl:1
	v_add_f32_dpp v116, v124, v132 row_shl:12 row_mask:0xf bank_mask:0xf bound_ctrl:1
	v_add_f32_dpp v124, v124, v124 row_shr:4 row_mask:0xf bank_mask:0xf bound_ctrl:1
	v_add_f32_dpp v132, v117, v117 row_shr:4 row_mask:0xf bank_mask:0xf bound_ctrl:1
	v_add_f32_dpp v117, v125, v132 row_shl:12 row_mask:0xf bank_mask:0xf bound_ctrl:1
	v_add_f32_dpp v125, v125, v125 row_shr:4 row_mask:0xf bank_mask:0xf bound_ctrl:1
	v_add_f32_dpp v132, v118, v118 row_shr:4 row_mask:0xf bank_mask:0xf bound_ctrl:1
; __device__ __forceinline__ unsigned cvt_pk_bf16(float lo, float hi) { return __builtin_bit_cast(unsigned, __builtin_convertvector((f32x2_t){lo, hi}, bf16x2_t)); }
; #define GAS __attribute__((address_space(1)))
; template <int S> __device__ __forceinline__ void win_step(float (&c)[8], float (&p)[8]) {
; #pragma unroll
;     for (int j = 0; j < 8; ++j) { const float cn = c[j] + row_shr<S>(c[j]) + row_shl<16 - S>(p[j]); p[j] += row_shr<S>(p[j]); c[j] = cn; }
; }
; template <int W> __device__ __forceinline__ void pool_group(const bf16* zrow  , const bf16* pw  , bf16* orow  , int pos, bool prev_ok) {
;     const float inv = 1.0f / (float)((pos + 1) < W ? (pos + 1) : W);
;     f32x4 acc[8];
; #pragma unroll
;     for (int dt = 0; dt < 8; ++dt) acc[dt] = (f32x4){0.f, 0.f, 0.f, 0.f};
;     v4u cw[4], pv[4], aw[2][8];
; #pragma unroll
;     for (int kk = 0; kk < 4; ++kk) { cw[kk] = *(const GAS v4u*)(zrow + 32 * kk); pv[kk] = prev_ok ? *(const GAS v4u*)(zrow + 32 * kk - (ptrdiff_t)16 * ZC) : (v4u){0u, 0u, 0u, 0u}; }
; #pragma unroll
;     for (int dt = 0; dt < 8; ++dt) aw[0][dt] = *(const GAS v4u*)(pw + (size_t)16 * dt * 128);
; #pragma unroll
;     for (int kk = 0; kk < 4; ++kk) {
;         if (kk < 3) {
; #pragma unroll
;             for (int dt = 0; dt < 8; ++dt) aw[(kk + 1) & 1][dt] = *(const GAS v4u*)(pw + (size_t)16 * dt * 128 + 32 * (kk + 1)); }
;         float own[8], c[8], p[8];
;         unpack8(cw[kk], own); unpack8(pv[kk], p);
; #pragma unroll
;         for (int j = 0; j < 8; ++j) c[j] = own[j];
;         win_step<1>(c, p);
;         if (W >= 4) win_step<2>(c, p);
;         if (W >= 8) win_step<4>(c, p);
;         if (W >= 16) win_step<8>(c, p);
;         float pl[8];
; #pragma unroll
;         for (int j = 0; j < 8; ++j) pl[j] = c[j] * inv - own[j];
;         const v4u pwk = pack8(pl); const bf16x8 pf = __builtin_bit_cast(bf16x8, pwk);
; #pragma unroll
;         for (int dt = 0; dt < 8; ++dt) acc[dt] = __builtin_amdgcn_mfma_f32_16x16x32_bf16(__builtin_bit_cast(bf16x8, aw[kk & 1][dt]), pf, acc[dt], 0, 0, 0);
;     }
; #pragma unroll
;     for (int dt = 0; dt < 8; ++dt) { v2u w; w.x = cvt_pk_bf16(acc[dt][0], acc[dt][1]); w.y = cvt_pk_bf16(acc[dt][2], acc[dt][3]); *(GAS v2u*)(orow + 16 * dt) = w; }
	v_add_f32_dpp v118, v126, v132 row_shl:12 row_mask:0xf bank_mask:0xf bound_ctrl:1
	v_add_f32_dpp v126, v126, v126 row_shr:4 row_mask:0xf bank_mask:0xf bound_ctrl:1
	v_add_f32_dpp v132, v119, v119 row_shr:4 row_mask:0xf bank_mask:0xf bound_ctrl:1
	v_add_f32_dpp v119, v127, v132 row_shl:12 row_mask:0xf bank_mask:0xf bound_ctrl:1
	v_add_f32_dpp v127, v127, v127 row_shr:4 row_mask:0xf bank_mask:0xf bound_ctrl:1
	v_add_f32_dpp v132, v120, v120 row_shr:4 row_mask:0xf bank_mask:0xf bound_ctrl:1
	v_add_f32_dpp v120, v128, v132 row_shl:12 row_mask:0xf bank_mask:0xf bound_ctrl:1
	v_add_f32_dpp v128, v128, v128 row_shr:4 row_mask:0xf bank_mask:0xf bound_ctrl:1
	v_add_f32_dpp v132, v121, v121 row_shr:4 row_mask:0xf bank_mask:0xf bound_ctrl:1
	v_add_f32_dpp v121, v129, v132 row_shl:12 row_mask:0xf bank_mask:0xf bound_ctrl:1
	v_add_f32_dpp v129, v129, v129 row_shr:4 row_mask:0xf bank_mask:0xf bound_ctrl:1
	v_add_f32_dpp v132, v122, v122 row_shr:4 row_mask:0xf bank_mask:0xf bound_ctrl:1
	v_add_f32_dpp v122, v130, v132 row_shl:12 row_mask:0xf bank_mask:0xf bound_ctrl:1
	v_add_f32_dpp v130, v130, v130 row_shr:4 row_mask:0xf bank_mask:0xf bound_ctrl:1
	v_add_f32_dpp v132, v123, v123 row_shr:4 row_mask:0xf bank_mask:0xf bound_ctrl:1
	v_add_f32_dpp v123, v131, v132 row_shl:12 row_mask:0xf bank_mask:0xf bound_ctrl:1
	v_add_f32_dpp v131, v131, v131 row_shr:4 row_mask:0xf bank_mask:0xf bound_ctrl:1
	v_add_f32_dpp v132, v116, v116 row_shr:8 row_mask:0xf bank_mask:0xf bound_ctrl:1
	v_add_f32_dpp v116, v124, v132 row_shl:8 row_mask:0xf bank_mask:0xf bound_ctrl:1
	v_add_f32_dpp v124, v124, v124 row_shr:8 row_mask:0xf bank_mask:0xf bound_ctrl:1
	v_add_f32_dpp v132, v117, v117 row_shr:8 row_mask:0xf bank_mask:0xf bound_ctrl:1
	v_add_f32_dpp v117, v125, v132 row_shl:8 row_mask:0xf bank_mask:0xf bound_ctrl:1
	v_add_f32_dpp v125, v125, v125 row_shr:8 row_mask:0xf bank_mask:0xf bound_ctrl:1
	v_add_f32_dpp v132, v118, v118 row_shr:8 row_mask:0xf bank_mask:0xf bound_ctrl:1
	v_add_f32_dpp v118, v126, v132 row_shl:8 row_mask:0xf bank_mask:0xf bound_ctrl:1
	v_add_f32_dpp v126, v126, v126 row_shr:8 row_mask:0xf bank_mask:0xf bound_ctrl:1
	v_add_f32_dpp v132, v119, v119 row_shr:8 row_mask:0xf bank_mask:0xf bound_ctrl:1
	v_add_f32_dpp v119, v127, v132 row_shl:8 row_mask:0xf bank_mask:0xf bound_ctrl:1
	v_add_f32_dpp v127, v127, v127 row_shr:8 row_mask:0xf bank_mask:0xf bound_ctrl:1
	v_add_f32_dpp v132, v120, v120 row_shr:8 row_mask:0xf bank_mask:0xf bound_ctrl:1
	v_add_f32_dpp v120, v128, v132 row_shl:8 row_mask:0xf bank_mask:0xf bound_ctrl:1
	v_add_f32_dpp v128, v128, v128 row_shr:8 row_mask:0xf bank_mask:0xf bound_ctrl:1
	v_add_f32_dpp v132, v121, v121 row_shr:8 row_mask:0xf bank_mask:0xf bound_ctrl:1
	v_add_f32_dpp v121, v129, v132 row_shl:8 row_mask:0xf bank_mask:0xf bound_ctrl:1
	v_add_f32_dpp v129, v129, v129 row_shr:8 row_mask:0xf bank_mask:0xf bound_ctrl:1
	v_add_f32_dpp v132, v122, v122 row_shr:8 row_mask:0xf bank_mask:0xf bound_ctrl:1
	v_add_f32_dpp v122, v130, v132 row_shl:8 row_mask:0xf bank_mask:0xf bound_ctrl:1
	v_add_f32_dpp v130, v130, v130 row_shr:8 row_mask:0xf bank_mask:0xf bound_ctrl:1
	v_add_f32_dpp v132, v123, v123 row_shr:8 row_mask:0xf bank_mask:0xf bound_ctrl:1
	v_add_f32_dpp v123, v131, v132 row_shl:8 row_mask:0xf bank_mask:0xf bound_ctrl:1
	v_add_f32_dpp v131, v131, v131 row_shr:8 row_mask:0xf bank_mask:0xf bound_ctrl:1
	v_fma_f32 v116, v116, v138, -v108
	v_fma_f32 v117, v117, v138, -v109
	v_fma_f32 v118, v118, v138, -v110
	v_fma_f32 v119, v119, v138, -v111
	v_fma_f32 v120, v120, v138, -v112
	v_fma_f32 v121, v121, v138, -v113
	v_fma_f32 v122, v122, v138, -v114
	v_fma_f32 v123, v123, v138, -v115
	v_cvt_pk_bf16_f32 v134, v116, v117
	v_cvt_pk_bf16_f32 v135, v118, v119
	v_cvt_pk_bf16_f32 v136, v120, v121
	v_cvt_pk_bf16_f32 v137, v122, v123
	s_waitcnt lgkmcnt(0)
	s_nop 0
	v_mfma_f32_16x16x32_bf16 v[76:79], v[44:47], v[134:137], v[76:79]
	v_mfma_f32_16x16x32_bf16 v[80:83], v[48:51], v[134:137], v[80:83]
	v_mfma_f32_16x16x32_bf16 v[84:87], v[52:55], v[134:137], v[84:87]
	v_mfma_f32_16x16x32_bf16 v[88:91], v[56:59], v[134:137], v[88:91]
	v_mfma_f32_16x16x32_bf16 v[92:95], v[60:63], v[134:137], v[92:95]
	v_mfma_f32_16x16x32_bf16 v[96:99], v[64:67], v[134:137], v[96:99]
	v_mfma_f32_16x16x32_bf16 v[100:103], v[68:71], v[134:137], v[100:103]
	v_mfma_f32_16x16x32_bf16 v[104:107], v[72:75], v[134:137], v[104:107]
	s_nop 7
	s_nop 1
	v_cvt_pk_bf16_f32 v132, v76, v77
	v_cvt_pk_bf16_f32 v133, v78, v79
	global_store_dwordx2 v142, v[132:133], s[46:47] offset:768
	s_nop 0
	v_cvt_pk_bf16_f32 v132, v80, v81
	v_cvt_pk_bf16_f32 v133, v82, v83
	global_store_dwordx2 v142, v[132:133], s[46:47] offset:800
	s_nop 0
	v_cvt_pk_bf16_f32 v132, v84, v85
	v_cvt_pk_bf16_f32 v133, v86, v87
	global_store_dwordx2 v142, v[132:133], s[46:47] offset:832
	s_nop 0
	v_cvt_pk_bf16_f32 v132, v88, v89
	v_cvt_pk_bf16_f32 v133, v90, v91
	global_store_dwordx2 v142, v[132:133], s[46:47] offset:864
	s_nop 0
	v_cvt_pk_bf16_f32 v132, v92, v93
	v_cvt_pk_bf16_f32 v133, v94, v95
	global_store_dwordx2 v142, v[132:133], s[46:47] offset:896
	s_nop 0
	v_cvt_pk_bf16_f32 v132, v96, v97
	v_cvt_pk_bf16_f32 v133, v98, v99
	global_store_dwordx2 v142, v[132:133], s[46:47] offset:928
	s_nop 0
	v_cvt_pk_bf16_f32 v132, v100, v101
	v_cvt_pk_bf16_f32 v133, v102, v103
	global_store_dwordx2 v142, v[132:133], s[46:47] offset:960
	s_nop 0
	v_cvt_pk_bf16_f32 v132, v104, v105
	v_cvt_pk_bf16_f32 v133, v106, v107
	global_store_dwordx2 v142, v[132:133], s[46:47] offset:992
	s_nop 0
	s_waitcnt lgkmcnt(0)
	s_barrier
; #define GAS __attribute__((address_space(1)))
; __device__ __forceinline__ int lane_opaque() { int l; asm volatile("v_mbcnt_lo_u32_b32 %0, -1, 0\n\tv_mbcnt_hi_u32_b32 %0, -1, %0" : "=v"(l)); return l; }
; __device__ __forceinline__ void mixer_sgu(const Frame& F, const Args& A, int l, int chunk, const bf16* Z, bf16* MIX) {
;     const int lane = lane_opaque(), tid = F.wave * 64 + lane;
;     const int row0 = chunk * 128;
;     const bf16* wsb = (const bf16*)(F.ws + WS_WSB) + (size_t)l * 4 * 128 * 128;
;     const int t1 = tid >> 2, q = tid & 3, i = lane & 15, g4 = lane >> 4, w = F.wave, t2 = 16 * w + i, kkmax = w >> 1;
;     const bf16* zv = Z + (size_t)(row0 + t1) * ZC + 512 + 32 * q;
;     const bf16* zu = Z + (size_t)(row0 + t2) * ZC + 4 * g4;
;     bf16* mo = MIX + (size_t)(row0 + t2) * D + 4 * g4;
;     v4u vr[4];
; #pragma unroll
;     for (int j = 0; j < 4; ++j) vr[j] = *(const GAS v4u*)(zv + 8 * j);
	s_mov_b32 s52, 0
	s_mov_b64 s[44:45], 0
	s_mov_b64 s[46:47], 0
	v_mbcnt_lo_u32_b32 v1, -1, 0
	v_mbcnt_hi_u32_b32 v1, -1, v1
	v_mov_b32_e32 v7, v0
	v_add_u32_e32 v2, s77, v1
	v_ashrrev_i32_e32 v76, 2, v2
	v_lshlrev_b32_e32 v6, 5, v1
	v_add_u32_e32 v4, s21, v76
	v_mov_b64_e32 v[2:3], s[82:83]
	v_and_b32_e32 v26, 0x60, v6
	v_mad_i64_i32 v[4:5], s[36:37], v4, s33, v[2:3]
	v_lshlrev_b32_e32 v6, 1, v26
	v_lshl_add_u64 v[16:17], v[4:5], 0, v[6:7]
	global_load_dwordx4 v[4:7], v[16:17], off offset:1072
	global_load_dwordx4 v[8:11], v[16:17], off offset:1056
	global_load_dwordx4 v[12:15], v[16:17], off offset:1040
	s_nop 0
	global_load_dwordx4 v[16:19], v[16:17], off offset:1024
	v_and_b32_e32 v27, 15, v1
	v_ashrrev_i32_e32 v28, 4, v1
	v_or_b32_e32 v60, s56, v27
	v_add_u32_e32 v20, s21, v60
	v_lshlrev_b32_e32 v22, 2, v28
	v_ashrrev_i32_e32 v21, 31, v20
	v_ashrrev_i32_e32 v23, 31, v22
	v_lshlrev_b64 v[24:25], 12, v[20:21]
	v_mad_i64_i32 v[2:3], s[36:37], v20, s33, v[2:3]
	v_lshlrev_b64 v[20:21], 1, v[22:23]
	v_lshl_add_u64 v[62:63], v[2:3], 0, v[20:21]
	v_lshlrev_b32_e32 v2, 3, v28
	v_ashrrev_i32_e32 v3, 31, v2
	v_lshl_add_u64 v[66:67], v[2:3], 1, s[8:9]
	v_mad_i64_i32 v[2:3], s[36:37], v76, s33, 0
	v_lshl_add_u64 v[24:25], s[2:3], 0, v[24:25]
	v_and_b32_e32 v77, -16, v1
	v_mad_u64_u32 v[2:3], s[36:37], s5, v225, v[2:3]
	v_and_b32_e32 v1, 3, v1
	v_lshl_add_u64 v[64:65], v[24:25], 0, v[20:21]
	v_lshl_or_b32 v2, v1, 6, v2
	v_add_u32_e32 v20, s56, v27
	v_lshl_add_u64 v[68:69], s[96:97], 0, v[2:3]
	v_lshlrev_b32_e32 v2, 7, v1
	v_mov_b32_e32 v3, v0
	v_ashrrev_i32_e32 v21, 31, v20
	v_ashrrev_i32_e32 v61, 31, v60
	v_mul_u32_u24_e32 v78, 0x110, v26
	v_mul_u32_u24_e32 v79, 0x110, v27
	v_lshl_add_u64 v[70:71], s[60:61], 0, v[2:3]
	v_lshl_add_u64 v[72:73], v[20:21], 2, s[66:67]
	v_lshl_add_u64 v[74:75], s[62:63], 0, v[2:3]
	s_waitcnt vmcnt(0)
	s_branch .LBB0_338

; __device__ __forceinline__ float sum_xor1_2(float v) { v += dpp_f<0xB1>(v); v += dpp_f<0x4E>(v); return v; }
; #define GAS __attribute__((address_space(1)))
; #define LAS __attribute__((address_space(3)))
; __device__ __forceinline__ void unpack8(const v4u w, float (&f)[8]) { f[0] = bf_lo(w.x); f[1] = bf_hi(w.x); f[2] = bf_lo(w.y); f[3] = bf_hi(w.y); f[4] = bf_lo(w.z); f[5] = bf_hi(w.z); f[6] = bf_lo(w.w); f[7] = bf_hi(w.w); }
; __device__ __forceinline__ void mixer_sgu(const Frame& F, const Args& A, int l, int chunk, const bf16* Z, bf16* MIX) {
;     ...
;     for (int hd = 0; hd < 4; ++hd) {
;         LAS bf16* VT = (LAS bf16*)(F.lds + (hd & 1) * (128 * VT_STRIDE * 2));
;         {
;             const float* lg = A.in[4] + (size_t)(l * 4 + hd) * 128 + 32 * q; const float* lb = A.in[5] + (size_t)(l * 4 + hd) * 128 + 32 * q;
;             f32x4 g4v[8], b4v[8];
; #pragma unroll
;             for (int j = 0; j < 8; ++j) { g4v[j] = *(const GAS f32x4*)(lg + 4 * j); b4v[j] = *(const GAS f32x4*)(lb + 4 * j); }
;             float v[32];
; #pragma unroll
;             for (int j = 0; j < 4; ++j) { float f[8]; unpack8(vr[j], f);
; #pragma unroll
;                 for (int e = 0; e < 8; ++e) v[8 * j + e] = f[e]; }
;             float s = 0.f;
; #pragma unroll
;             for (int j = 0; j < 32; ++j) s += v[j];
;             s = pg8::sum_xor1_2(s);
;             const float mean = s * (1.0f / 128.0f); float s2 = 0.f;
; #pragma unroll
;             for (int j = 0; j < 32; ++j) { v[j] -= mean; s2 += v[j] * v[j]; }
;             s2 = pg8::sum_xor1_2(s2);
;             const float rstd = __builtin_amdgcn_rsqf(s2 * (1.0f / 128.0f) + EPS);
.LBB0_338:
	v_lshl_add_u64 v[2:3], v[70:71], 0, s[44:45]
	s_waitcnt vmcnt(8)
	v_lshlrev_b32_e32 v1, 16, v16
	v_lshl_add_u64 v[100:101], v[74:75], 0, s[44:45]
	global_load_dwordx4 v[44:47], v[2:3], off offset:48
	global_load_dwordx4 v[52:55], v[2:3], off offset:32
	global_load_dwordx4 v[80:83], v[2:3], off offset:16
	global_load_dwordx4 v[84:87], v[2:3], off
	global_load_dwordx4 v[48:51], v[100:101], off offset:48
	global_load_dwordx4 v[56:59], v[100:101], off offset:32
	global_load_dwordx4 v[88:91], v[100:101], off offset:16
	global_load_dwordx4 v[92:95], v[100:101], off
	global_load_dwordx4 v[20:23], v[2:3], off offset:112
	global_load_dwordx4 v[24:27], v[2:3], off offset:96
	global_load_dwordx4 v[28:31], v[2:3], off offset:80
	global_load_dwordx4 v[36:39], v[2:3], off offset:64
	global_load_dwordx4 v[32:35], v[100:101], off offset:80
	global_load_dwordx4 v[40:43], v[100:101], off offset:64
	v_and_b32_e32 v2, 0xffff0000, v16
	v_add_f32_e32 v96, 0, v1
	v_lshlrev_b32_e32 v3, 16, v17
	v_add_f32_e32 v96, v96, v2
	v_and_b32_e32 v104, 0xffff0000, v17
	v_add_f32_e32 v96, v96, v3
	v_lshlrev_b32_e32 v105, 16, v18
	v_add_f32_e32 v96, v96, v104
	v_and_b32_e32 v106, 0xffff0000, v18
	v_add_f32_e32 v96, v96, v105
	v_lshlrev_b32_e32 v107, 16, v19
	v_add_f32_e32 v96, v96, v106
	v_and_b32_e32 v108, 0xffff0000, v19
	v_add_f32_e32 v96, v96, v107
	v_lshlrev_b32_e32 v109, 16, v12
	v_add_f32_e32 v96, v96, v108
	v_and_b32_e32 v110, 0xffff0000, v12
	v_add_f32_e32 v96, v96, v109
	v_lshlrev_b32_e32 v111, 16, v13
	v_add_f32_e32 v96, v96, v110
	v_and_b32_e32 v112, 0xffff0000, v13
	v_add_f32_e32 v96, v96, v111
	v_lshlrev_b32_e32 v113, 16, v14
	v_add_f32_e32 v96, v96, v112
	v_and_b32_e32 v114, 0xffff0000, v14
	v_add_f32_e32 v96, v96, v113
	v_lshlrev_b32_e32 v115, 16, v15
	v_add_f32_e32 v96, v96, v114
	v_and_b32_e32 v116, 0xffff0000, v15
	v_add_f32_e32 v96, v96, v115
	v_lshlrev_b32_e32 v117, 16, v8
	v_add_f32_e32 v96, v96, v116
	v_and_b32_e32 v118, 0xffff0000, v8
	v_add_f32_e32 v96, v96, v117
	v_lshlrev_b32_e32 v119, 16, v9
	v_add_f32_e32 v96, v96, v118
	v_and_b32_e32 v120, 0xffff0000, v9
	v_add_f32_e32 v96, v96, v119
	v_lshlrev_b32_e32 v121, 16, v10
	v_add_f32_e32 v96, v96, v120
	v_and_b32_e32 v122, 0xffff0000, v10
	v_add_f32_e32 v96, v96, v121
	v_lshlrev_b32_e32 v123, 16, v11
	v_add_f32_e32 v96, v96, v122
	v_and_b32_e32 v124, 0xffff0000, v11
	v_add_f32_e32 v96, v96, v123
	v_lshlrev_b32_e32 v125, 16, v4
	v_add_f32_e32 v96, v96, v124
	v_and_b32_e32 v126, 0xffff0000, v4
	v_add_f32_e32 v96, v96, v125
	v_lshlrev_b32_e32 v127, 16, v5
	v_add_f32_e32 v96, v96, v126
	v_and_b32_e32 v128, 0xffff0000, v5
	v_add_f32_e32 v96, v96, v127
	v_lshlrev_b32_e32 v129, 16, v6
	v_add_f32_e32 v96, v96, v128
	v_and_b32_e32 v130, 0xffff0000, v6
	v_add_f32_e32 v96, v96, v129
	v_lshlrev_b32_e32 v131, 16, v7
	v_add_f32_e32 v96, v96, v130
	v_and_b32_e32 v132, 0xffff0000, v7
	v_add_f32_e32 v96, v96, v131
	v_add_f32_e32 v96, v96, v132
	s_bitcmp1_b32 s52, 0
	s_cselect_b32 s5, 0x8800, 0
	v_add_f32_dpp v96, v96, v96 quad_perm:[1,0,3,2] row_mask:0xf bank_mask:0xf bound_ctrl:1
	s_add_i32 s5, s5, 0
	v_lshlrev_b32_e32 v134, 1, v76
	v_add_f32_dpp v96, v96, v96 quad_perm:[2,3,0,1] row_mask:0xf bank_mask:0xf bound_ctrl:1
	v_fmac_f32_e32 v2, 0xbc000000, v96
	v_fmac_f32_e32 v1, 0xbc000000, v96
	v_mul_f32_e32 v97, v2, v2
	v_fmac_f32_e32 v97, v1, v1
	v_fmac_f32_e32 v3, 0xbc000000, v96
	v_fmac_f32_e32 v97, v3, v3
	v_fmac_f32_e32 v104, 0xbc000000, v96
	v_fmac_f32_e32 v97, v104, v104
	v_fmac_f32_e32 v105, 0xbc000000, v96
	v_fmac_f32_e32 v97, v105, v105
	v_fmac_f32_e32 v106, 0xbc000000, v96
	v_fmac_f32_e32 v97, v106, v106
	v_fmac_f32_e32 v107, 0xbc000000, v96
	v_fmac_f32_e32 v97, v107, v107
	v_fmac_f32_e32 v108, 0xbc000000, v96
	v_fmac_f32_e32 v97, v108, v108
	v_fmac_f32_e32 v109, 0xbc000000, v96
	v_fmac_f32_e32 v97, v109, v109
	v_fmac_f32_e32 v110, 0xbc000000, v96
	v_fmac_f32_e32 v97, v110, v110
	v_fmac_f32_e32 v111, 0xbc000000, v96
	v_fmac_f32_e32 v97, v111, v111
	v_fmac_f32_e32 v112, 0xbc000000, v96
	v_fmac_f32_e32 v97, v112, v112
	v_fmac_f32_e32 v113, 0xbc000000, v96
	v_fmac_f32_e32 v97, v113, v113
	v_fmac_f32_e32 v114, 0xbc000000, v96
	v_fmac_f32_e32 v97, v114, v114
	v_fmac_f32_e32 v115, 0xbc000000, v96
	v_fmac_f32_e32 v97, v115, v115
	v_fmac_f32_e32 v116, 0xbc000000, v96
	v_fmac_f32_e32 v97, v116, v116
	v_fmac_f32_e32 v117, 0xbc000000, v96
	v_fmac_f32_e32 v97, v117, v117
	v_fmac_f32_e32 v118, 0xbc000000, v96
	v_fmac_f32_e32 v97, v118, v118
	v_fmac_f32_e32 v119, 0xbc000000, v96
	v_fmac_f32_e32 v97, v119, v119
	v_fmac_f32_e32 v120, 0xbc000000, v96
	v_fmac_f32_e32 v97, v120, v120
	v_fmac_f32_e32 v121, 0xbc000000, v96
	v_fmac_f32_e32 v97, v121, v121
	v_fmac_f32_e32 v122, 0xbc000000, v96
	v_fmac_f32_e32 v97, v122, v122
	v_fmac_f32_e32 v123, 0xbc000000, v96
	v_fmac_f32_e32 v97, v123, v123
	v_fmac_f32_e32 v124, 0xbc000000, v96
	v_fmac_f32_e32 v97, v124, v124
	v_fmac_f32_e32 v125, 0xbc000000, v96
	v_fmac_f32_e32 v97, v125, v125
	v_fmac_f32_e32 v126, 0xbc000000, v96
	v_fmac_f32_e32 v97, v126, v126
	v_fmac_f32_e32 v127, 0xbc000000, v96
	v_fmac_f32_e32 v97, v127, v127
	v_fmac_f32_e32 v128, 0xbc000000, v96
	v_fmac_f32_e32 v97, v128, v128
	v_fmac_f32_e32 v129, 0xbc000000, v96
	v_fmac_f32_e32 v97, v129, v129
	v_fmac_f32_e32 v130, 0xbc000000, v96
	v_fmac_f32_e32 v97, v130, v130
	v_fmac_f32_e32 v131, 0xbc000000, v96
	v_fmac_f32_e32 v97, v131, v131
	v_fmac_f32_e32 v132, 0xbc000000, v96
	v_fmac_f32_e32 v97, v132, v132
	s_cmpk_eq_i32 s44, 0x600
	s_mov_b64 s[48:49], 0x180
	v_add_f32_dpp v96, v97, v97 quad_perm:[1,0,3,2] row_mask:0xf bank_mask:0xf bound_ctrl:1
	s_nop 1
	v_add_f32_dpp v96, v96, v96 quad_perm:[2,3,0,1] row_mask:0xf bank_mask:0xf bound_ctrl:1
	v_fmamk_f32 v96, v96, 0x3c000000, v221
	v_rsq_f32_e32 v133, v96
	global_load_dwordx4 v[96:99], v[100:101], off offset:112
	s_nop 0
	global_load_dwordx4 v[100:103], v[100:101], off offset:96
	v_mul_f32_e32 v1, v1, v133
	s_waitcnt vmcnt(8)
; #define GAS __attribute__((address_space(1)))
; __device__ __forceinline__ bf16 f2bf(float f) { return (bf16)(cvt_pk_bf16(f, 0.f) & 0xffffu); }
; __device__ __forceinline__ void mixer_sgu(const Frame& F, const Args& A, int l, int chunk, const bf16* Z, bf16* MIX) {
;     ...
;             const float rstd = __builtin_amdgcn_rsqf(s2 * (1.0f / 128.0f) + EPS);
; #pragma unroll
;             for (int j = 0; j < 32; ++j) { const float y = v[j] * rstd * g4v[j >> 2][j & 3] + b4v[j >> 2][j & 3]; VT[(32 * q + j) * VT_STRIDE + t1] = f2bf(y); }
;         }
;         if (hd < 3) {
; #pragma unroll
;             for (int j = 0; j < 4; ++j) vr[j] = *(const GAS v4u*)(zv + 128 * (hd + 1) + 8 * j); }
	v_fma_f32 v1, v84, v1, v92
	v_cvt_pk_bf16_f32 v1, v1, s0
	v_add3_u32 v84, s5, v134, v78
	ds_write_b16 v84, v1
	v_mul_f32_e32 v1, v2, v133
	v_fma_f32 v1, v85, v1, v93
	v_cvt_pk_bf16_f32 v1, v1, s0
	ds_write_b16 v84, v1 offset:272
	v_mul_f32_e32 v1, v3, v133
	v_fma_f32 v1, v86, v1, v94
	v_cvt_pk_bf16_f32 v1, v1, s0
	ds_write_b16 v84, v1 offset:544
	v_mul_f32_e32 v1, v104, v133
	v_fmac_f32_e32 v95, v87, v1
	v_cvt_pk_bf16_f32 v1, v95, s0
	ds_write_b16 v84, v1 offset:816
	v_mul_f32_e32 v1, v105, v133
	v_fma_f32 v1, v80, v1, v88
	v_cvt_pk_bf16_f32 v1, v1, s0
	ds_write_b16 v84, v1 offset:1088
	v_mul_f32_e32 v1, v106, v133
	v_fma_f32 v1, v81, v1, v89
	v_cvt_pk_bf16_f32 v1, v1, s0
	ds_write_b16 v84, v1 offset:1360
	v_mul_f32_e32 v1, v107, v133
	v_fma_f32 v1, v82, v1, v90
	v_cvt_pk_bf16_f32 v1, v1, s0
	ds_write_b16 v84, v1 offset:1632
	v_mul_f32_e32 v1, v108, v133
	v_fmac_f32_e32 v91, v83, v1
	v_cvt_pk_bf16_f32 v1, v91, s0
	ds_write_b16 v84, v1 offset:1904
	v_mul_f32_e32 v1, v109, v133
	v_fma_f32 v1, v52, v1, v56
	v_cvt_pk_bf16_f32 v1, v1, s0
	ds_write_b16 v84, v1 offset:2176
	v_mul_f32_e32 v1, v110, v133
	v_fma_f32 v1, v53, v1, v57
	v_cvt_pk_bf16_f32 v1, v1, s0
	ds_write_b16 v84, v1 offset:2448
	v_mul_f32_e32 v1, v111, v133
	v_fma_f32 v1, v54, v1, v58
	v_cvt_pk_bf16_f32 v1, v1, s0
	ds_write_b16 v84, v1 offset:2720
	v_mul_f32_e32 v1, v112, v133
	v_fmac_f32_e32 v59, v55, v1
	v_cvt_pk_bf16_f32 v1, v59, s0
	ds_write_b16 v84, v1 offset:2992
	v_mul_f32_e32 v1, v113, v133
	v_fma_f32 v1, v44, v1, v48
	v_cvt_pk_bf16_f32 v1, v1, s0
	ds_write_b16 v84, v1 offset:3264
	v_mul_f32_e32 v1, v114, v133
	v_fma_f32 v1, v45, v1, v49
	v_cvt_pk_bf16_f32 v1, v1, s0
	ds_write_b16 v84, v1 offset:3536
	v_mul_f32_e32 v1, v115, v133
	v_fma_f32 v1, v46, v1, v50
	v_cvt_pk_bf16_f32 v1, v1, s0
	ds_write_b16 v84, v1 offset:3808
	v_mul_f32_e32 v1, v116, v133
	v_fmac_f32_e32 v51, v47, v1
	v_cvt_pk_bf16_f32 v1, v51, s0
	ds_write_b16 v84, v1 offset:4080
	v_mul_f32_e32 v1, v117, v133
	s_waitcnt vmcnt(2)
	v_fma_f32 v1, v36, v1, v40
	v_cvt_pk_bf16_f32 v1, v1, s0
	ds_write_b16 v84, v1 offset:4352
	v_mul_f32_e32 v1, v118, v133
	v_fma_f32 v1, v37, v1, v41
	v_cvt_pk_bf16_f32 v1, v1, s0
	ds_write_b16 v84, v1 offset:4624
	v_mul_f32_e32 v1, v119, v133
	v_fma_f32 v1, v38, v1, v42
	v_cvt_pk_bf16_f32 v1, v1, s0
	ds_write_b16 v84, v1 offset:4896
	v_mul_f32_e32 v1, v120, v133
	v_fmac_f32_e32 v43, v39, v1
	v_cvt_pk_bf16_f32 v1, v43, s0
	ds_write_b16 v84, v1 offset:5168
	v_mul_f32_e32 v1, v121, v133
	v_fma_f32 v1, v28, v1, v32
	v_cvt_pk_bf16_f32 v1, v1, s0
	ds_write_b16 v84, v1 offset:5440
	v_mul_f32_e32 v1, v122, v133
	v_fma_f32 v1, v29, v1, v33
	v_cvt_pk_bf16_f32 v1, v1, s0
	ds_write_b16 v84, v1 offset:5712
	v_mul_f32_e32 v1, v123, v133
	v_fma_f32 v1, v30, v1, v34
	v_cvt_pk_bf16_f32 v1, v1, s0
	ds_write_b16 v84, v1 offset:5984
	v_mul_f32_e32 v1, v124, v133
	v_fmac_f32_e32 v35, v31, v1
	v_cvt_pk_bf16_f32 v1, v35, s0
	ds_write_b16 v84, v1 offset:6256
	v_mul_f32_e32 v1, v125, v133
	s_waitcnt vmcnt(0)
	v_fma_f32 v1, v24, v1, v100
	v_cvt_pk_bf16_f32 v1, v1, s0
	ds_write_b16 v84, v1 offset:6528
	v_mul_f32_e32 v1, v126, v133
	v_fma_f32 v1, v25, v1, v101
	v_cvt_pk_bf16_f32 v1, v1, s0
	ds_write_b16 v84, v1 offset:6800
	v_mul_f32_e32 v1, v127, v133
	v_fma_f32 v1, v26, v1, v102
	v_cvt_pk_bf16_f32 v1, v1, s0
	ds_write_b16 v84, v1 offset:7072
	v_mul_f32_e32 v1, v128, v133
	v_fmac_f32_e32 v103, v27, v1
	v_cvt_pk_bf16_f32 v1, v103, s0
	ds_write_b16 v84, v1 offset:7344
	v_mul_f32_e32 v1, v129, v133
	v_fma_f32 v1, v20, v1, v96
	v_cvt_pk_bf16_f32 v1, v1, s0
	ds_write_b16 v84, v1 offset:7616
	v_mul_f32_e32 v1, v130, v133
	v_fma_f32 v1, v21, v1, v97
	v_cvt_pk_bf16_f32 v1, v1, s0
	ds_write_b16 v84, v1 offset:7888
	v_mul_f32_e32 v1, v131, v133
	v_fma_f32 v1, v22, v1, v98
	v_cvt_pk_bf16_f32 v1, v1, s0
	ds_write_b16 v84, v1 offset:8160
	v_mul_f32_e32 v1, v132, v133
	v_fmac_f32_e32 v99, v23, v1
	v_cvt_pk_bf16_f32 v1, v99, s0
	ds_write_b16 v84, v1 offset:8432
	s_cbranch_scc1 .LBB0_340
	global_load_dwordx4 v[4:7], v[68:69], off offset:48
	global_load_dwordx4 v[8:11], v[68:69], off offset:32
	global_load_dwordx4 v[12:15], v[68:69], off offset:16
	global_load_dwordx4 v[16:19], v[68:69], off
	s_mov_b64 s[48:49], s[46:47]
